# norm phases: lane-to-column layout changed so each 16-byte row load instruction covers a contiguous 1 KB (each cache line requested once); bf16 output written with 8-byte stores
# baseline (speedup 1.0000x reference)
.LBB0_277:
	v_readlane_b32 s46, v254, 54
	v_readlane_b32 s40, v254, 34
	v_readlane_b32 s44, v254, 38
	v_readlane_b32 s84, v255, 4
	s_andn2_b64 vcc, exec, s[2:3]
	v_readlane_b32 s47, v254, 55
	v_readlane_b32 s42, v250, 16
	v_readlane_b32 s16, v254, 18
	v_readlane_b32 s41, v254, 35
	v_readlane_b32 s45, v254, 39
	s_mov_b64 s[48:49], 0x200
	s_mov_b64 s[50:51], 0x400
	s_mov_b64 s[56:57], 0x600
	v_readlane_b32 s85, v255, 5
	v_readlane_b32 s86, v255, 6
	v_readlane_b32 s87, v255, 7
	v_readlane_b32 s17, v254, 56
	s_cbranch_vccnz .LBB0_281
	s_cmpk_gt_i32 s52, 0x7fff
	s_mov_b32 s36, s17
	s_cbranch_scc1 .LBB0_281
	v_readlane_b32 s2, v250, 0
	s_cmpk_lg_u32 s2, 0x100
	s_cbranch_scc1 .Lnrm_A_fallback
	v_lshrrev_b32_e32 v0, 6, v222
	v_and_b32_e32 v1, 63, v222
	v_readlane_b32 s4, v254, 48
	v_readfirstlane_b32 s3, v0
	v_readlane_b32 s82, v250, 2
	v_readlane_b32 s83, v250, 3
	s_lshl_b32 s4, s4, 3
	s_add_i32 s4, s4, s3
	s_load_dwordx2 s[18:19], s[82:83], 0x38
	s_mov_b32 s12, s72
	s_mov_b32 s13, s73
	s_lshr_b32 s2, s4, 7
	s_mul_i32 s2, s2, 0x9000
	s_add_u32 s20, s74, s2
	s_addc_u32 s21, s75, 0
	s_add_u32 s88, s20, 0x4000
	s_addc_u32 s89, s21, 0
	s_add_u32 s90, s20, 0x3000
	s_addc_u32 s91, s21, 0
	v_lshlrev_b32_e32 v202, 4, v1
	v_lshlrev_b32_e32 v203, 3, v1
	s_lshl_b32 s11, s4, 16
	s_lshl_b32 s2, s4, 15
	s_add_u32 s48, s74, s2
	s_addc_u32 s49, s75, 0
	s_add_u32 s48, s48, 0x3000000
	s_addc_u32 s49, s49, 0
	s_waitcnt lgkmcnt(0)
	s_and_b32 s13, s13, 0xffff
	s_mov_b32 s14, 0x8000000
	s_mov_b32 s15, 0x20000
	global_load_dwordx4 v[64:67], v202, s[18:19]
	global_load_dwordx4 v[68:71], v202, s[18:19] offset:1024
	global_load_dwordx4 v[72:75], v202, s[18:19] offset:2048
	global_load_dwordx4 v[76:79], v202, s[18:19] offset:3072
	global_load_dwordx4 v[80:83], v202, s[88:89]
	global_load_dwordx4 v[84:87], v202, s[88:89] offset:1024
	global_load_dwordx4 v[88:91], v202, s[88:89] offset:2048
	global_load_dwordx4 v[92:95], v202, s[88:89] offset:3072
	global_load_dwordx4 v[162:165], v202, s[90:91]
	global_load_dwordx4 v[166:169], v202, s[90:91] offset:1024
	global_load_dwordx4 v[170:173], v202, s[90:91] offset:2048
	global_load_dwordx4 v[174:177], v202, s[90:91] offset:3072
	buffer_load_dwordx4 v[0:3], v202, s[12:15], s11 offen sc1
	buffer_load_dwordx4 v[4:7], v202, s[12:15], s11 offen offset:1024 sc1
	buffer_load_dwordx4 v[8:11], v202, s[12:15], s11 offen offset:2048 sc1
	buffer_load_dwordx4 v[12:15], v202, s[12:15], s11 offen offset:3072 sc1
	s_add_u32 s11, s11, 0x1000
	buffer_load_dwordx4 v[16:19], v202, s[12:15], s11 offen sc1
	buffer_load_dwordx4 v[20:23], v202, s[12:15], s11 offen offset:1024 sc1
	buffer_load_dwordx4 v[24:27], v202, s[12:15], s11 offen offset:2048 sc1
	buffer_load_dwordx4 v[28:31], v202, s[12:15], s11 offen offset:3072 sc1
	s_add_u32 s11, s11, 0x1000
	buffer_load_dwordx4 v[32:35], v202, s[12:15], s11 offen sc1
	buffer_load_dwordx4 v[36:39], v202, s[12:15], s11 offen offset:1024 sc1
	buffer_load_dwordx4 v[40:43], v202, s[12:15], s11 offen offset:2048 sc1
	buffer_load_dwordx4 v[44:47], v202, s[12:15], s11 offen offset:3072 sc1
	s_add_u32 s11, s11, 0x1000
	buffer_load_dwordx4 v[48:51], v202, s[12:15], s11 offen sc1
	buffer_load_dwordx4 v[52:55], v202, s[12:15], s11 offen offset:1024 sc1
	buffer_load_dwordx4 v[56:59], v202, s[12:15], s11 offen offset:2048 sc1
	buffer_load_dwordx4 v[60:63], v202, s[12:15], s11 offen offset:3072 sc1
	s_add_u32 s11, s11, 0x1000
	buffer_load_dwordx4 v[98:101], v202, s[12:15], s11 offen sc1
	buffer_load_dwordx4 v[102:105], v202, s[12:15], s11 offen offset:1024 sc1
	buffer_load_dwordx4 v[106:109], v202, s[12:15], s11 offen offset:2048 sc1
	buffer_load_dwordx4 v[110:113], v202, s[12:15], s11 offen offset:3072 sc1
	s_add_u32 s11, s11, 0x1000
	buffer_load_dwordx4 v[114:117], v202, s[12:15], s11 offen sc1
	buffer_load_dwordx4 v[118:121], v202, s[12:15], s11 offen offset:1024 sc1
	buffer_load_dwordx4 v[122:125], v202, s[12:15], s11 offen offset:2048 sc1
	buffer_load_dwordx4 v[126:129], v202, s[12:15], s11 offen offset:3072 sc1
	s_add_u32 s11, s11, 0x1000
	buffer_load_dwordx4 v[130:133], v202, s[12:15], s11 offen sc1
	buffer_load_dwordx4 v[134:137], v202, s[12:15], s11 offen offset:1024 sc1
	buffer_load_dwordx4 v[138:141], v202, s[12:15], s11 offen offset:2048 sc1
	buffer_load_dwordx4 v[142:145], v202, s[12:15], s11 offen offset:3072 sc1
	s_add_u32 s11, s11, 0x1000
	buffer_load_dwordx4 v[146:149], v202, s[12:15], s11 offen sc1
	buffer_load_dwordx4 v[150:153], v202, s[12:15], s11 offen offset:1024 sc1
	buffer_load_dwordx4 v[154:157], v202, s[12:15], s11 offen offset:2048 sc1
	buffer_load_dwordx4 v[158:161], v202, s[12:15], s11 offen offset:3072 sc1
	s_add_u32 s11, s11, 0x1000
	s_waitcnt vmcnt(16)
	v_pk_add_f32 v[80:81], v[80:81], 1.0 op_sel_hi:[1,0]
	v_pk_add_f32 v[82:83], v[82:83], 1.0 op_sel_hi:[1,0]
	v_pk_add_f32 v[84:85], v[84:85], 1.0 op_sel_hi:[1,0]
	v_pk_add_f32 v[86:87], v[86:87], 1.0 op_sel_hi:[1,0]
	v_pk_add_f32 v[88:89], v[88:89], 1.0 op_sel_hi:[1,0]
	v_pk_add_f32 v[90:91], v[90:91], 1.0 op_sel_hi:[1,0]
	v_pk_add_f32 v[92:93], v[92:93], 1.0 op_sel_hi:[1,0]
	v_pk_add_f32 v[94:95], v[94:95], 1.0 op_sel_hi:[1,0]
	v_mul_f32_e32 v178, v0, v0
	v_mul_f32_e32 v179, v16, v16
	v_mul_f32_e32 v180, v32, v32
	v_mul_f32_e32 v181, v48, v48
	v_fma_f32 v178, v1, v1, v178
	v_fma_f32 v179, v17, v17, v179
	v_fma_f32 v180, v33, v33, v180
	v_fma_f32 v181, v49, v49, v181
	v_fma_f32 v178, v2, v2, v178
	v_fma_f32 v179, v18, v18, v179
	v_fma_f32 v180, v34, v34, v180
	v_fma_f32 v181, v50, v50, v181
	v_fma_f32 v178, v3, v3, v178
	v_fma_f32 v179, v19, v19, v179
	v_fma_f32 v180, v35, v35, v180
	v_fma_f32 v181, v51, v51, v181
	v_fma_f32 v178, v4, v4, v178
	v_fma_f32 v179, v20, v20, v179
	v_fma_f32 v180, v36, v36, v180
	v_fma_f32 v181, v52, v52, v181
	v_fma_f32 v178, v5, v5, v178
	v_fma_f32 v179, v21, v21, v179
	v_fma_f32 v180, v37, v37, v180
	v_fma_f32 v181, v53, v53, v181
	v_fma_f32 v178, v6, v6, v178
	v_fma_f32 v179, v22, v22, v179
	v_fma_f32 v180, v38, v38, v180
	v_fma_f32 v181, v54, v54, v181
	v_fma_f32 v178, v7, v7, v178
	v_fma_f32 v179, v23, v23, v179
	v_fma_f32 v180, v39, v39, v180
	v_fma_f32 v181, v55, v55, v181
	v_fma_f32 v178, v8, v8, v178
	v_fma_f32 v179, v24, v24, v179
	v_fma_f32 v180, v40, v40, v180
	v_fma_f32 v181, v56, v56, v181
	v_fma_f32 v178, v9, v9, v178
	v_fma_f32 v179, v25, v25, v179
	v_fma_f32 v180, v41, v41, v180
	v_fma_f32 v181, v57, v57, v181
	v_fma_f32 v178, v10, v10, v178
	v_fma_f32 v179, v26, v26, v179
	v_fma_f32 v180, v42, v42, v180
	v_fma_f32 v181, v58, v58, v181
	v_fma_f32 v178, v11, v11, v178
	v_fma_f32 v179, v27, v27, v179
	v_fma_f32 v180, v43, v43, v180
	v_fma_f32 v181, v59, v59, v181
	v_fma_f32 v178, v12, v12, v178
	v_fma_f32 v179, v28, v28, v179
	v_fma_f32 v180, v44, v44, v180
	v_fma_f32 v181, v60, v60, v181
	v_fma_f32 v178, v13, v13, v178
	v_fma_f32 v179, v29, v29, v179
	v_fma_f32 v180, v45, v45, v180
	v_fma_f32 v181, v61, v61, v181
	v_fma_f32 v178, v14, v14, v178
	v_fma_f32 v179, v30, v30, v179
	v_fma_f32 v180, v46, v46, v180
	v_fma_f32 v181, v62, v62, v181
	v_fma_f32 v178, v15, v15, v178
	v_fma_f32 v179, v31, v31, v179
	v_fma_f32 v180, v47, v47, v180
	v_fma_f32 v181, v63, v63, v181
	v_add_f32_dpp v178, v178, v178 quad_perm:[1,0,3,2] row_mask:0xf bank_mask:0xf
	v_add_f32_dpp v179, v179, v179 quad_perm:[1,0,3,2] row_mask:0xf bank_mask:0xf
	v_add_f32_dpp v180, v180, v180 quad_perm:[1,0,3,2] row_mask:0xf bank_mask:0xf
	v_add_f32_dpp v181, v181, v181 quad_perm:[1,0,3,2] row_mask:0xf bank_mask:0xf
	v_add_f32_dpp v178, v178, v178 quad_perm:[2,3,0,1] row_mask:0xf bank_mask:0xf
	v_add_f32_dpp v179, v179, v179 quad_perm:[2,3,0,1] row_mask:0xf bank_mask:0xf
	v_add_f32_dpp v180, v180, v180 quad_perm:[2,3,0,1] row_mask:0xf bank_mask:0xf
	v_add_f32_dpp v181, v181, v181 quad_perm:[2,3,0,1] row_mask:0xf bank_mask:0xf
	v_add_f32_dpp v178, v178, v178 row_half_mirror row_mask:0xf bank_mask:0xf
	v_add_f32_dpp v179, v179, v179 row_half_mirror row_mask:0xf bank_mask:0xf
	v_add_f32_dpp v180, v180, v180 row_half_mirror row_mask:0xf bank_mask:0xf
	v_add_f32_dpp v181, v181, v181 row_half_mirror row_mask:0xf bank_mask:0xf
	v_add_f32_dpp v178, v178, v178 row_ror:8 row_mask:0xf bank_mask:0xf
	v_add_f32_dpp v179, v179, v179 row_ror:8 row_mask:0xf bank_mask:0xf
	v_add_f32_dpp v180, v180, v180 row_ror:8 row_mask:0xf bank_mask:0xf
	v_add_f32_dpp v181, v181, v181 row_ror:8 row_mask:0xf bank_mask:0xf
	v_mov_b32_e32 v182, v178
	v_mov_b32_e32 v183, v179
	v_mov_b32_e32 v184, v180
	v_mov_b32_e32 v185, v181
	v_permlane16_swap_b32_e32 v182, v178
	v_permlane16_swap_b32_e32 v183, v179
	v_permlane16_swap_b32_e32 v184, v180
	v_permlane16_swap_b32_e32 v185, v181
	v_add_f32_e32 v178, v178, v182
	v_add_f32_e32 v179, v179, v183
	v_add_f32_e32 v180, v180, v184
	v_add_f32_e32 v181, v181, v185
	v_mov_b32_e32 v182, v178
	v_mov_b32_e32 v183, v179
	v_mov_b32_e32 v184, v180
	v_mov_b32_e32 v185, v181
	v_permlane32_swap_b32_e32 v182, v178
	v_permlane32_swap_b32_e32 v183, v179
	v_permlane32_swap_b32_e32 v184, v180
	v_permlane32_swap_b32_e32 v185, v181
	v_add_f32_e32 v178, v178, v182
	v_add_f32_e32 v179, v179, v183
	v_add_f32_e32 v180, v180, v184
	v_add_f32_e32 v181, v181, v185
	v_fmamk_f32 v198, v178, 0x3a800000, v225
	v_fmamk_f32 v199, v179, 0x3a800000, v225
	v_fmamk_f32 v200, v180, 0x3a800000, v225
	v_fmamk_f32 v201, v181, 0x3a800000, v225
	v_mul_f32_e32 v182, 0x4b800000, v198
	v_mul_f32_e32 v183, 0x4b800000, v199
	v_mul_f32_e32 v184, 0x4b800000, v200
	v_mul_f32_e32 v185, 0x4b800000, v201
	v_cmp_gt_f32_e64 s[2:3], s30, v198
	v_cmp_gt_f32_e64 s[50:51], s30, v199
	v_cmp_gt_f32_e64 s[88:89], s30, v200
	v_cmp_gt_f32_e64 s[90:91], s30, v201
	v_cndmask_b32_e64 v198, v198, v182, s[2:3]
	v_cndmask_b32_e64 v199, v199, v183, s[50:51]
	v_cndmask_b32_e64 v200, v200, v184, s[88:89]
	v_cndmask_b32_e64 v201, v201, v185, s[90:91]
	v_rsq_f32_e32 v198, v198
	v_rsq_f32_e32 v199, v199
	v_rsq_f32_e32 v200, v200
	v_rsq_f32_e32 v201, v201
	v_mul_f32_e32 v182, 0x45800000, v198
	v_mul_f32_e32 v183, 0x45800000, v199
	v_mul_f32_e32 v184, 0x45800000, v200
	v_mul_f32_e32 v185, 0x45800000, v201
	v_cndmask_b32_e64 v186, v198, v182, s[2:3]
	v_cndmask_b32_e64 v192, v199, v183, s[50:51]
	v_cndmask_b32_e64 v194, v200, v184, s[88:89]
	v_cndmask_b32_e64 v196, v201, v185, s[90:91]
	v_pk_mul_f32 v[0:1], v[186:187], v[0:1] op_sel_hi:[0,1]
	v_pk_mul_f32 v[2:3], v[186:187], v[2:3] op_sel_hi:[0,1]
	v_pk_mul_f32 v[4:5], v[186:187], v[4:5] op_sel_hi:[0,1]
	v_pk_mul_f32 v[6:7], v[186:187], v[6:7] op_sel_hi:[0,1]
	v_pk_mul_f32 v[8:9], v[186:187], v[8:9] op_sel_hi:[0,1]
	v_pk_mul_f32 v[10:11], v[186:187], v[10:11] op_sel_hi:[0,1]
	v_pk_mul_f32 v[12:13], v[186:187], v[12:13] op_sel_hi:[0,1]
	v_pk_mul_f32 v[14:15], v[186:187], v[14:15] op_sel_hi:[0,1]
	v_pk_mul_f32 v[0:1], v[64:65], v[0:1]
	v_pk_mul_f32 v[2:3], v[66:67], v[2:3]
	v_pk_mul_f32 v[4:5], v[68:69], v[4:5]
	v_pk_mul_f32 v[6:7], v[70:71], v[6:7]
	v_pk_mul_f32 v[8:9], v[72:73], v[8:9]
	v_pk_mul_f32 v[10:11], v[74:75], v[10:11]
	v_pk_mul_f32 v[12:13], v[76:77], v[12:13]
	v_pk_mul_f32 v[14:15], v[78:79], v[14:15]
	v_pk_fma_f32 v[0:1], v[80:81], v[0:1], v[162:163]
	v_pk_fma_f32 v[2:3], v[82:83], v[2:3], v[164:165]
	v_pk_fma_f32 v[4:5], v[84:85], v[4:5], v[166:167]
	v_pk_fma_f32 v[6:7], v[86:87], v[6:7], v[168:169]
	v_pk_fma_f32 v[8:9], v[88:89], v[8:9], v[170:171]
	v_pk_fma_f32 v[10:11], v[90:91], v[10:11], v[172:173]
	v_pk_fma_f32 v[12:13], v[92:93], v[12:13], v[174:175]
	v_pk_fma_f32 v[14:15], v[94:95], v[14:15], v[176:177]
	v_cvt_pk_bf16_f32 v204, v0, v1
	v_cvt_pk_bf16_f32 v205, v2, v3
	v_cvt_pk_bf16_f32 v206, v4, v5
	v_cvt_pk_bf16_f32 v207, v6, v7
	v_cvt_pk_bf16_f32 v208, v8, v9
	v_cvt_pk_bf16_f32 v209, v10, v11
	v_cvt_pk_bf16_f32 v210, v12, v13
	v_cvt_pk_bf16_f32 v211, v14, v15
	global_store_dwordx2 v203, v[204:205], s[48:49] sc1
	global_store_dwordx2 v203, v[206:207], s[48:49] offset:512 sc1
	global_store_dwordx2 v203, v[208:209], s[48:49] offset:1024 sc1
	global_store_dwordx2 v203, v[210:211], s[48:49] offset:1536 sc1
	s_add_u32 s48, s48, 0x800
	s_addc_u32 s49, s49, 0
	v_pk_mul_f32 v[16:17], v[192:193], v[16:17] op_sel_hi:[0,1]
	v_pk_mul_f32 v[18:19], v[192:193], v[18:19] op_sel_hi:[0,1]
	v_pk_mul_f32 v[20:21], v[192:193], v[20:21] op_sel_hi:[0,1]
	v_pk_mul_f32 v[22:23], v[192:193], v[22:23] op_sel_hi:[0,1]
	v_pk_mul_f32 v[24:25], v[192:193], v[24:25] op_sel_hi:[0,1]
	v_pk_mul_f32 v[26:27], v[192:193], v[26:27] op_sel_hi:[0,1]
	v_pk_mul_f32 v[28:29], v[192:193], v[28:29] op_sel_hi:[0,1]
	v_pk_mul_f32 v[30:31], v[192:193], v[30:31] op_sel_hi:[0,1]
	v_pk_mul_f32 v[16:17], v[64:65], v[16:17]
	v_pk_mul_f32 v[18:19], v[66:67], v[18:19]
	v_pk_mul_f32 v[20:21], v[68:69], v[20:21]
	v_pk_mul_f32 v[22:23], v[70:71], v[22:23]
	v_pk_mul_f32 v[24:25], v[72:73], v[24:25]
	v_pk_mul_f32 v[26:27], v[74:75], v[26:27]
	v_pk_mul_f32 v[28:29], v[76:77], v[28:29]
	v_pk_mul_f32 v[30:31], v[78:79], v[30:31]
	v_pk_fma_f32 v[16:17], v[80:81], v[16:17], v[162:163]
	v_pk_fma_f32 v[18:19], v[82:83], v[18:19], v[164:165]
	v_pk_fma_f32 v[20:21], v[84:85], v[20:21], v[166:167]
	v_pk_fma_f32 v[22:23], v[86:87], v[22:23], v[168:169]
	v_pk_fma_f32 v[24:25], v[88:89], v[24:25], v[170:171]
	v_pk_fma_f32 v[26:27], v[90:91], v[26:27], v[172:173]
	v_pk_fma_f32 v[28:29], v[92:93], v[28:29], v[174:175]
	v_pk_fma_f32 v[30:31], v[94:95], v[30:31], v[176:177]
	v_cvt_pk_bf16_f32 v212, v16, v17
	v_cvt_pk_bf16_f32 v213, v18, v19
	v_cvt_pk_bf16_f32 v214, v20, v21
	v_cvt_pk_bf16_f32 v215, v22, v23
	v_cvt_pk_bf16_f32 v216, v24, v25
	v_cvt_pk_bf16_f32 v217, v26, v27
	v_cvt_pk_bf16_f32 v218, v28, v29
	v_cvt_pk_bf16_f32 v219, v30, v31
	global_store_dwordx2 v203, v[212:213], s[48:49] sc1
	global_store_dwordx2 v203, v[214:215], s[48:49] offset:512 sc1
	global_store_dwordx2 v203, v[216:217], s[48:49] offset:1024 sc1
	global_store_dwordx2 v203, v[218:219], s[48:49] offset:1536 sc1
	s_add_u32 s48, s48, 0x800
	s_addc_u32 s49, s49, 0
	v_pk_mul_f32 v[32:33], v[194:195], v[32:33] op_sel_hi:[0,1]
	v_pk_mul_f32 v[34:35], v[194:195], v[34:35] op_sel_hi:[0,1]
	v_pk_mul_f32 v[36:37], v[194:195], v[36:37] op_sel_hi:[0,1]
	v_pk_mul_f32 v[38:39], v[194:195], v[38:39] op_sel_hi:[0,1]
	v_pk_mul_f32 v[40:41], v[194:195], v[40:41] op_sel_hi:[0,1]
	v_pk_mul_f32 v[42:43], v[194:195], v[42:43] op_sel_hi:[0,1]
	v_pk_mul_f32 v[44:45], v[194:195], v[44:45] op_sel_hi:[0,1]
	v_pk_mul_f32 v[46:47], v[194:195], v[46:47] op_sel_hi:[0,1]
	v_pk_mul_f32 v[32:33], v[64:65], v[32:33]
	v_pk_mul_f32 v[34:35], v[66:67], v[34:35]
	v_pk_mul_f32 v[36:37], v[68:69], v[36:37]
	v_pk_mul_f32 v[38:39], v[70:71], v[38:39]
	v_pk_mul_f32 v[40:41], v[72:73], v[40:41]
	v_pk_mul_f32 v[42:43], v[74:75], v[42:43]
	v_pk_mul_f32 v[44:45], v[76:77], v[44:45]
	v_pk_mul_f32 v[46:47], v[78:79], v[46:47]
	v_pk_fma_f32 v[32:33], v[80:81], v[32:33], v[162:163]
	v_pk_fma_f32 v[34:35], v[82:83], v[34:35], v[164:165]
	v_pk_fma_f32 v[36:37], v[84:85], v[36:37], v[166:167]
	v_pk_fma_f32 v[38:39], v[86:87], v[38:39], v[168:169]
	v_pk_fma_f32 v[40:41], v[88:89], v[40:41], v[170:171]
	v_pk_fma_f32 v[42:43], v[90:91], v[42:43], v[172:173]
	v_pk_fma_f32 v[44:45], v[92:93], v[44:45], v[174:175]
	v_pk_fma_f32 v[46:47], v[94:95], v[46:47], v[176:177]
	v_cvt_pk_bf16_f32 v204, v32, v33
	v_cvt_pk_bf16_f32 v205, v34, v35
	v_cvt_pk_bf16_f32 v206, v36, v37
	v_cvt_pk_bf16_f32 v207, v38, v39
	v_cvt_pk_bf16_f32 v208, v40, v41
	v_cvt_pk_bf16_f32 v209, v42, v43
	v_cvt_pk_bf16_f32 v210, v44, v45
	v_cvt_pk_bf16_f32 v211, v46, v47
	global_store_dwordx2 v203, v[204:205], s[48:49] sc1
	global_store_dwordx2 v203, v[206:207], s[48:49] offset:512 sc1
	global_store_dwordx2 v203, v[208:209], s[48:49] offset:1024 sc1
	global_store_dwordx2 v203, v[210:211], s[48:49] offset:1536 sc1
	s_add_u32 s48, s48, 0x800
	s_addc_u32 s49, s49, 0
	v_pk_mul_f32 v[48:49], v[196:197], v[48:49] op_sel_hi:[0,1]
	v_pk_mul_f32 v[50:51], v[196:197], v[50:51] op_sel_hi:[0,1]
	v_pk_mul_f32 v[52:53], v[196:197], v[52:53] op_sel_hi:[0,1]
	v_pk_mul_f32 v[54:55], v[196:197], v[54:55] op_sel_hi:[0,1]
	v_pk_mul_f32 v[56:57], v[196:197], v[56:57] op_sel_hi:[0,1]
	v_pk_mul_f32 v[58:59], v[196:197], v[58:59] op_sel_hi:[0,1]
	v_pk_mul_f32 v[60:61], v[196:197], v[60:61] op_sel_hi:[0,1]
	v_pk_mul_f32 v[62:63], v[196:197], v[62:63] op_sel_hi:[0,1]
	v_pk_mul_f32 v[48:49], v[64:65], v[48:49]
	v_pk_mul_f32 v[50:51], v[66:67], v[50:51]
	v_pk_mul_f32 v[52:53], v[68:69], v[52:53]
	v_pk_mul_f32 v[54:55], v[70:71], v[54:55]
	v_pk_mul_f32 v[56:57], v[72:73], v[56:57]
	v_pk_mul_f32 v[58:59], v[74:75], v[58:59]
	v_pk_mul_f32 v[60:61], v[76:77], v[60:61]
	v_pk_mul_f32 v[62:63], v[78:79], v[62:63]
	v_pk_fma_f32 v[48:49], v[80:81], v[48:49], v[162:163]
	v_pk_fma_f32 v[50:51], v[82:83], v[50:51], v[164:165]
	v_pk_fma_f32 v[52:53], v[84:85], v[52:53], v[166:167]
	v_pk_fma_f32 v[54:55], v[86:87], v[54:55], v[168:169]
	v_pk_fma_f32 v[56:57], v[88:89], v[56:57], v[170:171]
	v_pk_fma_f32 v[58:59], v[90:91], v[58:59], v[172:173]
	v_pk_fma_f32 v[60:61], v[92:93], v[60:61], v[174:175]
	v_pk_fma_f32 v[62:63], v[94:95], v[62:63], v[176:177]
	v_cvt_pk_bf16_f32 v212, v48, v49
	v_cvt_pk_bf16_f32 v213, v50, v51
	v_cvt_pk_bf16_f32 v214, v52, v53
	v_cvt_pk_bf16_f32 v215, v54, v55
	v_cvt_pk_bf16_f32 v216, v56, v57
	v_cvt_pk_bf16_f32 v217, v58, v59
	v_cvt_pk_bf16_f32 v218, v60, v61
	v_cvt_pk_bf16_f32 v219, v62, v63
	global_store_dwordx2 v203, v[212:213], s[48:49] sc1
	global_store_dwordx2 v203, v[214:215], s[48:49] offset:512 sc1
	global_store_dwordx2 v203, v[216:217], s[48:49] offset:1024 sc1
	global_store_dwordx2 v203, v[218:219], s[48:49] offset:1536 sc1
	s_add_u32 s48, s48, 0x800
	s_addc_u32 s49, s49, 0
	buffer_load_dwordx4 v[0:3], v202, s[12:15], s11 offen sc1
	buffer_load_dwordx4 v[4:7], v202, s[12:15], s11 offen offset:1024 sc1
	buffer_load_dwordx4 v[8:11], v202, s[12:15], s11 offen offset:2048 sc1
	buffer_load_dwordx4 v[12:15], v202, s[12:15], s11 offen offset:3072 sc1
	s_add_u32 s11, s11, 0x1000
	buffer_load_dwordx4 v[16:19], v202, s[12:15], s11 offen sc1
	buffer_load_dwordx4 v[20:23], v202, s[12:15], s11 offen offset:1024 sc1
	buffer_load_dwordx4 v[24:27], v202, s[12:15], s11 offen offset:2048 sc1
	buffer_load_dwordx4 v[28:31], v202, s[12:15], s11 offen offset:3072 sc1
	s_add_u32 s11, s11, 0x1000
	buffer_load_dwordx4 v[32:35], v202, s[12:15], s11 offen sc1
	buffer_load_dwordx4 v[36:39], v202, s[12:15], s11 offen offset:1024 sc1
	buffer_load_dwordx4 v[40:43], v202, s[12:15], s11 offen offset:2048 sc1
	buffer_load_dwordx4 v[44:47], v202, s[12:15], s11 offen offset:3072 sc1
	s_add_u32 s11, s11, 0x1000
	buffer_load_dwordx4 v[48:51], v202, s[12:15], s11 offen sc1
	buffer_load_dwordx4 v[52:55], v202, s[12:15], s11 offen offset:1024 sc1
	buffer_load_dwordx4 v[56:59], v202, s[12:15], s11 offen offset:2048 sc1
	buffer_load_dwordx4 v[60:63], v202, s[12:15], s11 offen offset:3072 sc1
	s_add_u32 s11, s11, 0x1000
	s_waitcnt vmcnt(24)
	v_mul_f32_e32 v178, v98, v98
	v_mul_f32_e32 v179, v114, v114
	v_mul_f32_e32 v180, v130, v130
	v_mul_f32_e32 v181, v146, v146
	v_fma_f32 v178, v99, v99, v178
	v_fma_f32 v179, v115, v115, v179
	v_fma_f32 v180, v131, v131, v180
	v_fma_f32 v181, v147, v147, v181
	v_fma_f32 v178, v100, v100, v178
	v_fma_f32 v179, v116, v116, v179
	v_fma_f32 v180, v132, v132, v180
	v_fma_f32 v181, v148, v148, v181
	v_fma_f32 v178, v101, v101, v178
	v_fma_f32 v179, v117, v117, v179
	v_fma_f32 v180, v133, v133, v180
	v_fma_f32 v181, v149, v149, v181
	v_fma_f32 v178, v102, v102, v178
	v_fma_f32 v179, v118, v118, v179
	v_fma_f32 v180, v134, v134, v180
	v_fma_f32 v181, v150, v150, v181
	v_fma_f32 v178, v103, v103, v178
	v_fma_f32 v179, v119, v119, v179
	v_fma_f32 v180, v135, v135, v180
	v_fma_f32 v181, v151, v151, v181
	v_fma_f32 v178, v104, v104, v178
	v_fma_f32 v179, v120, v120, v179
	v_fma_f32 v180, v136, v136, v180
	v_fma_f32 v181, v152, v152, v181
	v_fma_f32 v178, v105, v105, v178
	v_fma_f32 v179, v121, v121, v179
	v_fma_f32 v180, v137, v137, v180
	v_fma_f32 v181, v153, v153, v181
	v_fma_f32 v178, v106, v106, v178
	v_fma_f32 v179, v122, v122, v179
	v_fma_f32 v180, v138, v138, v180
	v_fma_f32 v181, v154, v154, v181
	v_fma_f32 v178, v107, v107, v178
	v_fma_f32 v179, v123, v123, v179
	v_fma_f32 v180, v139, v139, v180
	v_fma_f32 v181, v155, v155, v181
	v_fma_f32 v178, v108, v108, v178
	v_fma_f32 v179, v124, v124, v179
	v_fma_f32 v180, v140, v140, v180
	v_fma_f32 v181, v156, v156, v181
	v_fma_f32 v178, v109, v109, v178
	v_fma_f32 v179, v125, v125, v179
	v_fma_f32 v180, v141, v141, v180
	v_fma_f32 v181, v157, v157, v181
	v_fma_f32 v178, v110, v110, v178
	v_fma_f32 v179, v126, v126, v179
	v_fma_f32 v180, v142, v142, v180
	v_fma_f32 v181, v158, v158, v181
	v_fma_f32 v178, v111, v111, v178
	v_fma_f32 v179, v127, v127, v179
	v_fma_f32 v180, v143, v143, v180
	v_fma_f32 v181, v159, v159, v181
	v_fma_f32 v178, v112, v112, v178
	v_fma_f32 v179, v128, v128, v179
	v_fma_f32 v180, v144, v144, v180
	v_fma_f32 v181, v160, v160, v181
	v_fma_f32 v178, v113, v113, v178
	v_fma_f32 v179, v129, v129, v179
	v_fma_f32 v180, v145, v145, v180
	v_fma_f32 v181, v161, v161, v181
	v_add_f32_dpp v178, v178, v178 quad_perm:[1,0,3,2] row_mask:0xf bank_mask:0xf
	v_add_f32_dpp v179, v179, v179 quad_perm:[1,0,3,2] row_mask:0xf bank_mask:0xf
	v_add_f32_dpp v180, v180, v180 quad_perm:[1,0,3,2] row_mask:0xf bank_mask:0xf
	v_add_f32_dpp v181, v181, v181 quad_perm:[1,0,3,2] row_mask:0xf bank_mask:0xf
	v_add_f32_dpp v178, v178, v178 quad_perm:[2,3,0,1] row_mask:0xf bank_mask:0xf
	v_add_f32_dpp v179, v179, v179 quad_perm:[2,3,0,1] row_mask:0xf bank_mask:0xf
	v_add_f32_dpp v180, v180, v180 quad_perm:[2,3,0,1] row_mask:0xf bank_mask:0xf
	v_add_f32_dpp v181, v181, v181 quad_perm:[2,3,0,1] row_mask:0xf bank_mask:0xf
	v_add_f32_dpp v178, v178, v178 row_half_mirror row_mask:0xf bank_mask:0xf
	v_add_f32_dpp v179, v179, v179 row_half_mirror row_mask:0xf bank_mask:0xf
	v_add_f32_dpp v180, v180, v180 row_half_mirror row_mask:0xf bank_mask:0xf
	v_add_f32_dpp v181, v181, v181 row_half_mirror row_mask:0xf bank_mask:0xf
	v_add_f32_dpp v178, v178, v178 row_ror:8 row_mask:0xf bank_mask:0xf
	v_add_f32_dpp v179, v179, v179 row_ror:8 row_mask:0xf bank_mask:0xf
	v_add_f32_dpp v180, v180, v180 row_ror:8 row_mask:0xf bank_mask:0xf
	v_add_f32_dpp v181, v181, v181 row_ror:8 row_mask:0xf bank_mask:0xf
	v_mov_b32_e32 v182, v178
	v_mov_b32_e32 v183, v179
	v_mov_b32_e32 v184, v180
	v_mov_b32_e32 v185, v181
	v_permlane16_swap_b32_e32 v182, v178
	v_permlane16_swap_b32_e32 v183, v179
	v_permlane16_swap_b32_e32 v184, v180
	v_permlane16_swap_b32_e32 v185, v181
	v_add_f32_e32 v178, v178, v182
	v_add_f32_e32 v179, v179, v183
	v_add_f32_e32 v180, v180, v184
	v_add_f32_e32 v181, v181, v185
	v_mov_b32_e32 v182, v178
	v_mov_b32_e32 v183, v179
	v_mov_b32_e32 v184, v180
	v_mov_b32_e32 v185, v181
	v_permlane32_swap_b32_e32 v182, v178
	v_permlane32_swap_b32_e32 v183, v179
	v_permlane32_swap_b32_e32 v184, v180
	v_permlane32_swap_b32_e32 v185, v181
	v_add_f32_e32 v178, v178, v182
	v_add_f32_e32 v179, v179, v183
	v_add_f32_e32 v180, v180, v184
	v_add_f32_e32 v181, v181, v185
	v_fmamk_f32 v198, v178, 0x3a800000, v225
	v_fmamk_f32 v199, v179, 0x3a800000, v225
	v_fmamk_f32 v200, v180, 0x3a800000, v225
	v_fmamk_f32 v201, v181, 0x3a800000, v225
	v_mul_f32_e32 v182, 0x4b800000, v198
	v_mul_f32_e32 v183, 0x4b800000, v199
	v_mul_f32_e32 v184, 0x4b800000, v200
	v_mul_f32_e32 v185, 0x4b800000, v201
	v_cmp_gt_f32_e64 s[2:3], s30, v198
	v_cmp_gt_f32_e64 s[50:51], s30, v199
	v_cmp_gt_f32_e64 s[88:89], s30, v200
	v_cmp_gt_f32_e64 s[90:91], s30, v201
	v_cndmask_b32_e64 v198, v198, v182, s[2:3]
	v_cndmask_b32_e64 v199, v199, v183, s[50:51]
	v_cndmask_b32_e64 v200, v200, v184, s[88:89]
	v_cndmask_b32_e64 v201, v201, v185, s[90:91]
	v_rsq_f32_e32 v198, v198
	v_rsq_f32_e32 v199, v199
	v_rsq_f32_e32 v200, v200
	v_rsq_f32_e32 v201, v201
	v_mul_f32_e32 v182, 0x45800000, v198
	v_mul_f32_e32 v183, 0x45800000, v199
	v_mul_f32_e32 v184, 0x45800000, v200
	v_mul_f32_e32 v185, 0x45800000, v201
	v_cndmask_b32_e64 v186, v198, v182, s[2:3]
	v_cndmask_b32_e64 v192, v199, v183, s[50:51]
	v_cndmask_b32_e64 v194, v200, v184, s[88:89]
	v_cndmask_b32_e64 v196, v201, v185, s[90:91]
	v_pk_mul_f32 v[98:99], v[186:187], v[98:99] op_sel_hi:[0,1]
	v_pk_mul_f32 v[100:101], v[186:187], v[100:101] op_sel_hi:[0,1]
	v_pk_mul_f32 v[102:103], v[186:187], v[102:103] op_sel_hi:[0,1]
	v_pk_mul_f32 v[104:105], v[186:187], v[104:105] op_sel_hi:[0,1]
	v_pk_mul_f32 v[106:107], v[186:187], v[106:107] op_sel_hi:[0,1]
	v_pk_mul_f32 v[108:109], v[186:187], v[108:109] op_sel_hi:[0,1]
	v_pk_mul_f32 v[110:111], v[186:187], v[110:111] op_sel_hi:[0,1]
	v_pk_mul_f32 v[112:113], v[186:187], v[112:113] op_sel_hi:[0,1]
	v_pk_mul_f32 v[98:99], v[64:65], v[98:99]
	v_pk_mul_f32 v[100:101], v[66:67], v[100:101]
	v_pk_mul_f32 v[102:103], v[68:69], v[102:103]
	v_pk_mul_f32 v[104:105], v[70:71], v[104:105]
	v_pk_mul_f32 v[106:107], v[72:73], v[106:107]
	v_pk_mul_f32 v[108:109], v[74:75], v[108:109]
	v_pk_mul_f32 v[110:111], v[76:77], v[110:111]
	v_pk_mul_f32 v[112:113], v[78:79], v[112:113]
	v_pk_fma_f32 v[98:99], v[80:81], v[98:99], v[162:163]
	v_pk_fma_f32 v[100:101], v[82:83], v[100:101], v[164:165]
	v_pk_fma_f32 v[102:103], v[84:85], v[102:103], v[166:167]
	v_pk_fma_f32 v[104:105], v[86:87], v[104:105], v[168:169]
	v_pk_fma_f32 v[106:107], v[88:89], v[106:107], v[170:171]
	v_pk_fma_f32 v[108:109], v[90:91], v[108:109], v[172:173]
	v_pk_fma_f32 v[110:111], v[92:93], v[110:111], v[174:175]
	v_pk_fma_f32 v[112:113], v[94:95], v[112:113], v[176:177]
	v_cvt_pk_bf16_f32 v204, v98, v99
	v_cvt_pk_bf16_f32 v205, v100, v101
	v_cvt_pk_bf16_f32 v206, v102, v103
	v_cvt_pk_bf16_f32 v207, v104, v105
	v_cvt_pk_bf16_f32 v208, v106, v107
	v_cvt_pk_bf16_f32 v209, v108, v109
	v_cvt_pk_bf16_f32 v210, v110, v111
	v_cvt_pk_bf16_f32 v211, v112, v113
	global_store_dwordx2 v203, v[204:205], s[48:49] sc1
	global_store_dwordx2 v203, v[206:207], s[48:49] offset:512 sc1
	global_store_dwordx2 v203, v[208:209], s[48:49] offset:1024 sc1
	global_store_dwordx2 v203, v[210:211], s[48:49] offset:1536 sc1
	s_add_u32 s48, s48, 0x800
	s_addc_u32 s49, s49, 0
	v_pk_mul_f32 v[114:115], v[192:193], v[114:115] op_sel_hi:[0,1]
	v_pk_mul_f32 v[116:117], v[192:193], v[116:117] op_sel_hi:[0,1]
	v_pk_mul_f32 v[118:119], v[192:193], v[118:119] op_sel_hi:[0,1]
	v_pk_mul_f32 v[120:121], v[192:193], v[120:121] op_sel_hi:[0,1]
	v_pk_mul_f32 v[122:123], v[192:193], v[122:123] op_sel_hi:[0,1]
	v_pk_mul_f32 v[124:125], v[192:193], v[124:125] op_sel_hi:[0,1]
	v_pk_mul_f32 v[126:127], v[192:193], v[126:127] op_sel_hi:[0,1]
	v_pk_mul_f32 v[128:129], v[192:193], v[128:129] op_sel_hi:[0,1]
	v_pk_mul_f32 v[114:115], v[64:65], v[114:115]
	v_pk_mul_f32 v[116:117], v[66:67], v[116:117]
	v_pk_mul_f32 v[118:119], v[68:69], v[118:119]
	v_pk_mul_f32 v[120:121], v[70:71], v[120:121]
	v_pk_mul_f32 v[122:123], v[72:73], v[122:123]
	v_pk_mul_f32 v[124:125], v[74:75], v[124:125]
	v_pk_mul_f32 v[126:127], v[76:77], v[126:127]
	v_pk_mul_f32 v[128:129], v[78:79], v[128:129]
	v_pk_fma_f32 v[114:115], v[80:81], v[114:115], v[162:163]
	v_pk_fma_f32 v[116:117], v[82:83], v[116:117], v[164:165]
	v_pk_fma_f32 v[118:119], v[84:85], v[118:119], v[166:167]
	v_pk_fma_f32 v[120:121], v[86:87], v[120:121], v[168:169]
	v_pk_fma_f32 v[122:123], v[88:89], v[122:123], v[170:171]
	v_pk_fma_f32 v[124:125], v[90:91], v[124:125], v[172:173]
	v_pk_fma_f32 v[126:127], v[92:93], v[126:127], v[174:175]
	v_pk_fma_f32 v[128:129], v[94:95], v[128:129], v[176:177]
	v_cvt_pk_bf16_f32 v212, v114, v115
	v_cvt_pk_bf16_f32 v213, v116, v117
	v_cvt_pk_bf16_f32 v214, v118, v119
	v_cvt_pk_bf16_f32 v215, v120, v121
	v_cvt_pk_bf16_f32 v216, v122, v123
	v_cvt_pk_bf16_f32 v217, v124, v125
	v_cvt_pk_bf16_f32 v218, v126, v127
	v_cvt_pk_bf16_f32 v219, v128, v129
	global_store_dwordx2 v203, v[212:213], s[48:49] sc1
	global_store_dwordx2 v203, v[214:215], s[48:49] offset:512 sc1
	global_store_dwordx2 v203, v[216:217], s[48:49] offset:1024 sc1
	global_store_dwordx2 v203, v[218:219], s[48:49] offset:1536 sc1
	s_add_u32 s48, s48, 0x800
	s_addc_u32 s49, s49, 0
	v_pk_mul_f32 v[130:131], v[194:195], v[130:131] op_sel_hi:[0,1]
	v_pk_mul_f32 v[132:133], v[194:195], v[132:133] op_sel_hi:[0,1]
	v_pk_mul_f32 v[134:135], v[194:195], v[134:135] op_sel_hi:[0,1]
	v_pk_mul_f32 v[136:137], v[194:195], v[136:137] op_sel_hi:[0,1]
	v_pk_mul_f32 v[138:139], v[194:195], v[138:139] op_sel_hi:[0,1]
	v_pk_mul_f32 v[140:141], v[194:195], v[140:141] op_sel_hi:[0,1]
	v_pk_mul_f32 v[142:143], v[194:195], v[142:143] op_sel_hi:[0,1]
	v_pk_mul_f32 v[144:145], v[194:195], v[144:145] op_sel_hi:[0,1]
	v_pk_mul_f32 v[130:131], v[64:65], v[130:131]
	v_pk_mul_f32 v[132:133], v[66:67], v[132:133]
	v_pk_mul_f32 v[134:135], v[68:69], v[134:135]
	v_pk_mul_f32 v[136:137], v[70:71], v[136:137]
	v_pk_mul_f32 v[138:139], v[72:73], v[138:139]
	v_pk_mul_f32 v[140:141], v[74:75], v[140:141]
	v_pk_mul_f32 v[142:143], v[76:77], v[142:143]
	v_pk_mul_f32 v[144:145], v[78:79], v[144:145]
	v_pk_fma_f32 v[130:131], v[80:81], v[130:131], v[162:163]
	v_pk_fma_f32 v[132:133], v[82:83], v[132:133], v[164:165]
	v_pk_fma_f32 v[134:135], v[84:85], v[134:135], v[166:167]
	v_pk_fma_f32 v[136:137], v[86:87], v[136:137], v[168:169]
	v_pk_fma_f32 v[138:139], v[88:89], v[138:139], v[170:171]
	v_pk_fma_f32 v[140:141], v[90:91], v[140:141], v[172:173]
	v_pk_fma_f32 v[142:143], v[92:93], v[142:143], v[174:175]
	v_pk_fma_f32 v[144:145], v[94:95], v[144:145], v[176:177]
	v_cvt_pk_bf16_f32 v204, v130, v131
	v_cvt_pk_bf16_f32 v205, v132, v133
	v_cvt_pk_bf16_f32 v206, v134, v135
	v_cvt_pk_bf16_f32 v207, v136, v137
	v_cvt_pk_bf16_f32 v208, v138, v139
	v_cvt_pk_bf16_f32 v209, v140, v141
	v_cvt_pk_bf16_f32 v210, v142, v143
	v_cvt_pk_bf16_f32 v211, v144, v145
	global_store_dwordx2 v203, v[204:205], s[48:49] sc1
	global_store_dwordx2 v203, v[206:207], s[48:49] offset:512 sc1
	global_store_dwordx2 v203, v[208:209], s[48:49] offset:1024 sc1
	global_store_dwordx2 v203, v[210:211], s[48:49] offset:1536 sc1
	s_add_u32 s48, s48, 0x800
	s_addc_u32 s49, s49, 0
	v_pk_mul_f32 v[146:147], v[196:197], v[146:147] op_sel_hi:[0,1]
	v_pk_mul_f32 v[148:149], v[196:197], v[148:149] op_sel_hi:[0,1]
	v_pk_mul_f32 v[150:151], v[196:197], v[150:151] op_sel_hi:[0,1]
	v_pk_mul_f32 v[152:153], v[196:197], v[152:153] op_sel_hi:[0,1]
	v_pk_mul_f32 v[154:155], v[196:197], v[154:155] op_sel_hi:[0,1]
	v_pk_mul_f32 v[156:157], v[196:197], v[156:157] op_sel_hi:[0,1]
	v_pk_mul_f32 v[158:159], v[196:197], v[158:159] op_sel_hi:[0,1]
	v_pk_mul_f32 v[160:161], v[196:197], v[160:161] op_sel_hi:[0,1]
	v_pk_mul_f32 v[146:147], v[64:65], v[146:147]
	v_pk_mul_f32 v[148:149], v[66:67], v[148:149]
	v_pk_mul_f32 v[150:151], v[68:69], v[150:151]
	v_pk_mul_f32 v[152:153], v[70:71], v[152:153]
	v_pk_mul_f32 v[154:155], v[72:73], v[154:155]
	v_pk_mul_f32 v[156:157], v[74:75], v[156:157]
	v_pk_mul_f32 v[158:159], v[76:77], v[158:159]
	v_pk_mul_f32 v[160:161], v[78:79], v[160:161]
	v_pk_fma_f32 v[146:147], v[80:81], v[146:147], v[162:163]
	v_pk_fma_f32 v[148:149], v[82:83], v[148:149], v[164:165]
	v_pk_fma_f32 v[150:151], v[84:85], v[150:151], v[166:167]
	v_pk_fma_f32 v[152:153], v[86:87], v[152:153], v[168:169]
	v_pk_fma_f32 v[154:155], v[88:89], v[154:155], v[170:171]
	v_pk_fma_f32 v[156:157], v[90:91], v[156:157], v[172:173]
	v_pk_fma_f32 v[158:159], v[92:93], v[158:159], v[174:175]
	v_pk_fma_f32 v[160:161], v[94:95], v[160:161], v[176:177]
	v_cvt_pk_bf16_f32 v212, v146, v147
	v_cvt_pk_bf16_f32 v213, v148, v149
	v_cvt_pk_bf16_f32 v214, v150, v151
	v_cvt_pk_bf16_f32 v215, v152, v153
	v_cvt_pk_bf16_f32 v216, v154, v155
	v_cvt_pk_bf16_f32 v217, v156, v157
	v_cvt_pk_bf16_f32 v218, v158, v159
	v_cvt_pk_bf16_f32 v219, v160, v161
	global_store_dwordx2 v203, v[212:213], s[48:49] sc1
	global_store_dwordx2 v203, v[214:215], s[48:49] offset:512 sc1
	global_store_dwordx2 v203, v[216:217], s[48:49] offset:1024 sc1
	global_store_dwordx2 v203, v[218:219], s[48:49] offset:1536 sc1
	s_add_u32 s48, s48, 0x800
	s_addc_u32 s49, s49, 0
	buffer_load_dwordx4 v[98:101], v202, s[12:15], s11 offen sc1
	buffer_load_dwordx4 v[102:105], v202, s[12:15], s11 offen offset:1024 sc1
	buffer_load_dwordx4 v[106:109], v202, s[12:15], s11 offen offset:2048 sc1
	buffer_load_dwordx4 v[110:113], v202, s[12:15], s11 offen offset:3072 sc1
	s_add_u32 s11, s11, 0x1000
	buffer_load_dwordx4 v[114:117], v202, s[12:15], s11 offen sc1
	buffer_load_dwordx4 v[118:121], v202, s[12:15], s11 offen offset:1024 sc1
	buffer_load_dwordx4 v[122:125], v202, s[12:15], s11 offen offset:2048 sc1
	buffer_load_dwordx4 v[126:129], v202, s[12:15], s11 offen offset:3072 sc1
	s_add_u32 s11, s11, 0x1000
	buffer_load_dwordx4 v[130:133], v202, s[12:15], s11 offen sc1
	buffer_load_dwordx4 v[134:137], v202, s[12:15], s11 offen offset:1024 sc1
	buffer_load_dwordx4 v[138:141], v202, s[12:15], s11 offen offset:2048 sc1
	buffer_load_dwordx4 v[142:145], v202, s[12:15], s11 offen offset:3072 sc1
	s_add_u32 s11, s11, 0x1000
	buffer_load_dwordx4 v[146:149], v202, s[12:15], s11 offen sc1
	buffer_load_dwordx4 v[150:153], v202, s[12:15], s11 offen offset:1024 sc1
	buffer_load_dwordx4 v[154:157], v202, s[12:15], s11 offen offset:2048 sc1
	buffer_load_dwordx4 v[158:161], v202, s[12:15], s11 offen offset:3072 sc1
	s_add_u32 s11, s11, 0x1000
	s_waitcnt vmcnt(24)
	v_mul_f32_e32 v178, v0, v0
	v_mul_f32_e32 v179, v16, v16
	v_mul_f32_e32 v180, v32, v32
	v_mul_f32_e32 v181, v48, v48
	v_fma_f32 v178, v1, v1, v178
	v_fma_f32 v179, v17, v17, v179
	v_fma_f32 v180, v33, v33, v180
	v_fma_f32 v181, v49, v49, v181
	v_fma_f32 v178, v2, v2, v178
	v_fma_f32 v179, v18, v18, v179
	v_fma_f32 v180, v34, v34, v180
	v_fma_f32 v181, v50, v50, v181
	v_fma_f32 v178, v3, v3, v178
	v_fma_f32 v179, v19, v19, v179
	v_fma_f32 v180, v35, v35, v180
	v_fma_f32 v181, v51, v51, v181
	v_fma_f32 v178, v4, v4, v178
	v_fma_f32 v179, v20, v20, v179
	v_fma_f32 v180, v36, v36, v180
	v_fma_f32 v181, v52, v52, v181
	v_fma_f32 v178, v5, v5, v178
	v_fma_f32 v179, v21, v21, v179
	v_fma_f32 v180, v37, v37, v180
	v_fma_f32 v181, v53, v53, v181
	v_fma_f32 v178, v6, v6, v178
	v_fma_f32 v179, v22, v22, v179
	v_fma_f32 v180, v38, v38, v180
	v_fma_f32 v181, v54, v54, v181
	v_fma_f32 v178, v7, v7, v178
	v_fma_f32 v179, v23, v23, v179
	v_fma_f32 v180, v39, v39, v180
	v_fma_f32 v181, v55, v55, v181
	v_fma_f32 v178, v8, v8, v178
	v_fma_f32 v179, v24, v24, v179
	v_fma_f32 v180, v40, v40, v180
	v_fma_f32 v181, v56, v56, v181
	v_fma_f32 v178, v9, v9, v178
	v_fma_f32 v179, v25, v25, v179
	v_fma_f32 v180, v41, v41, v180
	v_fma_f32 v181, v57, v57, v181
	v_fma_f32 v178, v10, v10, v178
	v_fma_f32 v179, v26, v26, v179
	v_fma_f32 v180, v42, v42, v180
	v_fma_f32 v181, v58, v58, v181
	v_fma_f32 v178, v11, v11, v178
	v_fma_f32 v179, v27, v27, v179
	v_fma_f32 v180, v43, v43, v180
	v_fma_f32 v181, v59, v59, v181
	v_fma_f32 v178, v12, v12, v178
	v_fma_f32 v179, v28, v28, v179
	v_fma_f32 v180, v44, v44, v180
	v_fma_f32 v181, v60, v60, v181
	v_fma_f32 v178, v13, v13, v178
	v_fma_f32 v179, v29, v29, v179
	v_fma_f32 v180, v45, v45, v180
	v_fma_f32 v181, v61, v61, v181
	v_fma_f32 v178, v14, v14, v178
	v_fma_f32 v179, v30, v30, v179
	v_fma_f32 v180, v46, v46, v180
	v_fma_f32 v181, v62, v62, v181
	v_fma_f32 v178, v15, v15, v178
	v_fma_f32 v179, v31, v31, v179
	v_fma_f32 v180, v47, v47, v180
	v_fma_f32 v181, v63, v63, v181
	v_add_f32_dpp v178, v178, v178 quad_perm:[1,0,3,2] row_mask:0xf bank_mask:0xf
	v_add_f32_dpp v179, v179, v179 quad_perm:[1,0,3,2] row_mask:0xf bank_mask:0xf
	v_add_f32_dpp v180, v180, v180 quad_perm:[1,0,3,2] row_mask:0xf bank_mask:0xf
	v_add_f32_dpp v181, v181, v181 quad_perm:[1,0,3,2] row_mask:0xf bank_mask:0xf
	v_add_f32_dpp v178, v178, v178 quad_perm:[2,3,0,1] row_mask:0xf bank_mask:0xf
	v_add_f32_dpp v179, v179, v179 quad_perm:[2,3,0,1] row_mask:0xf bank_mask:0xf
	v_add_f32_dpp v180, v180, v180 quad_perm:[2,3,0,1] row_mask:0xf bank_mask:0xf
	v_add_f32_dpp v181, v181, v181 quad_perm:[2,3,0,1] row_mask:0xf bank_mask:0xf
	v_add_f32_dpp v178, v178, v178 row_half_mirror row_mask:0xf bank_mask:0xf
	v_add_f32_dpp v179, v179, v179 row_half_mirror row_mask:0xf bank_mask:0xf
	v_add_f32_dpp v180, v180, v180 row_half_mirror row_mask:0xf bank_mask:0xf
	v_add_f32_dpp v181, v181, v181 row_half_mirror row_mask:0xf bank_mask:0xf
	v_add_f32_dpp v178, v178, v178 row_ror:8 row_mask:0xf bank_mask:0xf
	v_add_f32_dpp v179, v179, v179 row_ror:8 row_mask:0xf bank_mask:0xf
	v_add_f32_dpp v180, v180, v180 row_ror:8 row_mask:0xf bank_mask:0xf
	v_add_f32_dpp v181, v181, v181 row_ror:8 row_mask:0xf bank_mask:0xf
	v_mov_b32_e32 v182, v178
	v_mov_b32_e32 v183, v179
	v_mov_b32_e32 v184, v180
	v_mov_b32_e32 v185, v181
	v_permlane16_swap_b32_e32 v182, v178
	v_permlane16_swap_b32_e32 v183, v179
	v_permlane16_swap_b32_e32 v184, v180
	v_permlane16_swap_b32_e32 v185, v181
	v_add_f32_e32 v178, v178, v182
	v_add_f32_e32 v179, v179, v183
	v_add_f32_e32 v180, v180, v184
	v_add_f32_e32 v181, v181, v185
	v_mov_b32_e32 v182, v178
	v_mov_b32_e32 v183, v179
	v_mov_b32_e32 v184, v180
	v_mov_b32_e32 v185, v181
	v_permlane32_swap_b32_e32 v182, v178
	v_permlane32_swap_b32_e32 v183, v179
	v_permlane32_swap_b32_e32 v184, v180
	v_permlane32_swap_b32_e32 v185, v181
	v_add_f32_e32 v178, v178, v182
	v_add_f32_e32 v179, v179, v183
	v_add_f32_e32 v180, v180, v184
	v_add_f32_e32 v181, v181, v185
	v_fmamk_f32 v198, v178, 0x3a800000, v225
	v_fmamk_f32 v199, v179, 0x3a800000, v225
	v_fmamk_f32 v200, v180, 0x3a800000, v225
	v_fmamk_f32 v201, v181, 0x3a800000, v225
	v_mul_f32_e32 v182, 0x4b800000, v198
	v_mul_f32_e32 v183, 0x4b800000, v199
	v_mul_f32_e32 v184, 0x4b800000, v200
	v_mul_f32_e32 v185, 0x4b800000, v201
	v_cmp_gt_f32_e64 s[2:3], s30, v198
	v_cmp_gt_f32_e64 s[50:51], s30, v199
	v_cmp_gt_f32_e64 s[88:89], s30, v200
	v_cmp_gt_f32_e64 s[90:91], s30, v201
	v_cndmask_b32_e64 v198, v198, v182, s[2:3]
	v_cndmask_b32_e64 v199, v199, v183, s[50:51]
	v_cndmask_b32_e64 v200, v200, v184, s[88:89]
	v_cndmask_b32_e64 v201, v201, v185, s[90:91]
	v_rsq_f32_e32 v198, v198
	v_rsq_f32_e32 v199, v199
	v_rsq_f32_e32 v200, v200
	v_rsq_f32_e32 v201, v201
	v_mul_f32_e32 v182, 0x45800000, v198
	v_mul_f32_e32 v183, 0x45800000, v199
	v_mul_f32_e32 v184, 0x45800000, v200
	v_mul_f32_e32 v185, 0x45800000, v201
	v_cndmask_b32_e64 v186, v198, v182, s[2:3]
	v_cndmask_b32_e64 v192, v199, v183, s[50:51]
	v_cndmask_b32_e64 v194, v200, v184, s[88:89]
	v_cndmask_b32_e64 v196, v201, v185, s[90:91]
	v_pk_mul_f32 v[0:1], v[186:187], v[0:1] op_sel_hi:[0,1]
	v_pk_mul_f32 v[2:3], v[186:187], v[2:3] op_sel_hi:[0,1]
	v_pk_mul_f32 v[4:5], v[186:187], v[4:5] op_sel_hi:[0,1]
	v_pk_mul_f32 v[6:7], v[186:187], v[6:7] op_sel_hi:[0,1]
	v_pk_mul_f32 v[8:9], v[186:187], v[8:9] op_sel_hi:[0,1]
	v_pk_mul_f32 v[10:11], v[186:187], v[10:11] op_sel_hi:[0,1]
	v_pk_mul_f32 v[12:13], v[186:187], v[12:13] op_sel_hi:[0,1]
	v_pk_mul_f32 v[14:15], v[186:187], v[14:15] op_sel_hi:[0,1]
	v_pk_mul_f32 v[0:1], v[64:65], v[0:1]
	v_pk_mul_f32 v[2:3], v[66:67], v[2:3]
	v_pk_mul_f32 v[4:5], v[68:69], v[4:5]
	v_pk_mul_f32 v[6:7], v[70:71], v[6:7]
	v_pk_mul_f32 v[8:9], v[72:73], v[8:9]
	v_pk_mul_f32 v[10:11], v[74:75], v[10:11]
	v_pk_mul_f32 v[12:13], v[76:77], v[12:13]
	v_pk_mul_f32 v[14:15], v[78:79], v[14:15]
	v_pk_fma_f32 v[0:1], v[80:81], v[0:1], v[162:163]
	v_pk_fma_f32 v[2:3], v[82:83], v[2:3], v[164:165]
	v_pk_fma_f32 v[4:5], v[84:85], v[4:5], v[166:167]
	v_pk_fma_f32 v[6:7], v[86:87], v[6:7], v[168:169]
	v_pk_fma_f32 v[8:9], v[88:89], v[8:9], v[170:171]
	v_pk_fma_f32 v[10:11], v[90:91], v[10:11], v[172:173]
	v_pk_fma_f32 v[12:13], v[92:93], v[12:13], v[174:175]
	v_pk_fma_f32 v[14:15], v[94:95], v[14:15], v[176:177]
	v_cvt_pk_bf16_f32 v204, v0, v1
	v_cvt_pk_bf16_f32 v205, v2, v3
	v_cvt_pk_bf16_f32 v206, v4, v5
	v_cvt_pk_bf16_f32 v207, v6, v7
	v_cvt_pk_bf16_f32 v208, v8, v9
	v_cvt_pk_bf16_f32 v209, v10, v11
	v_cvt_pk_bf16_f32 v210, v12, v13
	v_cvt_pk_bf16_f32 v211, v14, v15
	global_store_dwordx2 v203, v[204:205], s[48:49] sc1
	global_store_dwordx2 v203, v[206:207], s[48:49] offset:512 sc1
	global_store_dwordx2 v203, v[208:209], s[48:49] offset:1024 sc1
	global_store_dwordx2 v203, v[210:211], s[48:49] offset:1536 sc1
	s_add_u32 s48, s48, 0x800
	s_addc_u32 s49, s49, 0
	v_pk_mul_f32 v[16:17], v[192:193], v[16:17] op_sel_hi:[0,1]
	v_pk_mul_f32 v[18:19], v[192:193], v[18:19] op_sel_hi:[0,1]
	v_pk_mul_f32 v[20:21], v[192:193], v[20:21] op_sel_hi:[0,1]
	v_pk_mul_f32 v[22:23], v[192:193], v[22:23] op_sel_hi:[0,1]
	v_pk_mul_f32 v[24:25], v[192:193], v[24:25] op_sel_hi:[0,1]
	v_pk_mul_f32 v[26:27], v[192:193], v[26:27] op_sel_hi:[0,1]
	v_pk_mul_f32 v[28:29], v[192:193], v[28:29] op_sel_hi:[0,1]
	v_pk_mul_f32 v[30:31], v[192:193], v[30:31] op_sel_hi:[0,1]
	v_pk_mul_f32 v[16:17], v[64:65], v[16:17]
	v_pk_mul_f32 v[18:19], v[66:67], v[18:19]
	v_pk_mul_f32 v[20:21], v[68:69], v[20:21]
	v_pk_mul_f32 v[22:23], v[70:71], v[22:23]
	v_pk_mul_f32 v[24:25], v[72:73], v[24:25]
	v_pk_mul_f32 v[26:27], v[74:75], v[26:27]
	v_pk_mul_f32 v[28:29], v[76:77], v[28:29]
	v_pk_mul_f32 v[30:31], v[78:79], v[30:31]
	v_pk_fma_f32 v[16:17], v[80:81], v[16:17], v[162:163]
	v_pk_fma_f32 v[18:19], v[82:83], v[18:19], v[164:165]
	v_pk_fma_f32 v[20:21], v[84:85], v[20:21], v[166:167]
	v_pk_fma_f32 v[22:23], v[86:87], v[22:23], v[168:169]
	v_pk_fma_f32 v[24:25], v[88:89], v[24:25], v[170:171]
	v_pk_fma_f32 v[26:27], v[90:91], v[26:27], v[172:173]
	v_pk_fma_f32 v[28:29], v[92:93], v[28:29], v[174:175]
	v_pk_fma_f32 v[30:31], v[94:95], v[30:31], v[176:177]
	v_cvt_pk_bf16_f32 v212, v16, v17
	v_cvt_pk_bf16_f32 v213, v18, v19
	v_cvt_pk_bf16_f32 v214, v20, v21
	v_cvt_pk_bf16_f32 v215, v22, v23
	v_cvt_pk_bf16_f32 v216, v24, v25
	v_cvt_pk_bf16_f32 v217, v26, v27
	v_cvt_pk_bf16_f32 v218, v28, v29
	v_cvt_pk_bf16_f32 v219, v30, v31
	global_store_dwordx2 v203, v[212:213], s[48:49] sc1
	global_store_dwordx2 v203, v[214:215], s[48:49] offset:512 sc1
	global_store_dwordx2 v203, v[216:217], s[48:49] offset:1024 sc1
	global_store_dwordx2 v203, v[218:219], s[48:49] offset:1536 sc1
	s_add_u32 s48, s48, 0x800
	s_addc_u32 s49, s49, 0
	v_pk_mul_f32 v[32:33], v[194:195], v[32:33] op_sel_hi:[0,1]
	v_pk_mul_f32 v[34:35], v[194:195], v[34:35] op_sel_hi:[0,1]
	v_pk_mul_f32 v[36:37], v[194:195], v[36:37] op_sel_hi:[0,1]
	v_pk_mul_f32 v[38:39], v[194:195], v[38:39] op_sel_hi:[0,1]
	v_pk_mul_f32 v[40:41], v[194:195], v[40:41] op_sel_hi:[0,1]
	v_pk_mul_f32 v[42:43], v[194:195], v[42:43] op_sel_hi:[0,1]
	v_pk_mul_f32 v[44:45], v[194:195], v[44:45] op_sel_hi:[0,1]
	v_pk_mul_f32 v[46:47], v[194:195], v[46:47] op_sel_hi:[0,1]
	v_pk_mul_f32 v[32:33], v[64:65], v[32:33]
	v_pk_mul_f32 v[34:35], v[66:67], v[34:35]
	v_pk_mul_f32 v[36:37], v[68:69], v[36:37]
	v_pk_mul_f32 v[38:39], v[70:71], v[38:39]
	v_pk_mul_f32 v[40:41], v[72:73], v[40:41]
	v_pk_mul_f32 v[42:43], v[74:75], v[42:43]
	v_pk_mul_f32 v[44:45], v[76:77], v[44:45]
	v_pk_mul_f32 v[46:47], v[78:79], v[46:47]
	v_pk_fma_f32 v[32:33], v[80:81], v[32:33], v[162:163]
	v_pk_fma_f32 v[34:35], v[82:83], v[34:35], v[164:165]
	v_pk_fma_f32 v[36:37], v[84:85], v[36:37], v[166:167]
	v_pk_fma_f32 v[38:39], v[86:87], v[38:39], v[168:169]
	v_pk_fma_f32 v[40:41], v[88:89], v[40:41], v[170:171]
	v_pk_fma_f32 v[42:43], v[90:91], v[42:43], v[172:173]
	v_pk_fma_f32 v[44:45], v[92:93], v[44:45], v[174:175]
	v_pk_fma_f32 v[46:47], v[94:95], v[46:47], v[176:177]
	v_cvt_pk_bf16_f32 v204, v32, v33
	v_cvt_pk_bf16_f32 v205, v34, v35
	v_cvt_pk_bf16_f32 v206, v36, v37
	v_cvt_pk_bf16_f32 v207, v38, v39
	v_cvt_pk_bf16_f32 v208, v40, v41
	v_cvt_pk_bf16_f32 v209, v42, v43
	v_cvt_pk_bf16_f32 v210, v44, v45
	v_cvt_pk_bf16_f32 v211, v46, v47
	global_store_dwordx2 v203, v[204:205], s[48:49] sc1
	global_store_dwordx2 v203, v[206:207], s[48:49] offset:512 sc1
	global_store_dwordx2 v203, v[208:209], s[48:49] offset:1024 sc1
	global_store_dwordx2 v203, v[210:211], s[48:49] offset:1536 sc1
	s_add_u32 s48, s48, 0x800
	s_addc_u32 s49, s49, 0
	v_pk_mul_f32 v[48:49], v[196:197], v[48:49] op_sel_hi:[0,1]
	v_pk_mul_f32 v[50:51], v[196:197], v[50:51] op_sel_hi:[0,1]
	v_pk_mul_f32 v[52:53], v[196:197], v[52:53] op_sel_hi:[0,1]
	v_pk_mul_f32 v[54:55], v[196:197], v[54:55] op_sel_hi:[0,1]
	v_pk_mul_f32 v[56:57], v[196:197], v[56:57] op_sel_hi:[0,1]
	v_pk_mul_f32 v[58:59], v[196:197], v[58:59] op_sel_hi:[0,1]
	v_pk_mul_f32 v[60:61], v[196:197], v[60:61] op_sel_hi:[0,1]
	v_pk_mul_f32 v[62:63], v[196:197], v[62:63] op_sel_hi:[0,1]
	v_pk_mul_f32 v[48:49], v[64:65], v[48:49]
	v_pk_mul_f32 v[50:51], v[66:67], v[50:51]
	v_pk_mul_f32 v[52:53], v[68:69], v[52:53]
	v_pk_mul_f32 v[54:55], v[70:71], v[54:55]
	v_pk_mul_f32 v[56:57], v[72:73], v[56:57]
	v_pk_mul_f32 v[58:59], v[74:75], v[58:59]
	v_pk_mul_f32 v[60:61], v[76:77], v[60:61]
	v_pk_mul_f32 v[62:63], v[78:79], v[62:63]
	v_pk_fma_f32 v[48:49], v[80:81], v[48:49], v[162:163]
	v_pk_fma_f32 v[50:51], v[82:83], v[50:51], v[164:165]
	v_pk_fma_f32 v[52:53], v[84:85], v[52:53], v[166:167]
	v_pk_fma_f32 v[54:55], v[86:87], v[54:55], v[168:169]
	v_pk_fma_f32 v[56:57], v[88:89], v[56:57], v[170:171]
	v_pk_fma_f32 v[58:59], v[90:91], v[58:59], v[172:173]
	v_pk_fma_f32 v[60:61], v[92:93], v[60:61], v[174:175]
	v_pk_fma_f32 v[62:63], v[94:95], v[62:63], v[176:177]
	v_cvt_pk_bf16_f32 v212, v48, v49
	v_cvt_pk_bf16_f32 v213, v50, v51
	v_cvt_pk_bf16_f32 v214, v52, v53
	v_cvt_pk_bf16_f32 v215, v54, v55
	v_cvt_pk_bf16_f32 v216, v56, v57
	v_cvt_pk_bf16_f32 v217, v58, v59
	v_cvt_pk_bf16_f32 v218, v60, v61
	v_cvt_pk_bf16_f32 v219, v62, v63
	global_store_dwordx2 v203, v[212:213], s[48:49] sc1
	global_store_dwordx2 v203, v[214:215], s[48:49] offset:512 sc1
	global_store_dwordx2 v203, v[216:217], s[48:49] offset:1024 sc1
	global_store_dwordx2 v203, v[218:219], s[48:49] offset:1536 sc1
	s_add_u32 s48, s48, 0x800
	s_addc_u32 s49, s49, 0
	s_waitcnt vmcnt(8)
	v_mul_f32_e32 v178, v98, v98
	v_mul_f32_e32 v179, v114, v114
	v_mul_f32_e32 v180, v130, v130
	v_mul_f32_e32 v181, v146, v146
	v_fma_f32 v178, v99, v99, v178
	v_fma_f32 v179, v115, v115, v179
	v_fma_f32 v180, v131, v131, v180
	v_fma_f32 v181, v147, v147, v181
	v_fma_f32 v178, v100, v100, v178
	v_fma_f32 v179, v116, v116, v179
	v_fma_f32 v180, v132, v132, v180
	v_fma_f32 v181, v148, v148, v181
	v_fma_f32 v178, v101, v101, v178
	v_fma_f32 v179, v117, v117, v179
	v_fma_f32 v180, v133, v133, v180
	v_fma_f32 v181, v149, v149, v181
	v_fma_f32 v178, v102, v102, v178
	v_fma_f32 v179, v118, v118, v179
	v_fma_f32 v180, v134, v134, v180
	v_fma_f32 v181, v150, v150, v181
	v_fma_f32 v178, v103, v103, v178
	v_fma_f32 v179, v119, v119, v179
	v_fma_f32 v180, v135, v135, v180
	v_fma_f32 v181, v151, v151, v181
	v_fma_f32 v178, v104, v104, v178
	v_fma_f32 v179, v120, v120, v179
	v_fma_f32 v180, v136, v136, v180
	v_fma_f32 v181, v152, v152, v181
	v_fma_f32 v178, v105, v105, v178
	v_fma_f32 v179, v121, v121, v179
	v_fma_f32 v180, v137, v137, v180
	v_fma_f32 v181, v153, v153, v181
	v_fma_f32 v178, v106, v106, v178
	v_fma_f32 v179, v122, v122, v179
	v_fma_f32 v180, v138, v138, v180
	v_fma_f32 v181, v154, v154, v181
	v_fma_f32 v178, v107, v107, v178
	v_fma_f32 v179, v123, v123, v179
	v_fma_f32 v180, v139, v139, v180
	v_fma_f32 v181, v155, v155, v181
	v_fma_f32 v178, v108, v108, v178
	v_fma_f32 v179, v124, v124, v179
	v_fma_f32 v180, v140, v140, v180
	v_fma_f32 v181, v156, v156, v181
	v_fma_f32 v178, v109, v109, v178
	v_fma_f32 v179, v125, v125, v179
	v_fma_f32 v180, v141, v141, v180
	v_fma_f32 v181, v157, v157, v181
	v_fma_f32 v178, v110, v110, v178
	v_fma_f32 v179, v126, v126, v179
	v_fma_f32 v180, v142, v142, v180
	v_fma_f32 v181, v158, v158, v181
	v_fma_f32 v178, v111, v111, v178
	v_fma_f32 v179, v127, v127, v179
	v_fma_f32 v180, v143, v143, v180
	v_fma_f32 v181, v159, v159, v181
	v_fma_f32 v178, v112, v112, v178
	v_fma_f32 v179, v128, v128, v179
	v_fma_f32 v180, v144, v144, v180
	v_fma_f32 v181, v160, v160, v181
	v_fma_f32 v178, v113, v113, v178
	v_fma_f32 v179, v129, v129, v179
	v_fma_f32 v180, v145, v145, v180
	v_fma_f32 v181, v161, v161, v181
	v_add_f32_dpp v178, v178, v178 quad_perm:[1,0,3,2] row_mask:0xf bank_mask:0xf
	v_add_f32_dpp v179, v179, v179 quad_perm:[1,0,3,2] row_mask:0xf bank_mask:0xf
	v_add_f32_dpp v180, v180, v180 quad_perm:[1,0,3,2] row_mask:0xf bank_mask:0xf
	v_add_f32_dpp v181, v181, v181 quad_perm:[1,0,3,2] row_mask:0xf bank_mask:0xf
	v_add_f32_dpp v178, v178, v178 quad_perm:[2,3,0,1] row_mask:0xf bank_mask:0xf
	v_add_f32_dpp v179, v179, v179 quad_perm:[2,3,0,1] row_mask:0xf bank_mask:0xf
	v_add_f32_dpp v180, v180, v180 quad_perm:[2,3,0,1] row_mask:0xf bank_mask:0xf
	v_add_f32_dpp v181, v181, v181 quad_perm:[2,3,0,1] row_mask:0xf bank_mask:0xf
	v_add_f32_dpp v178, v178, v178 row_half_mirror row_mask:0xf bank_mask:0xf
	v_add_f32_dpp v179, v179, v179 row_half_mirror row_mask:0xf bank_mask:0xf
	v_add_f32_dpp v180, v180, v180 row_half_mirror row_mask:0xf bank_mask:0xf
	v_add_f32_dpp v181, v181, v181 row_half_mirror row_mask:0xf bank_mask:0xf
	v_add_f32_dpp v178, v178, v178 row_ror:8 row_mask:0xf bank_mask:0xf
	v_add_f32_dpp v179, v179, v179 row_ror:8 row_mask:0xf bank_mask:0xf
	v_add_f32_dpp v180, v180, v180 row_ror:8 row_mask:0xf bank_mask:0xf
	v_add_f32_dpp v181, v181, v181 row_ror:8 row_mask:0xf bank_mask:0xf
	v_mov_b32_e32 v182, v178
	v_mov_b32_e32 v183, v179
	v_mov_b32_e32 v184, v180
	v_mov_b32_e32 v185, v181
	v_permlane16_swap_b32_e32 v182, v178
	v_permlane16_swap_b32_e32 v183, v179
	v_permlane16_swap_b32_e32 v184, v180
	v_permlane16_swap_b32_e32 v185, v181
	v_add_f32_e32 v178, v178, v182
	v_add_f32_e32 v179, v179, v183
	v_add_f32_e32 v180, v180, v184
	v_add_f32_e32 v181, v181, v185
	v_mov_b32_e32 v182, v178
	v_mov_b32_e32 v183, v179
	v_mov_b32_e32 v184, v180
	v_mov_b32_e32 v185, v181
	v_permlane32_swap_b32_e32 v182, v178
	v_permlane32_swap_b32_e32 v183, v179
	v_permlane32_swap_b32_e32 v184, v180
	v_permlane32_swap_b32_e32 v185, v181
	v_add_f32_e32 v178, v178, v182
	v_add_f32_e32 v179, v179, v183
	v_add_f32_e32 v180, v180, v184
	v_add_f32_e32 v181, v181, v185
	v_fmamk_f32 v198, v178, 0x3a800000, v225
	v_fmamk_f32 v199, v179, 0x3a800000, v225
	v_fmamk_f32 v200, v180, 0x3a800000, v225
	v_fmamk_f32 v201, v181, 0x3a800000, v225
	v_mul_f32_e32 v182, 0x4b800000, v198
	v_mul_f32_e32 v183, 0x4b800000, v199
	v_mul_f32_e32 v184, 0x4b800000, v200
	v_mul_f32_e32 v185, 0x4b800000, v201
	v_cmp_gt_f32_e64 s[2:3], s30, v198
	v_cmp_gt_f32_e64 s[50:51], s30, v199
	v_cmp_gt_f32_e64 s[88:89], s30, v200
	v_cmp_gt_f32_e64 s[90:91], s30, v201
	v_cndmask_b32_e64 v198, v198, v182, s[2:3]
	v_cndmask_b32_e64 v199, v199, v183, s[50:51]
	v_cndmask_b32_e64 v200, v200, v184, s[88:89]
	v_cndmask_b32_e64 v201, v201, v185, s[90:91]
	v_rsq_f32_e32 v198, v198
	v_rsq_f32_e32 v199, v199
	v_rsq_f32_e32 v200, v200
	v_rsq_f32_e32 v201, v201
	v_mul_f32_e32 v182, 0x45800000, v198
	v_mul_f32_e32 v183, 0x45800000, v199
	v_mul_f32_e32 v184, 0x45800000, v200
	v_mul_f32_e32 v185, 0x45800000, v201
	v_cndmask_b32_e64 v186, v198, v182, s[2:3]
	v_cndmask_b32_e64 v192, v199, v183, s[50:51]
	v_cndmask_b32_e64 v194, v200, v184, s[88:89]
	v_cndmask_b32_e64 v196, v201, v185, s[90:91]
	v_pk_mul_f32 v[98:99], v[186:187], v[98:99] op_sel_hi:[0,1]
	v_pk_mul_f32 v[100:101], v[186:187], v[100:101] op_sel_hi:[0,1]
	v_pk_mul_f32 v[102:103], v[186:187], v[102:103] op_sel_hi:[0,1]
	v_pk_mul_f32 v[104:105], v[186:187], v[104:105] op_sel_hi:[0,1]
	v_pk_mul_f32 v[106:107], v[186:187], v[106:107] op_sel_hi:[0,1]
	v_pk_mul_f32 v[108:109], v[186:187], v[108:109] op_sel_hi:[0,1]
	v_pk_mul_f32 v[110:111], v[186:187], v[110:111] op_sel_hi:[0,1]
	v_pk_mul_f32 v[112:113], v[186:187], v[112:113] op_sel_hi:[0,1]
	v_pk_mul_f32 v[98:99], v[64:65], v[98:99]
	v_pk_mul_f32 v[100:101], v[66:67], v[100:101]
	v_pk_mul_f32 v[102:103], v[68:69], v[102:103]
	v_pk_mul_f32 v[104:105], v[70:71], v[104:105]
	v_pk_mul_f32 v[106:107], v[72:73], v[106:107]
	v_pk_mul_f32 v[108:109], v[74:75], v[108:109]
	v_pk_mul_f32 v[110:111], v[76:77], v[110:111]
	v_pk_mul_f32 v[112:113], v[78:79], v[112:113]
	v_pk_fma_f32 v[98:99], v[80:81], v[98:99], v[162:163]
	v_pk_fma_f32 v[100:101], v[82:83], v[100:101], v[164:165]
	v_pk_fma_f32 v[102:103], v[84:85], v[102:103], v[166:167]
	v_pk_fma_f32 v[104:105], v[86:87], v[104:105], v[168:169]
	v_pk_fma_f32 v[106:107], v[88:89], v[106:107], v[170:171]
	v_pk_fma_f32 v[108:109], v[90:91], v[108:109], v[172:173]
	v_pk_fma_f32 v[110:111], v[92:93], v[110:111], v[174:175]
	v_pk_fma_f32 v[112:113], v[94:95], v[112:113], v[176:177]
	v_cvt_pk_bf16_f32 v204, v98, v99
	v_cvt_pk_bf16_f32 v205, v100, v101
	v_cvt_pk_bf16_f32 v206, v102, v103
	v_cvt_pk_bf16_f32 v207, v104, v105
	v_cvt_pk_bf16_f32 v208, v106, v107
	v_cvt_pk_bf16_f32 v209, v108, v109
	v_cvt_pk_bf16_f32 v210, v110, v111
	v_cvt_pk_bf16_f32 v211, v112, v113
	global_store_dwordx2 v203, v[204:205], s[48:49] sc1
	global_store_dwordx2 v203, v[206:207], s[48:49] offset:512 sc1
	global_store_dwordx2 v203, v[208:209], s[48:49] offset:1024 sc1
	global_store_dwordx2 v203, v[210:211], s[48:49] offset:1536 sc1
	s_add_u32 s48, s48, 0x800
	s_addc_u32 s49, s49, 0
	v_pk_mul_f32 v[114:115], v[192:193], v[114:115] op_sel_hi:[0,1]
	v_pk_mul_f32 v[116:117], v[192:193], v[116:117] op_sel_hi:[0,1]
	v_pk_mul_f32 v[118:119], v[192:193], v[118:119] op_sel_hi:[0,1]
	v_pk_mul_f32 v[120:121], v[192:193], v[120:121] op_sel_hi:[0,1]
	v_pk_mul_f32 v[122:123], v[192:193], v[122:123] op_sel_hi:[0,1]
	v_pk_mul_f32 v[124:125], v[192:193], v[124:125] op_sel_hi:[0,1]
	v_pk_mul_f32 v[126:127], v[192:193], v[126:127] op_sel_hi:[0,1]
	v_pk_mul_f32 v[128:129], v[192:193], v[128:129] op_sel_hi:[0,1]
	v_pk_mul_f32 v[114:115], v[64:65], v[114:115]
	v_pk_mul_f32 v[116:117], v[66:67], v[116:117]
	v_pk_mul_f32 v[118:119], v[68:69], v[118:119]
	v_pk_mul_f32 v[120:121], v[70:71], v[120:121]
	v_pk_mul_f32 v[122:123], v[72:73], v[122:123]
	v_pk_mul_f32 v[124:125], v[74:75], v[124:125]
	v_pk_mul_f32 v[126:127], v[76:77], v[126:127]
	v_pk_mul_f32 v[128:129], v[78:79], v[128:129]
	v_pk_fma_f32 v[114:115], v[80:81], v[114:115], v[162:163]
	v_pk_fma_f32 v[116:117], v[82:83], v[116:117], v[164:165]
	v_pk_fma_f32 v[118:119], v[84:85], v[118:119], v[166:167]
	v_pk_fma_f32 v[120:121], v[86:87], v[120:121], v[168:169]
	v_pk_fma_f32 v[122:123], v[88:89], v[122:123], v[170:171]
	v_pk_fma_f32 v[124:125], v[90:91], v[124:125], v[172:173]
	v_pk_fma_f32 v[126:127], v[92:93], v[126:127], v[174:175]
	v_pk_fma_f32 v[128:129], v[94:95], v[128:129], v[176:177]
	v_cvt_pk_bf16_f32 v212, v114, v115
	v_cvt_pk_bf16_f32 v213, v116, v117
	v_cvt_pk_bf16_f32 v214, v118, v119
	v_cvt_pk_bf16_f32 v215, v120, v121
	v_cvt_pk_bf16_f32 v216, v122, v123
	v_cvt_pk_bf16_f32 v217, v124, v125
	v_cvt_pk_bf16_f32 v218, v126, v127
	v_cvt_pk_bf16_f32 v219, v128, v129
	global_store_dwordx2 v203, v[212:213], s[48:49] sc1
	global_store_dwordx2 v203, v[214:215], s[48:49] offset:512 sc1
	global_store_dwordx2 v203, v[216:217], s[48:49] offset:1024 sc1
	global_store_dwordx2 v203, v[218:219], s[48:49] offset:1536 sc1
	s_add_u32 s48, s48, 0x800
	s_addc_u32 s49, s49, 0
	v_pk_mul_f32 v[130:131], v[194:195], v[130:131] op_sel_hi:[0,1]
	v_pk_mul_f32 v[132:133], v[194:195], v[132:133] op_sel_hi:[0,1]
	v_pk_mul_f32 v[134:135], v[194:195], v[134:135] op_sel_hi:[0,1]
	v_pk_mul_f32 v[136:137], v[194:195], v[136:137] op_sel_hi:[0,1]
	v_pk_mul_f32 v[138:139], v[194:195], v[138:139] op_sel_hi:[0,1]
	v_pk_mul_f32 v[140:141], v[194:195], v[140:141] op_sel_hi:[0,1]
	v_pk_mul_f32 v[142:143], v[194:195], v[142:143] op_sel_hi:[0,1]
	v_pk_mul_f32 v[144:145], v[194:195], v[144:145] op_sel_hi:[0,1]
	v_pk_mul_f32 v[130:131], v[64:65], v[130:131]
	v_pk_mul_f32 v[132:133], v[66:67], v[132:133]
	v_pk_mul_f32 v[134:135], v[68:69], v[134:135]
	v_pk_mul_f32 v[136:137], v[70:71], v[136:137]
	v_pk_mul_f32 v[138:139], v[72:73], v[138:139]
	v_pk_mul_f32 v[140:141], v[74:75], v[140:141]
	v_pk_mul_f32 v[142:143], v[76:77], v[142:143]
	v_pk_mul_f32 v[144:145], v[78:79], v[144:145]
	v_pk_fma_f32 v[130:131], v[80:81], v[130:131], v[162:163]
	v_pk_fma_f32 v[132:133], v[82:83], v[132:133], v[164:165]
	v_pk_fma_f32 v[134:135], v[84:85], v[134:135], v[166:167]
	v_pk_fma_f32 v[136:137], v[86:87], v[136:137], v[168:169]
	v_pk_fma_f32 v[138:139], v[88:89], v[138:139], v[170:171]
	v_pk_fma_f32 v[140:141], v[90:91], v[140:141], v[172:173]
	v_pk_fma_f32 v[142:143], v[92:93], v[142:143], v[174:175]
	v_pk_fma_f32 v[144:145], v[94:95], v[144:145], v[176:177]
	v_cvt_pk_bf16_f32 v204, v130, v131
	v_cvt_pk_bf16_f32 v205, v132, v133
	v_cvt_pk_bf16_f32 v206, v134, v135
	v_cvt_pk_bf16_f32 v207, v136, v137
	v_cvt_pk_bf16_f32 v208, v138, v139
	v_cvt_pk_bf16_f32 v209, v140, v141
	v_cvt_pk_bf16_f32 v210, v142, v143
	v_cvt_pk_bf16_f32 v211, v144, v145
	global_store_dwordx2 v203, v[204:205], s[48:49] sc1
	global_store_dwordx2 v203, v[206:207], s[48:49] offset:512 sc1
	global_store_dwordx2 v203, v[208:209], s[48:49] offset:1024 sc1
	global_store_dwordx2 v203, v[210:211], s[48:49] offset:1536 sc1
	s_add_u32 s48, s48, 0x800
	s_addc_u32 s49, s49, 0
	v_pk_mul_f32 v[146:147], v[196:197], v[146:147] op_sel_hi:[0,1]
	v_pk_mul_f32 v[148:149], v[196:197], v[148:149] op_sel_hi:[0,1]
	v_pk_mul_f32 v[150:151], v[196:197], v[150:151] op_sel_hi:[0,1]
	v_pk_mul_f32 v[152:153], v[196:197], v[152:153] op_sel_hi:[0,1]
	v_pk_mul_f32 v[154:155], v[196:197], v[154:155] op_sel_hi:[0,1]
	v_pk_mul_f32 v[156:157], v[196:197], v[156:157] op_sel_hi:[0,1]
	v_pk_mul_f32 v[158:159], v[196:197], v[158:159] op_sel_hi:[0,1]
	v_pk_mul_f32 v[160:161], v[196:197], v[160:161] op_sel_hi:[0,1]
	v_pk_mul_f32 v[146:147], v[64:65], v[146:147]
	v_pk_mul_f32 v[148:149], v[66:67], v[148:149]
	v_pk_mul_f32 v[150:151], v[68:69], v[150:151]
	v_pk_mul_f32 v[152:153], v[70:71], v[152:153]
	v_pk_mul_f32 v[154:155], v[72:73], v[154:155]
	v_pk_mul_f32 v[156:157], v[74:75], v[156:157]
	v_pk_mul_f32 v[158:159], v[76:77], v[158:159]
	v_pk_mul_f32 v[160:161], v[78:79], v[160:161]
	v_pk_fma_f32 v[146:147], v[80:81], v[146:147], v[162:163]
	v_pk_fma_f32 v[148:149], v[82:83], v[148:149], v[164:165]
	v_pk_fma_f32 v[150:151], v[84:85], v[150:151], v[166:167]
	v_pk_fma_f32 v[152:153], v[86:87], v[152:153], v[168:169]
	v_pk_fma_f32 v[154:155], v[88:89], v[154:155], v[170:171]
	v_pk_fma_f32 v[156:157], v[90:91], v[156:157], v[172:173]
	v_pk_fma_f32 v[158:159], v[92:93], v[158:159], v[174:175]
	v_pk_fma_f32 v[160:161], v[94:95], v[160:161], v[176:177]
	v_cvt_pk_bf16_f32 v212, v146, v147
	v_cvt_pk_bf16_f32 v213, v148, v149
	v_cvt_pk_bf16_f32 v214, v150, v151
	v_cvt_pk_bf16_f32 v215, v152, v153
	v_cvt_pk_bf16_f32 v216, v154, v155
	v_cvt_pk_bf16_f32 v217, v156, v157
	v_cvt_pk_bf16_f32 v218, v158, v159
	v_cvt_pk_bf16_f32 v219, v160, v161
	global_store_dwordx2 v203, v[212:213], s[48:49] sc1
	global_store_dwordx2 v203, v[214:215], s[48:49] offset:512 sc1
	global_store_dwordx2 v203, v[216:217], s[48:49] offset:1024 sc1
	global_store_dwordx2 v203, v[218:219], s[48:49] offset:1536 sc1
	s_add_u32 s48, s48, 0x800
	s_addc_u32 s49, s49, 0
	s_nop 1
	s_branch .LBB0_281

.LBB0_281:
	v_readlane_b32 s2, v254, 58
	v_readlane_b32 s3, v254, 59
	s_mov_b64 s[56:57], s[84:85]
	s_andn2_b64 vcc, exec, s[2:3]
	s_mov_b64 s[58:59], s[86:87]
	s_cbranch_vccnz .LBB0_355
	v_readlane_b32 s2, v254, 60
	s_and_b32 s2, 0xffff, s2
	s_cmp_gt_i32 s2, 0
	s_mov_b64 s[12:13], -1
	s_cbranch_scc0 .LBB0_287
	v_readlane_b32 s44, v254, 34
	v_readlane_b32 s48, v254, 38
	s_cmpk_gt_i32 s52, 0x7fff
	v_readlane_b32 s16, v254, 18
	v_readlane_b32 s45, v254, 35
	v_readlane_b32 s49, v254, 39
	s_mov_b64 s[50:51], 0x200
	s_mov_b64 s[82:83], 0x400
	s_mov_b32 s17, s63
	s_mov_b64 s[62:63], 0x600
	s_cbranch_scc1 .LBB0_286
	v_readlane_b32 s2, v250, 0
	s_cmpk_lg_u32 s2, 0x100
	s_cbranch_scc1 .Lnrm_B_fallback
	v_lshrrev_b32_e32 v0, 6, v222
	v_and_b32_e32 v1, 63, v222
	v_readlane_b32 s4, v254, 48
	v_readfirstlane_b32 s3, v0
	v_readlane_b32 s82, v250, 2
	v_readlane_b32 s83, v250, 3
	s_lshl_b32 s4, s4, 3
	s_add_i32 s4, s4, s3
	s_load_dwordx2 s[18:19], s[82:83], 0x20
	s_load_dwordx2 s[12:13], s[82:83], 0x0
	s_lshr_b32 s2, s4, 7
	s_mul_i32 s2, s2, 0x9000
	s_add_u32 s20, s74, s2
	s_addc_u32 s21, s75, 0
	s_add_u32 s88, s20, 0x1000
	s_addc_u32 s89, s21, 0
	s_add_u32 s90, s20, 0x0
	s_addc_u32 s91, s21, 0
	v_lshlrev_b32_e32 v202, 4, v1
	v_lshlrev_b32_e32 v203, 3, v1
	s_lshl_b32 s11, s4, 16
	s_lshl_b32 s2, s4, 15
	s_add_u32 s48, s74, s2
	s_addc_u32 s49, s75, 0
	s_add_u32 s48, s48, 0x3000000
	s_addc_u32 s49, s49, 0
	s_waitcnt lgkmcnt(0)
	s_and_b32 s13, s13, 0xffff
	s_mov_b32 s14, 0x8000000
	s_mov_b32 s15, 0x20000
	global_load_dwordx4 v[64:67], v202, s[18:19]
	global_load_dwordx4 v[68:71], v202, s[18:19] offset:1024
	global_load_dwordx4 v[72:75], v202, s[18:19] offset:2048
	global_load_dwordx4 v[76:79], v202, s[18:19] offset:3072
	global_load_dwordx4 v[80:83], v202, s[88:89]
	global_load_dwordx4 v[84:87], v202, s[88:89] offset:1024
	global_load_dwordx4 v[88:91], v202, s[88:89] offset:2048
	global_load_dwordx4 v[92:95], v202, s[88:89] offset:3072
	global_load_dwordx4 v[162:165], v202, s[90:91]
	global_load_dwordx4 v[166:169], v202, s[90:91] offset:1024
	global_load_dwordx4 v[170:173], v202, s[90:91] offset:2048
	global_load_dwordx4 v[174:177], v202, s[90:91] offset:3072
	buffer_load_dwordx4 v[0:3], v202, s[12:15], s11 offen sc1
	buffer_load_dwordx4 v[4:7], v202, s[12:15], s11 offen offset:1024 sc1
	buffer_load_dwordx4 v[8:11], v202, s[12:15], s11 offen offset:2048 sc1
	buffer_load_dwordx4 v[12:15], v202, s[12:15], s11 offen offset:3072 sc1
	s_add_u32 s11, s11, 0x1000
	buffer_load_dwordx4 v[16:19], v202, s[12:15], s11 offen sc1
	buffer_load_dwordx4 v[20:23], v202, s[12:15], s11 offen offset:1024 sc1
	buffer_load_dwordx4 v[24:27], v202, s[12:15], s11 offen offset:2048 sc1
	buffer_load_dwordx4 v[28:31], v202, s[12:15], s11 offen offset:3072 sc1
	s_add_u32 s11, s11, 0x1000
	buffer_load_dwordx4 v[32:35], v202, s[12:15], s11 offen sc1
	buffer_load_dwordx4 v[36:39], v202, s[12:15], s11 offen offset:1024 sc1
	buffer_load_dwordx4 v[40:43], v202, s[12:15], s11 offen offset:2048 sc1
	buffer_load_dwordx4 v[44:47], v202, s[12:15], s11 offen offset:3072 sc1
	s_add_u32 s11, s11, 0x1000
	buffer_load_dwordx4 v[48:51], v202, s[12:15], s11 offen sc1
	buffer_load_dwordx4 v[52:55], v202, s[12:15], s11 offen offset:1024 sc1
	buffer_load_dwordx4 v[56:59], v202, s[12:15], s11 offen offset:2048 sc1
	buffer_load_dwordx4 v[60:63], v202, s[12:15], s11 offen offset:3072 sc1
	s_add_u32 s11, s11, 0x1000
	buffer_load_dwordx4 v[98:101], v202, s[12:15], s11 offen sc1
	buffer_load_dwordx4 v[102:105], v202, s[12:15], s11 offen offset:1024 sc1
	buffer_load_dwordx4 v[106:109], v202, s[12:15], s11 offen offset:2048 sc1
	buffer_load_dwordx4 v[110:113], v202, s[12:15], s11 offen offset:3072 sc1
	s_add_u32 s11, s11, 0x1000
	buffer_load_dwordx4 v[114:117], v202, s[12:15], s11 offen sc1
	buffer_load_dwordx4 v[118:121], v202, s[12:15], s11 offen offset:1024 sc1
	buffer_load_dwordx4 v[122:125], v202, s[12:15], s11 offen offset:2048 sc1
	buffer_load_dwordx4 v[126:129], v202, s[12:15], s11 offen offset:3072 sc1
	s_add_u32 s11, s11, 0x1000
	buffer_load_dwordx4 v[130:133], v202, s[12:15], s11 offen sc1
	buffer_load_dwordx4 v[134:137], v202, s[12:15], s11 offen offset:1024 sc1
	buffer_load_dwordx4 v[138:141], v202, s[12:15], s11 offen offset:2048 sc1
	buffer_load_dwordx4 v[142:145], v202, s[12:15], s11 offen offset:3072 sc1
	s_add_u32 s11, s11, 0x1000
	buffer_load_dwordx4 v[146:149], v202, s[12:15], s11 offen sc1
	buffer_load_dwordx4 v[150:153], v202, s[12:15], s11 offen offset:1024 sc1
	buffer_load_dwordx4 v[154:157], v202, s[12:15], s11 offen offset:2048 sc1
	buffer_load_dwordx4 v[158:161], v202, s[12:15], s11 offen offset:3072 sc1
	s_add_u32 s11, s11, 0x1000
	s_waitcnt vmcnt(16)
	v_pk_add_f32 v[80:81], v[80:81], 1.0 op_sel_hi:[1,0]
	v_pk_add_f32 v[82:83], v[82:83], 1.0 op_sel_hi:[1,0]
	v_pk_add_f32 v[84:85], v[84:85], 1.0 op_sel_hi:[1,0]
	v_pk_add_f32 v[86:87], v[86:87], 1.0 op_sel_hi:[1,0]
	v_pk_add_f32 v[88:89], v[88:89], 1.0 op_sel_hi:[1,0]
	v_pk_add_f32 v[90:91], v[90:91], 1.0 op_sel_hi:[1,0]
	v_pk_add_f32 v[92:93], v[92:93], 1.0 op_sel_hi:[1,0]
	v_pk_add_f32 v[94:95], v[94:95], 1.0 op_sel_hi:[1,0]
	v_mul_f32_e32 v178, v0, v0
	v_mul_f32_e32 v179, v16, v16
	v_mul_f32_e32 v180, v32, v32
	v_mul_f32_e32 v181, v48, v48
	v_fma_f32 v178, v1, v1, v178
	v_fma_f32 v179, v17, v17, v179
	v_fma_f32 v180, v33, v33, v180
	v_fma_f32 v181, v49, v49, v181
	v_fma_f32 v178, v2, v2, v178
	v_fma_f32 v179, v18, v18, v179
	v_fma_f32 v180, v34, v34, v180
	v_fma_f32 v181, v50, v50, v181
	v_fma_f32 v178, v3, v3, v178
	v_fma_f32 v179, v19, v19, v179
	v_fma_f32 v180, v35, v35, v180
	v_fma_f32 v181, v51, v51, v181
	v_fma_f32 v178, v4, v4, v178
	v_fma_f32 v179, v20, v20, v179
	v_fma_f32 v180, v36, v36, v180
	v_fma_f32 v181, v52, v52, v181
	v_fma_f32 v178, v5, v5, v178
	v_fma_f32 v179, v21, v21, v179
	v_fma_f32 v180, v37, v37, v180
	v_fma_f32 v181, v53, v53, v181
	v_fma_f32 v178, v6, v6, v178
	v_fma_f32 v179, v22, v22, v179
	v_fma_f32 v180, v38, v38, v180
	v_fma_f32 v181, v54, v54, v181
	v_fma_f32 v178, v7, v7, v178
	v_fma_f32 v179, v23, v23, v179
	v_fma_f32 v180, v39, v39, v180
	v_fma_f32 v181, v55, v55, v181
	v_fma_f32 v178, v8, v8, v178
	v_fma_f32 v179, v24, v24, v179
	v_fma_f32 v180, v40, v40, v180
	v_fma_f32 v181, v56, v56, v181
	v_fma_f32 v178, v9, v9, v178
	v_fma_f32 v179, v25, v25, v179
	v_fma_f32 v180, v41, v41, v180
	v_fma_f32 v181, v57, v57, v181
	v_fma_f32 v178, v10, v10, v178
	v_fma_f32 v179, v26, v26, v179
	v_fma_f32 v180, v42, v42, v180
	v_fma_f32 v181, v58, v58, v181
	v_fma_f32 v178, v11, v11, v178
	v_fma_f32 v179, v27, v27, v179
	v_fma_f32 v180, v43, v43, v180
	v_fma_f32 v181, v59, v59, v181
	v_fma_f32 v178, v12, v12, v178
	v_fma_f32 v179, v28, v28, v179
	v_fma_f32 v180, v44, v44, v180
	v_fma_f32 v181, v60, v60, v181
	v_fma_f32 v178, v13, v13, v178
	v_fma_f32 v179, v29, v29, v179
	v_fma_f32 v180, v45, v45, v180
	v_fma_f32 v181, v61, v61, v181
	v_fma_f32 v178, v14, v14, v178
	v_fma_f32 v179, v30, v30, v179
	v_fma_f32 v180, v46, v46, v180
	v_fma_f32 v181, v62, v62, v181
	v_fma_f32 v178, v15, v15, v178
	v_fma_f32 v179, v31, v31, v179
	v_fma_f32 v180, v47, v47, v180
	v_fma_f32 v181, v63, v63, v181
	v_add_f32_dpp v178, v178, v178 quad_perm:[1,0,3,2] row_mask:0xf bank_mask:0xf
	v_add_f32_dpp v179, v179, v179 quad_perm:[1,0,3,2] row_mask:0xf bank_mask:0xf
	v_add_f32_dpp v180, v180, v180 quad_perm:[1,0,3,2] row_mask:0xf bank_mask:0xf
	v_add_f32_dpp v181, v181, v181 quad_perm:[1,0,3,2] row_mask:0xf bank_mask:0xf
	v_add_f32_dpp v178, v178, v178 quad_perm:[2,3,0,1] row_mask:0xf bank_mask:0xf
	v_add_f32_dpp v179, v179, v179 quad_perm:[2,3,0,1] row_mask:0xf bank_mask:0xf
	v_add_f32_dpp v180, v180, v180 quad_perm:[2,3,0,1] row_mask:0xf bank_mask:0xf
	v_add_f32_dpp v181, v181, v181 quad_perm:[2,3,0,1] row_mask:0xf bank_mask:0xf
	v_add_f32_dpp v178, v178, v178 row_half_mirror row_mask:0xf bank_mask:0xf
	v_add_f32_dpp v179, v179, v179 row_half_mirror row_mask:0xf bank_mask:0xf
	v_add_f32_dpp v180, v180, v180 row_half_mirror row_mask:0xf bank_mask:0xf
	v_add_f32_dpp v181, v181, v181 row_half_mirror row_mask:0xf bank_mask:0xf
	v_add_f32_dpp v178, v178, v178 row_ror:8 row_mask:0xf bank_mask:0xf
	v_add_f32_dpp v179, v179, v179 row_ror:8 row_mask:0xf bank_mask:0xf
	v_add_f32_dpp v180, v180, v180 row_ror:8 row_mask:0xf bank_mask:0xf
	v_add_f32_dpp v181, v181, v181 row_ror:8 row_mask:0xf bank_mask:0xf
	v_mov_b32_e32 v182, v178
	v_mov_b32_e32 v183, v179
	v_mov_b32_e32 v184, v180
	v_mov_b32_e32 v185, v181
	v_permlane16_swap_b32_e32 v182, v178
	v_permlane16_swap_b32_e32 v183, v179
	v_permlane16_swap_b32_e32 v184, v180
	v_permlane16_swap_b32_e32 v185, v181
	v_add_f32_e32 v178, v178, v182
	v_add_f32_e32 v179, v179, v183
	v_add_f32_e32 v180, v180, v184
	v_add_f32_e32 v181, v181, v185
	v_mov_b32_e32 v182, v178
	v_mov_b32_e32 v183, v179
	v_mov_b32_e32 v184, v180
	v_mov_b32_e32 v185, v181
	v_permlane32_swap_b32_e32 v182, v178
	v_permlane32_swap_b32_e32 v183, v179
	v_permlane32_swap_b32_e32 v184, v180
	v_permlane32_swap_b32_e32 v185, v181
	v_add_f32_e32 v178, v178, v182
	v_add_f32_e32 v179, v179, v183
	v_add_f32_e32 v180, v180, v184
	v_add_f32_e32 v181, v181, v185
	v_fmamk_f32 v198, v178, 0x3a800000, v225
	v_fmamk_f32 v199, v179, 0x3a800000, v225
	v_fmamk_f32 v200, v180, 0x3a800000, v225
	v_fmamk_f32 v201, v181, 0x3a800000, v225
	v_mul_f32_e32 v182, 0x4b800000, v198
	v_mul_f32_e32 v183, 0x4b800000, v199
	v_mul_f32_e32 v184, 0x4b800000, v200
	v_mul_f32_e32 v185, 0x4b800000, v201
	v_cmp_gt_f32_e64 s[2:3], s30, v198
	v_cmp_gt_f32_e64 s[50:51], s30, v199
	v_cmp_gt_f32_e64 s[88:89], s30, v200
	v_cmp_gt_f32_e64 s[90:91], s30, v201
	v_cndmask_b32_e64 v198, v198, v182, s[2:3]
	v_cndmask_b32_e64 v199, v199, v183, s[50:51]
	v_cndmask_b32_e64 v200, v200, v184, s[88:89]
	v_cndmask_b32_e64 v201, v201, v185, s[90:91]
	v_rsq_f32_e32 v198, v198
	v_rsq_f32_e32 v199, v199
	v_rsq_f32_e32 v200, v200
	v_rsq_f32_e32 v201, v201
	v_mul_f32_e32 v182, 0x45800000, v198
	v_mul_f32_e32 v183, 0x45800000, v199
	v_mul_f32_e32 v184, 0x45800000, v200
	v_mul_f32_e32 v185, 0x45800000, v201
	v_cndmask_b32_e64 v186, v198, v182, s[2:3]
	v_cndmask_b32_e64 v192, v199, v183, s[50:51]
	v_cndmask_b32_e64 v194, v200, v184, s[88:89]
	v_cndmask_b32_e64 v196, v201, v185, s[90:91]
	v_pk_mul_f32 v[0:1], v[186:187], v[0:1] op_sel_hi:[0,1]
	v_pk_mul_f32 v[2:3], v[186:187], v[2:3] op_sel_hi:[0,1]
	v_pk_mul_f32 v[4:5], v[186:187], v[4:5] op_sel_hi:[0,1]
	v_pk_mul_f32 v[6:7], v[186:187], v[6:7] op_sel_hi:[0,1]
	v_pk_mul_f32 v[8:9], v[186:187], v[8:9] op_sel_hi:[0,1]
	v_pk_mul_f32 v[10:11], v[186:187], v[10:11] op_sel_hi:[0,1]
	v_pk_mul_f32 v[12:13], v[186:187], v[12:13] op_sel_hi:[0,1]
	v_pk_mul_f32 v[14:15], v[186:187], v[14:15] op_sel_hi:[0,1]
	v_pk_mul_f32 v[0:1], v[64:65], v[0:1]
	v_pk_mul_f32 v[2:3], v[66:67], v[2:3]
	v_pk_mul_f32 v[4:5], v[68:69], v[4:5]
	v_pk_mul_f32 v[6:7], v[70:71], v[6:7]
	v_pk_mul_f32 v[8:9], v[72:73], v[8:9]
	v_pk_mul_f32 v[10:11], v[74:75], v[10:11]
	v_pk_mul_f32 v[12:13], v[76:77], v[12:13]
	v_pk_mul_f32 v[14:15], v[78:79], v[14:15]
	v_pk_fma_f32 v[0:1], v[80:81], v[0:1], v[162:163]
	v_pk_fma_f32 v[2:3], v[82:83], v[2:3], v[164:165]
	v_pk_fma_f32 v[4:5], v[84:85], v[4:5], v[166:167]
	v_pk_fma_f32 v[6:7], v[86:87], v[6:7], v[168:169]
	v_pk_fma_f32 v[8:9], v[88:89], v[8:9], v[170:171]
	v_pk_fma_f32 v[10:11], v[90:91], v[10:11], v[172:173]
	v_pk_fma_f32 v[12:13], v[92:93], v[12:13], v[174:175]
	v_pk_fma_f32 v[14:15], v[94:95], v[14:15], v[176:177]
	v_cvt_pk_bf16_f32 v204, v0, v1
	v_cvt_pk_bf16_f32 v205, v2, v3
	v_cvt_pk_bf16_f32 v206, v4, v5
	v_cvt_pk_bf16_f32 v207, v6, v7
	v_cvt_pk_bf16_f32 v208, v8, v9
	v_cvt_pk_bf16_f32 v209, v10, v11
	v_cvt_pk_bf16_f32 v210, v12, v13
	v_cvt_pk_bf16_f32 v211, v14, v15
	global_store_dwordx2 v203, v[204:205], s[48:49] sc1
	global_store_dwordx2 v203, v[206:207], s[48:49] offset:512 sc1
	global_store_dwordx2 v203, v[208:209], s[48:49] offset:1024 sc1
	global_store_dwordx2 v203, v[210:211], s[48:49] offset:1536 sc1
	s_add_u32 s48, s48, 0x800
	s_addc_u32 s49, s49, 0
	v_pk_mul_f32 v[16:17], v[192:193], v[16:17] op_sel_hi:[0,1]
	v_pk_mul_f32 v[18:19], v[192:193], v[18:19] op_sel_hi:[0,1]
	v_pk_mul_f32 v[20:21], v[192:193], v[20:21] op_sel_hi:[0,1]
	v_pk_mul_f32 v[22:23], v[192:193], v[22:23] op_sel_hi:[0,1]
	v_pk_mul_f32 v[24:25], v[192:193], v[24:25] op_sel_hi:[0,1]
	v_pk_mul_f32 v[26:27], v[192:193], v[26:27] op_sel_hi:[0,1]
	v_pk_mul_f32 v[28:29], v[192:193], v[28:29] op_sel_hi:[0,1]
	v_pk_mul_f32 v[30:31], v[192:193], v[30:31] op_sel_hi:[0,1]
	v_pk_mul_f32 v[16:17], v[64:65], v[16:17]
	v_pk_mul_f32 v[18:19], v[66:67], v[18:19]
	v_pk_mul_f32 v[20:21], v[68:69], v[20:21]
	v_pk_mul_f32 v[22:23], v[70:71], v[22:23]
	v_pk_mul_f32 v[24:25], v[72:73], v[24:25]
	v_pk_mul_f32 v[26:27], v[74:75], v[26:27]
	v_pk_mul_f32 v[28:29], v[76:77], v[28:29]
	v_pk_mul_f32 v[30:31], v[78:79], v[30:31]
	v_pk_fma_f32 v[16:17], v[80:81], v[16:17], v[162:163]
	v_pk_fma_f32 v[18:19], v[82:83], v[18:19], v[164:165]
	v_pk_fma_f32 v[20:21], v[84:85], v[20:21], v[166:167]
	v_pk_fma_f32 v[22:23], v[86:87], v[22:23], v[168:169]
	v_pk_fma_f32 v[24:25], v[88:89], v[24:25], v[170:171]
	v_pk_fma_f32 v[26:27], v[90:91], v[26:27], v[172:173]
	v_pk_fma_f32 v[28:29], v[92:93], v[28:29], v[174:175]
	v_pk_fma_f32 v[30:31], v[94:95], v[30:31], v[176:177]
	v_cvt_pk_bf16_f32 v212, v16, v17
	v_cvt_pk_bf16_f32 v213, v18, v19
	v_cvt_pk_bf16_f32 v214, v20, v21
	v_cvt_pk_bf16_f32 v215, v22, v23
	v_cvt_pk_bf16_f32 v216, v24, v25
	v_cvt_pk_bf16_f32 v217, v26, v27
	v_cvt_pk_bf16_f32 v218, v28, v29
	v_cvt_pk_bf16_f32 v219, v30, v31
	global_store_dwordx2 v203, v[212:213], s[48:49] sc1
	global_store_dwordx2 v203, v[214:215], s[48:49] offset:512 sc1
	global_store_dwordx2 v203, v[216:217], s[48:49] offset:1024 sc1
	global_store_dwordx2 v203, v[218:219], s[48:49] offset:1536 sc1
	s_add_u32 s48, s48, 0x800
	s_addc_u32 s49, s49, 0
	v_pk_mul_f32 v[32:33], v[194:195], v[32:33] op_sel_hi:[0,1]
	v_pk_mul_f32 v[34:35], v[194:195], v[34:35] op_sel_hi:[0,1]
	v_pk_mul_f32 v[36:37], v[194:195], v[36:37] op_sel_hi:[0,1]
	v_pk_mul_f32 v[38:39], v[194:195], v[38:39] op_sel_hi:[0,1]
	v_pk_mul_f32 v[40:41], v[194:195], v[40:41] op_sel_hi:[0,1]
	v_pk_mul_f32 v[42:43], v[194:195], v[42:43] op_sel_hi:[0,1]
	v_pk_mul_f32 v[44:45], v[194:195], v[44:45] op_sel_hi:[0,1]
	v_pk_mul_f32 v[46:47], v[194:195], v[46:47] op_sel_hi:[0,1]
	v_pk_mul_f32 v[32:33], v[64:65], v[32:33]
	v_pk_mul_f32 v[34:35], v[66:67], v[34:35]
	v_pk_mul_f32 v[36:37], v[68:69], v[36:37]
	v_pk_mul_f32 v[38:39], v[70:71], v[38:39]
	v_pk_mul_f32 v[40:41], v[72:73], v[40:41]
	v_pk_mul_f32 v[42:43], v[74:75], v[42:43]
	v_pk_mul_f32 v[44:45], v[76:77], v[44:45]
	v_pk_mul_f32 v[46:47], v[78:79], v[46:47]
	v_pk_fma_f32 v[32:33], v[80:81], v[32:33], v[162:163]
	v_pk_fma_f32 v[34:35], v[82:83], v[34:35], v[164:165]
	v_pk_fma_f32 v[36:37], v[84:85], v[36:37], v[166:167]
	v_pk_fma_f32 v[38:39], v[86:87], v[38:39], v[168:169]
	v_pk_fma_f32 v[40:41], v[88:89], v[40:41], v[170:171]
	v_pk_fma_f32 v[42:43], v[90:91], v[42:43], v[172:173]
	v_pk_fma_f32 v[44:45], v[92:93], v[44:45], v[174:175]
	v_pk_fma_f32 v[46:47], v[94:95], v[46:47], v[176:177]
	v_cvt_pk_bf16_f32 v204, v32, v33
	v_cvt_pk_bf16_f32 v205, v34, v35
	v_cvt_pk_bf16_f32 v206, v36, v37
	v_cvt_pk_bf16_f32 v207, v38, v39
	v_cvt_pk_bf16_f32 v208, v40, v41
	v_cvt_pk_bf16_f32 v209, v42, v43
	v_cvt_pk_bf16_f32 v210, v44, v45
	v_cvt_pk_bf16_f32 v211, v46, v47
	global_store_dwordx2 v203, v[204:205], s[48:49] sc1
	global_store_dwordx2 v203, v[206:207], s[48:49] offset:512 sc1
	global_store_dwordx2 v203, v[208:209], s[48:49] offset:1024 sc1
	global_store_dwordx2 v203, v[210:211], s[48:49] offset:1536 sc1
	s_add_u32 s48, s48, 0x800
	s_addc_u32 s49, s49, 0
	v_pk_mul_f32 v[48:49], v[196:197], v[48:49] op_sel_hi:[0,1]
	v_pk_mul_f32 v[50:51], v[196:197], v[50:51] op_sel_hi:[0,1]
	v_pk_mul_f32 v[52:53], v[196:197], v[52:53] op_sel_hi:[0,1]
	v_pk_mul_f32 v[54:55], v[196:197], v[54:55] op_sel_hi:[0,1]
	v_pk_mul_f32 v[56:57], v[196:197], v[56:57] op_sel_hi:[0,1]
	v_pk_mul_f32 v[58:59], v[196:197], v[58:59] op_sel_hi:[0,1]
	v_pk_mul_f32 v[60:61], v[196:197], v[60:61] op_sel_hi:[0,1]
	v_pk_mul_f32 v[62:63], v[196:197], v[62:63] op_sel_hi:[0,1]
	v_pk_mul_f32 v[48:49], v[64:65], v[48:49]
	v_pk_mul_f32 v[50:51], v[66:67], v[50:51]
	v_pk_mul_f32 v[52:53], v[68:69], v[52:53]
	v_pk_mul_f32 v[54:55], v[70:71], v[54:55]
	v_pk_mul_f32 v[56:57], v[72:73], v[56:57]
	v_pk_mul_f32 v[58:59], v[74:75], v[58:59]
	v_pk_mul_f32 v[60:61], v[76:77], v[60:61]
	v_pk_mul_f32 v[62:63], v[78:79], v[62:63]
	v_pk_fma_f32 v[48:49], v[80:81], v[48:49], v[162:163]
	v_pk_fma_f32 v[50:51], v[82:83], v[50:51], v[164:165]
	v_pk_fma_f32 v[52:53], v[84:85], v[52:53], v[166:167]
	v_pk_fma_f32 v[54:55], v[86:87], v[54:55], v[168:169]
	v_pk_fma_f32 v[56:57], v[88:89], v[56:57], v[170:171]
	v_pk_fma_f32 v[58:59], v[90:91], v[58:59], v[172:173]
	v_pk_fma_f32 v[60:61], v[92:93], v[60:61], v[174:175]
	v_pk_fma_f32 v[62:63], v[94:95], v[62:63], v[176:177]
	v_cvt_pk_bf16_f32 v212, v48, v49
	v_cvt_pk_bf16_f32 v213, v50, v51
	v_cvt_pk_bf16_f32 v214, v52, v53
	v_cvt_pk_bf16_f32 v215, v54, v55
	v_cvt_pk_bf16_f32 v216, v56, v57
	v_cvt_pk_bf16_f32 v217, v58, v59
	v_cvt_pk_bf16_f32 v218, v60, v61
	v_cvt_pk_bf16_f32 v219, v62, v63
	global_store_dwordx2 v203, v[212:213], s[48:49] sc1
	global_store_dwordx2 v203, v[214:215], s[48:49] offset:512 sc1
	global_store_dwordx2 v203, v[216:217], s[48:49] offset:1024 sc1
	global_store_dwordx2 v203, v[218:219], s[48:49] offset:1536 sc1
	s_add_u32 s48, s48, 0x800
	s_addc_u32 s49, s49, 0
	buffer_load_dwordx4 v[0:3], v202, s[12:15], s11 offen sc1
	buffer_load_dwordx4 v[4:7], v202, s[12:15], s11 offen offset:1024 sc1
	buffer_load_dwordx4 v[8:11], v202, s[12:15], s11 offen offset:2048 sc1
	buffer_load_dwordx4 v[12:15], v202, s[12:15], s11 offen offset:3072 sc1
	s_add_u32 s11, s11, 0x1000
	buffer_load_dwordx4 v[16:19], v202, s[12:15], s11 offen sc1
	buffer_load_dwordx4 v[20:23], v202, s[12:15], s11 offen offset:1024 sc1
	buffer_load_dwordx4 v[24:27], v202, s[12:15], s11 offen offset:2048 sc1
	buffer_load_dwordx4 v[28:31], v202, s[12:15], s11 offen offset:3072 sc1
	s_add_u32 s11, s11, 0x1000
	buffer_load_dwordx4 v[32:35], v202, s[12:15], s11 offen sc1
	buffer_load_dwordx4 v[36:39], v202, s[12:15], s11 offen offset:1024 sc1
	buffer_load_dwordx4 v[40:43], v202, s[12:15], s11 offen offset:2048 sc1
	buffer_load_dwordx4 v[44:47], v202, s[12:15], s11 offen offset:3072 sc1
	s_add_u32 s11, s11, 0x1000
	buffer_load_dwordx4 v[48:51], v202, s[12:15], s11 offen sc1
	buffer_load_dwordx4 v[52:55], v202, s[12:15], s11 offen offset:1024 sc1
	buffer_load_dwordx4 v[56:59], v202, s[12:15], s11 offen offset:2048 sc1
	buffer_load_dwordx4 v[60:63], v202, s[12:15], s11 offen offset:3072 sc1
	s_add_u32 s11, s11, 0x1000
	s_waitcnt vmcnt(24)
	v_mul_f32_e32 v178, v98, v98
	v_mul_f32_e32 v179, v114, v114
	v_mul_f32_e32 v180, v130, v130
	v_mul_f32_e32 v181, v146, v146
	v_fma_f32 v178, v99, v99, v178
	v_fma_f32 v179, v115, v115, v179
	v_fma_f32 v180, v131, v131, v180
	v_fma_f32 v181, v147, v147, v181
	v_fma_f32 v178, v100, v100, v178
	v_fma_f32 v179, v116, v116, v179
	v_fma_f32 v180, v132, v132, v180
	v_fma_f32 v181, v148, v148, v181
	v_fma_f32 v178, v101, v101, v178
	v_fma_f32 v179, v117, v117, v179
	v_fma_f32 v180, v133, v133, v180
	v_fma_f32 v181, v149, v149, v181
	v_fma_f32 v178, v102, v102, v178
	v_fma_f32 v179, v118, v118, v179
	v_fma_f32 v180, v134, v134, v180
	v_fma_f32 v181, v150, v150, v181
	v_fma_f32 v178, v103, v103, v178
	v_fma_f32 v179, v119, v119, v179
	v_fma_f32 v180, v135, v135, v180
	v_fma_f32 v181, v151, v151, v181
	v_fma_f32 v178, v104, v104, v178
	v_fma_f32 v179, v120, v120, v179
	v_fma_f32 v180, v136, v136, v180
	v_fma_f32 v181, v152, v152, v181
	v_fma_f32 v178, v105, v105, v178
	v_fma_f32 v179, v121, v121, v179
	v_fma_f32 v180, v137, v137, v180
	v_fma_f32 v181, v153, v153, v181
	v_fma_f32 v178, v106, v106, v178
	v_fma_f32 v179, v122, v122, v179
	v_fma_f32 v180, v138, v138, v180
	v_fma_f32 v181, v154, v154, v181
	v_fma_f32 v178, v107, v107, v178
	v_fma_f32 v179, v123, v123, v179
	v_fma_f32 v180, v139, v139, v180
	v_fma_f32 v181, v155, v155, v181
	v_fma_f32 v178, v108, v108, v178
	v_fma_f32 v179, v124, v124, v179
	v_fma_f32 v180, v140, v140, v180
	v_fma_f32 v181, v156, v156, v181
	v_fma_f32 v178, v109, v109, v178
	v_fma_f32 v179, v125, v125, v179
	v_fma_f32 v180, v141, v141, v180
	v_fma_f32 v181, v157, v157, v181
	v_fma_f32 v178, v110, v110, v178
	v_fma_f32 v179, v126, v126, v179
	v_fma_f32 v180, v142, v142, v180
	v_fma_f32 v181, v158, v158, v181
	v_fma_f32 v178, v111, v111, v178
	v_fma_f32 v179, v127, v127, v179
	v_fma_f32 v180, v143, v143, v180
	v_fma_f32 v181, v159, v159, v181
	v_fma_f32 v178, v112, v112, v178
	v_fma_f32 v179, v128, v128, v179
	v_fma_f32 v180, v144, v144, v180
	v_fma_f32 v181, v160, v160, v181
	v_fma_f32 v178, v113, v113, v178
	v_fma_f32 v179, v129, v129, v179
	v_fma_f32 v180, v145, v145, v180
	v_fma_f32 v181, v161, v161, v181
	v_add_f32_dpp v178, v178, v178 quad_perm:[1,0,3,2] row_mask:0xf bank_mask:0xf
	v_add_f32_dpp v179, v179, v179 quad_perm:[1,0,3,2] row_mask:0xf bank_mask:0xf
	v_add_f32_dpp v180, v180, v180 quad_perm:[1,0,3,2] row_mask:0xf bank_mask:0xf
	v_add_f32_dpp v181, v181, v181 quad_perm:[1,0,3,2] row_mask:0xf bank_mask:0xf
	v_add_f32_dpp v178, v178, v178 quad_perm:[2,3,0,1] row_mask:0xf bank_mask:0xf
	v_add_f32_dpp v179, v179, v179 quad_perm:[2,3,0,1] row_mask:0xf bank_mask:0xf
	v_add_f32_dpp v180, v180, v180 quad_perm:[2,3,0,1] row_mask:0xf bank_mask:0xf
	v_add_f32_dpp v181, v181, v181 quad_perm:[2,3,0,1] row_mask:0xf bank_mask:0xf
	v_add_f32_dpp v178, v178, v178 row_half_mirror row_mask:0xf bank_mask:0xf
	v_add_f32_dpp v179, v179, v179 row_half_mirror row_mask:0xf bank_mask:0xf
	v_add_f32_dpp v180, v180, v180 row_half_mirror row_mask:0xf bank_mask:0xf
	v_add_f32_dpp v181, v181, v181 row_half_mirror row_mask:0xf bank_mask:0xf
	v_add_f32_dpp v178, v178, v178 row_ror:8 row_mask:0xf bank_mask:0xf
	v_add_f32_dpp v179, v179, v179 row_ror:8 row_mask:0xf bank_mask:0xf
	v_add_f32_dpp v180, v180, v180 row_ror:8 row_mask:0xf bank_mask:0xf
	v_add_f32_dpp v181, v181, v181 row_ror:8 row_mask:0xf bank_mask:0xf
	v_mov_b32_e32 v182, v178
	v_mov_b32_e32 v183, v179
	v_mov_b32_e32 v184, v180
	v_mov_b32_e32 v185, v181
	v_permlane16_swap_b32_e32 v182, v178
	v_permlane16_swap_b32_e32 v183, v179
	v_permlane16_swap_b32_e32 v184, v180
	v_permlane16_swap_b32_e32 v185, v181
	v_add_f32_e32 v178, v178, v182
	v_add_f32_e32 v179, v179, v183
	v_add_f32_e32 v180, v180, v184
	v_add_f32_e32 v181, v181, v185
	v_mov_b32_e32 v182, v178
	v_mov_b32_e32 v183, v179
	v_mov_b32_e32 v184, v180
	v_mov_b32_e32 v185, v181
	v_permlane32_swap_b32_e32 v182, v178
	v_permlane32_swap_b32_e32 v183, v179
	v_permlane32_swap_b32_e32 v184, v180
	v_permlane32_swap_b32_e32 v185, v181
	v_add_f32_e32 v178, v178, v182
	v_add_f32_e32 v179, v179, v183
	v_add_f32_e32 v180, v180, v184
	v_add_f32_e32 v181, v181, v185
	v_fmamk_f32 v198, v178, 0x3a800000, v225
	v_fmamk_f32 v199, v179, 0x3a800000, v225
	v_fmamk_f32 v200, v180, 0x3a800000, v225
	v_fmamk_f32 v201, v181, 0x3a800000, v225
	v_mul_f32_e32 v182, 0x4b800000, v198
	v_mul_f32_e32 v183, 0x4b800000, v199
	v_mul_f32_e32 v184, 0x4b800000, v200
	v_mul_f32_e32 v185, 0x4b800000, v201
	v_cmp_gt_f32_e64 s[2:3], s30, v198
	v_cmp_gt_f32_e64 s[50:51], s30, v199
	v_cmp_gt_f32_e64 s[88:89], s30, v200
	v_cmp_gt_f32_e64 s[90:91], s30, v201
	v_cndmask_b32_e64 v198, v198, v182, s[2:3]
	v_cndmask_b32_e64 v199, v199, v183, s[50:51]
	v_cndmask_b32_e64 v200, v200, v184, s[88:89]
	v_cndmask_b32_e64 v201, v201, v185, s[90:91]
	v_rsq_f32_e32 v198, v198
	v_rsq_f32_e32 v199, v199
	v_rsq_f32_e32 v200, v200
	v_rsq_f32_e32 v201, v201
	v_mul_f32_e32 v182, 0x45800000, v198
	v_mul_f32_e32 v183, 0x45800000, v199
	v_mul_f32_e32 v184, 0x45800000, v200
	v_mul_f32_e32 v185, 0x45800000, v201
	v_cndmask_b32_e64 v186, v198, v182, s[2:3]
	v_cndmask_b32_e64 v192, v199, v183, s[50:51]
	v_cndmask_b32_e64 v194, v200, v184, s[88:89]
	v_cndmask_b32_e64 v196, v201, v185, s[90:91]
	v_pk_mul_f32 v[98:99], v[186:187], v[98:99] op_sel_hi:[0,1]
	v_pk_mul_f32 v[100:101], v[186:187], v[100:101] op_sel_hi:[0,1]
	v_pk_mul_f32 v[102:103], v[186:187], v[102:103] op_sel_hi:[0,1]
	v_pk_mul_f32 v[104:105], v[186:187], v[104:105] op_sel_hi:[0,1]
	v_pk_mul_f32 v[106:107], v[186:187], v[106:107] op_sel_hi:[0,1]
	v_pk_mul_f32 v[108:109], v[186:187], v[108:109] op_sel_hi:[0,1]
	v_pk_mul_f32 v[110:111], v[186:187], v[110:111] op_sel_hi:[0,1]
	v_pk_mul_f32 v[112:113], v[186:187], v[112:113] op_sel_hi:[0,1]
	v_pk_mul_f32 v[98:99], v[64:65], v[98:99]
	v_pk_mul_f32 v[100:101], v[66:67], v[100:101]
	v_pk_mul_f32 v[102:103], v[68:69], v[102:103]
	v_pk_mul_f32 v[104:105], v[70:71], v[104:105]
	v_pk_mul_f32 v[106:107], v[72:73], v[106:107]
	v_pk_mul_f32 v[108:109], v[74:75], v[108:109]
	v_pk_mul_f32 v[110:111], v[76:77], v[110:111]
	v_pk_mul_f32 v[112:113], v[78:79], v[112:113]
	v_pk_fma_f32 v[98:99], v[80:81], v[98:99], v[162:163]
	v_pk_fma_f32 v[100:101], v[82:83], v[100:101], v[164:165]
	v_pk_fma_f32 v[102:103], v[84:85], v[102:103], v[166:167]
	v_pk_fma_f32 v[104:105], v[86:87], v[104:105], v[168:169]
	v_pk_fma_f32 v[106:107], v[88:89], v[106:107], v[170:171]
	v_pk_fma_f32 v[108:109], v[90:91], v[108:109], v[172:173]
	v_pk_fma_f32 v[110:111], v[92:93], v[110:111], v[174:175]
	v_pk_fma_f32 v[112:113], v[94:95], v[112:113], v[176:177]
	v_cvt_pk_bf16_f32 v204, v98, v99
	v_cvt_pk_bf16_f32 v205, v100, v101
	v_cvt_pk_bf16_f32 v206, v102, v103
	v_cvt_pk_bf16_f32 v207, v104, v105
	v_cvt_pk_bf16_f32 v208, v106, v107
	v_cvt_pk_bf16_f32 v209, v108, v109
	v_cvt_pk_bf16_f32 v210, v110, v111
	v_cvt_pk_bf16_f32 v211, v112, v113
	global_store_dwordx2 v203, v[204:205], s[48:49] sc1
	global_store_dwordx2 v203, v[206:207], s[48:49] offset:512 sc1
	global_store_dwordx2 v203, v[208:209], s[48:49] offset:1024 sc1
	global_store_dwordx2 v203, v[210:211], s[48:49] offset:1536 sc1
	s_add_u32 s48, s48, 0x800
	s_addc_u32 s49, s49, 0
	v_pk_mul_f32 v[114:115], v[192:193], v[114:115] op_sel_hi:[0,1]
	v_pk_mul_f32 v[116:117], v[192:193], v[116:117] op_sel_hi:[0,1]
	v_pk_mul_f32 v[118:119], v[192:193], v[118:119] op_sel_hi:[0,1]
	v_pk_mul_f32 v[120:121], v[192:193], v[120:121] op_sel_hi:[0,1]
	v_pk_mul_f32 v[122:123], v[192:193], v[122:123] op_sel_hi:[0,1]
	v_pk_mul_f32 v[124:125], v[192:193], v[124:125] op_sel_hi:[0,1]
	v_pk_mul_f32 v[126:127], v[192:193], v[126:127] op_sel_hi:[0,1]
	v_pk_mul_f32 v[128:129], v[192:193], v[128:129] op_sel_hi:[0,1]
	v_pk_mul_f32 v[114:115], v[64:65], v[114:115]
	v_pk_mul_f32 v[116:117], v[66:67], v[116:117]
	v_pk_mul_f32 v[118:119], v[68:69], v[118:119]
	v_pk_mul_f32 v[120:121], v[70:71], v[120:121]
	v_pk_mul_f32 v[122:123], v[72:73], v[122:123]
	v_pk_mul_f32 v[124:125], v[74:75], v[124:125]
	v_pk_mul_f32 v[126:127], v[76:77], v[126:127]
	v_pk_mul_f32 v[128:129], v[78:79], v[128:129]
	v_pk_fma_f32 v[114:115], v[80:81], v[114:115], v[162:163]
	v_pk_fma_f32 v[116:117], v[82:83], v[116:117], v[164:165]
	v_pk_fma_f32 v[118:119], v[84:85], v[118:119], v[166:167]
	v_pk_fma_f32 v[120:121], v[86:87], v[120:121], v[168:169]
	v_pk_fma_f32 v[122:123], v[88:89], v[122:123], v[170:171]
	v_pk_fma_f32 v[124:125], v[90:91], v[124:125], v[172:173]
	v_pk_fma_f32 v[126:127], v[92:93], v[126:127], v[174:175]
	v_pk_fma_f32 v[128:129], v[94:95], v[128:129], v[176:177]
	v_cvt_pk_bf16_f32 v212, v114, v115
	v_cvt_pk_bf16_f32 v213, v116, v117
	v_cvt_pk_bf16_f32 v214, v118, v119
	v_cvt_pk_bf16_f32 v215, v120, v121
	v_cvt_pk_bf16_f32 v216, v122, v123
	v_cvt_pk_bf16_f32 v217, v124, v125
	v_cvt_pk_bf16_f32 v218, v126, v127
	v_cvt_pk_bf16_f32 v219, v128, v129
	global_store_dwordx2 v203, v[212:213], s[48:49] sc1
	global_store_dwordx2 v203, v[214:215], s[48:49] offset:512 sc1
	global_store_dwordx2 v203, v[216:217], s[48:49] offset:1024 sc1
	global_store_dwordx2 v203, v[218:219], s[48:49] offset:1536 sc1
	s_add_u32 s48, s48, 0x800
	s_addc_u32 s49, s49, 0
	v_pk_mul_f32 v[130:131], v[194:195], v[130:131] op_sel_hi:[0,1]
	v_pk_mul_f32 v[132:133], v[194:195], v[132:133] op_sel_hi:[0,1]
	v_pk_mul_f32 v[134:135], v[194:195], v[134:135] op_sel_hi:[0,1]
	v_pk_mul_f32 v[136:137], v[194:195], v[136:137] op_sel_hi:[0,1]
	v_pk_mul_f32 v[138:139], v[194:195], v[138:139] op_sel_hi:[0,1]
	v_pk_mul_f32 v[140:141], v[194:195], v[140:141] op_sel_hi:[0,1]
	v_pk_mul_f32 v[142:143], v[194:195], v[142:143] op_sel_hi:[0,1]
	v_pk_mul_f32 v[144:145], v[194:195], v[144:145] op_sel_hi:[0,1]
	v_pk_mul_f32 v[130:131], v[64:65], v[130:131]
	v_pk_mul_f32 v[132:133], v[66:67], v[132:133]
	v_pk_mul_f32 v[134:135], v[68:69], v[134:135]
	v_pk_mul_f32 v[136:137], v[70:71], v[136:137]
	v_pk_mul_f32 v[138:139], v[72:73], v[138:139]
	v_pk_mul_f32 v[140:141], v[74:75], v[140:141]
	v_pk_mul_f32 v[142:143], v[76:77], v[142:143]
	v_pk_mul_f32 v[144:145], v[78:79], v[144:145]
	v_pk_fma_f32 v[130:131], v[80:81], v[130:131], v[162:163]
	v_pk_fma_f32 v[132:133], v[82:83], v[132:133], v[164:165]
	v_pk_fma_f32 v[134:135], v[84:85], v[134:135], v[166:167]
	v_pk_fma_f32 v[136:137], v[86:87], v[136:137], v[168:169]
	v_pk_fma_f32 v[138:139], v[88:89], v[138:139], v[170:171]
	v_pk_fma_f32 v[140:141], v[90:91], v[140:141], v[172:173]
	v_pk_fma_f32 v[142:143], v[92:93], v[142:143], v[174:175]
	v_pk_fma_f32 v[144:145], v[94:95], v[144:145], v[176:177]
	v_cvt_pk_bf16_f32 v204, v130, v131
	v_cvt_pk_bf16_f32 v205, v132, v133
	v_cvt_pk_bf16_f32 v206, v134, v135
	v_cvt_pk_bf16_f32 v207, v136, v137
	v_cvt_pk_bf16_f32 v208, v138, v139
	v_cvt_pk_bf16_f32 v209, v140, v141
	v_cvt_pk_bf16_f32 v210, v142, v143
	v_cvt_pk_bf16_f32 v211, v144, v145
	global_store_dwordx2 v203, v[204:205], s[48:49] sc1
	global_store_dwordx2 v203, v[206:207], s[48:49] offset:512 sc1
	global_store_dwordx2 v203, v[208:209], s[48:49] offset:1024 sc1
	global_store_dwordx2 v203, v[210:211], s[48:49] offset:1536 sc1
	s_add_u32 s48, s48, 0x800
	s_addc_u32 s49, s49, 0
	v_pk_mul_f32 v[146:147], v[196:197], v[146:147] op_sel_hi:[0,1]
	v_pk_mul_f32 v[148:149], v[196:197], v[148:149] op_sel_hi:[0,1]
	v_pk_mul_f32 v[150:151], v[196:197], v[150:151] op_sel_hi:[0,1]
	v_pk_mul_f32 v[152:153], v[196:197], v[152:153] op_sel_hi:[0,1]
	v_pk_mul_f32 v[154:155], v[196:197], v[154:155] op_sel_hi:[0,1]
	v_pk_mul_f32 v[156:157], v[196:197], v[156:157] op_sel_hi:[0,1]
	v_pk_mul_f32 v[158:159], v[196:197], v[158:159] op_sel_hi:[0,1]
	v_pk_mul_f32 v[160:161], v[196:197], v[160:161] op_sel_hi:[0,1]
	v_pk_mul_f32 v[146:147], v[64:65], v[146:147]
	v_pk_mul_f32 v[148:149], v[66:67], v[148:149]
	v_pk_mul_f32 v[150:151], v[68:69], v[150:151]
	v_pk_mul_f32 v[152:153], v[70:71], v[152:153]
	v_pk_mul_f32 v[154:155], v[72:73], v[154:155]
	v_pk_mul_f32 v[156:157], v[74:75], v[156:157]
	v_pk_mul_f32 v[158:159], v[76:77], v[158:159]
	v_pk_mul_f32 v[160:161], v[78:79], v[160:161]
	v_pk_fma_f32 v[146:147], v[80:81], v[146:147], v[162:163]
	v_pk_fma_f32 v[148:149], v[82:83], v[148:149], v[164:165]
	v_pk_fma_f32 v[150:151], v[84:85], v[150:151], v[166:167]
	v_pk_fma_f32 v[152:153], v[86:87], v[152:153], v[168:169]
	v_pk_fma_f32 v[154:155], v[88:89], v[154:155], v[170:171]
	v_pk_fma_f32 v[156:157], v[90:91], v[156:157], v[172:173]
	v_pk_fma_f32 v[158:159], v[92:93], v[158:159], v[174:175]
	v_pk_fma_f32 v[160:161], v[94:95], v[160:161], v[176:177]
	v_cvt_pk_bf16_f32 v212, v146, v147
	v_cvt_pk_bf16_f32 v213, v148, v149
	v_cvt_pk_bf16_f32 v214, v150, v151
	v_cvt_pk_bf16_f32 v215, v152, v153
	v_cvt_pk_bf16_f32 v216, v154, v155
	v_cvt_pk_bf16_f32 v217, v156, v157
	v_cvt_pk_bf16_f32 v218, v158, v159
	v_cvt_pk_bf16_f32 v219, v160, v161
	global_store_dwordx2 v203, v[212:213], s[48:49] sc1
	global_store_dwordx2 v203, v[214:215], s[48:49] offset:512 sc1
	global_store_dwordx2 v203, v[216:217], s[48:49] offset:1024 sc1
	global_store_dwordx2 v203, v[218:219], s[48:49] offset:1536 sc1
	s_add_u32 s48, s48, 0x800
	s_addc_u32 s49, s49, 0
	buffer_load_dwordx4 v[98:101], v202, s[12:15], s11 offen sc1
	buffer_load_dwordx4 v[102:105], v202, s[12:15], s11 offen offset:1024 sc1
	buffer_load_dwordx4 v[106:109], v202, s[12:15], s11 offen offset:2048 sc1
	buffer_load_dwordx4 v[110:113], v202, s[12:15], s11 offen offset:3072 sc1
	s_add_u32 s11, s11, 0x1000
	buffer_load_dwordx4 v[114:117], v202, s[12:15], s11 offen sc1
	buffer_load_dwordx4 v[118:121], v202, s[12:15], s11 offen offset:1024 sc1
	buffer_load_dwordx4 v[122:125], v202, s[12:15], s11 offen offset:2048 sc1
	buffer_load_dwordx4 v[126:129], v202, s[12:15], s11 offen offset:3072 sc1
	s_add_u32 s11, s11, 0x1000
	buffer_load_dwordx4 v[130:133], v202, s[12:15], s11 offen sc1
	buffer_load_dwordx4 v[134:137], v202, s[12:15], s11 offen offset:1024 sc1
	buffer_load_dwordx4 v[138:141], v202, s[12:15], s11 offen offset:2048 sc1
	buffer_load_dwordx4 v[142:145], v202, s[12:15], s11 offen offset:3072 sc1
	s_add_u32 s11, s11, 0x1000
	buffer_load_dwordx4 v[146:149], v202, s[12:15], s11 offen sc1
	buffer_load_dwordx4 v[150:153], v202, s[12:15], s11 offen offset:1024 sc1
	buffer_load_dwordx4 v[154:157], v202, s[12:15], s11 offen offset:2048 sc1
	buffer_load_dwordx4 v[158:161], v202, s[12:15], s11 offen offset:3072 sc1
	s_add_u32 s11, s11, 0x1000
	s_waitcnt vmcnt(24)
	v_mul_f32_e32 v178, v0, v0
	v_mul_f32_e32 v179, v16, v16
	v_mul_f32_e32 v180, v32, v32
	v_mul_f32_e32 v181, v48, v48
	v_fma_f32 v178, v1, v1, v178
	v_fma_f32 v179, v17, v17, v179
	v_fma_f32 v180, v33, v33, v180
	v_fma_f32 v181, v49, v49, v181
	v_fma_f32 v178, v2, v2, v178
	v_fma_f32 v179, v18, v18, v179
	v_fma_f32 v180, v34, v34, v180
	v_fma_f32 v181, v50, v50, v181
	v_fma_f32 v178, v3, v3, v178
	v_fma_f32 v179, v19, v19, v179
	v_fma_f32 v180, v35, v35, v180
	v_fma_f32 v181, v51, v51, v181
	v_fma_f32 v178, v4, v4, v178
	v_fma_f32 v179, v20, v20, v179
	v_fma_f32 v180, v36, v36, v180
	v_fma_f32 v181, v52, v52, v181
	v_fma_f32 v178, v5, v5, v178
	v_fma_f32 v179, v21, v21, v179
	v_fma_f32 v180, v37, v37, v180
	v_fma_f32 v181, v53, v53, v181
	v_fma_f32 v178, v6, v6, v178
	v_fma_f32 v179, v22, v22, v179
	v_fma_f32 v180, v38, v38, v180
	v_fma_f32 v181, v54, v54, v181
	v_fma_f32 v178, v7, v7, v178
	v_fma_f32 v179, v23, v23, v179
	v_fma_f32 v180, v39, v39, v180
	v_fma_f32 v181, v55, v55, v181
	v_fma_f32 v178, v8, v8, v178
	v_fma_f32 v179, v24, v24, v179
	v_fma_f32 v180, v40, v40, v180
	v_fma_f32 v181, v56, v56, v181
	v_fma_f32 v178, v9, v9, v178
	v_fma_f32 v179, v25, v25, v179
	v_fma_f32 v180, v41, v41, v180
	v_fma_f32 v181, v57, v57, v181
	v_fma_f32 v178, v10, v10, v178
	v_fma_f32 v179, v26, v26, v179
	v_fma_f32 v180, v42, v42, v180
	v_fma_f32 v181, v58, v58, v181
	v_fma_f32 v178, v11, v11, v178
	v_fma_f32 v179, v27, v27, v179
	v_fma_f32 v180, v43, v43, v180
	v_fma_f32 v181, v59, v59, v181
	v_fma_f32 v178, v12, v12, v178
	v_fma_f32 v179, v28, v28, v179
	v_fma_f32 v180, v44, v44, v180
	v_fma_f32 v181, v60, v60, v181
	v_fma_f32 v178, v13, v13, v178
	v_fma_f32 v179, v29, v29, v179
	v_fma_f32 v180, v45, v45, v180
	v_fma_f32 v181, v61, v61, v181
	v_fma_f32 v178, v14, v14, v178
	v_fma_f32 v179, v30, v30, v179
	v_fma_f32 v180, v46, v46, v180
	v_fma_f32 v181, v62, v62, v181
	v_fma_f32 v178, v15, v15, v178
	v_fma_f32 v179, v31, v31, v179
	v_fma_f32 v180, v47, v47, v180
	v_fma_f32 v181, v63, v63, v181
	v_add_f32_dpp v178, v178, v178 quad_perm:[1,0,3,2] row_mask:0xf bank_mask:0xf
	v_add_f32_dpp v179, v179, v179 quad_perm:[1,0,3,2] row_mask:0xf bank_mask:0xf
	v_add_f32_dpp v180, v180, v180 quad_perm:[1,0,3,2] row_mask:0xf bank_mask:0xf
	v_add_f32_dpp v181, v181, v181 quad_perm:[1,0,3,2] row_mask:0xf bank_mask:0xf
	v_add_f32_dpp v178, v178, v178 quad_perm:[2,3,0,1] row_mask:0xf bank_mask:0xf
	v_add_f32_dpp v179, v179, v179 quad_perm:[2,3,0,1] row_mask:0xf bank_mask:0xf
	v_add_f32_dpp v180, v180, v180 quad_perm:[2,3,0,1] row_mask:0xf bank_mask:0xf
	v_add_f32_dpp v181, v181, v181 quad_perm:[2,3,0,1] row_mask:0xf bank_mask:0xf
	v_add_f32_dpp v178, v178, v178 row_half_mirror row_mask:0xf bank_mask:0xf
	v_add_f32_dpp v179, v179, v179 row_half_mirror row_mask:0xf bank_mask:0xf
	v_add_f32_dpp v180, v180, v180 row_half_mirror row_mask:0xf bank_mask:0xf
	v_add_f32_dpp v181, v181, v181 row_half_mirror row_mask:0xf bank_mask:0xf
	v_add_f32_dpp v178, v178, v178 row_ror:8 row_mask:0xf bank_mask:0xf
	v_add_f32_dpp v179, v179, v179 row_ror:8 row_mask:0xf bank_mask:0xf
	v_add_f32_dpp v180, v180, v180 row_ror:8 row_mask:0xf bank_mask:0xf
	v_add_f32_dpp v181, v181, v181 row_ror:8 row_mask:0xf bank_mask:0xf
	v_mov_b32_e32 v182, v178
	v_mov_b32_e32 v183, v179
	v_mov_b32_e32 v184, v180
	v_mov_b32_e32 v185, v181
	v_permlane16_swap_b32_e32 v182, v178
	v_permlane16_swap_b32_e32 v183, v179
	v_permlane16_swap_b32_e32 v184, v180
	v_permlane16_swap_b32_e32 v185, v181
	v_add_f32_e32 v178, v178, v182
	v_add_f32_e32 v179, v179, v183
	v_add_f32_e32 v180, v180, v184
	v_add_f32_e32 v181, v181, v185
	v_mov_b32_e32 v182, v178
	v_mov_b32_e32 v183, v179
	v_mov_b32_e32 v184, v180
	v_mov_b32_e32 v185, v181
	v_permlane32_swap_b32_e32 v182, v178
	v_permlane32_swap_b32_e32 v183, v179
	v_permlane32_swap_b32_e32 v184, v180
	v_permlane32_swap_b32_e32 v185, v181
	v_add_f32_e32 v178, v178, v182
	v_add_f32_e32 v179, v179, v183
	v_add_f32_e32 v180, v180, v184
	v_add_f32_e32 v181, v181, v185
	v_fmamk_f32 v198, v178, 0x3a800000, v225
	v_fmamk_f32 v199, v179, 0x3a800000, v225
	v_fmamk_f32 v200, v180, 0x3a800000, v225
	v_fmamk_f32 v201, v181, 0x3a800000, v225
	v_mul_f32_e32 v182, 0x4b800000, v198
	v_mul_f32_e32 v183, 0x4b800000, v199
	v_mul_f32_e32 v184, 0x4b800000, v200
	v_mul_f32_e32 v185, 0x4b800000, v201
	v_cmp_gt_f32_e64 s[2:3], s30, v198
	v_cmp_gt_f32_e64 s[50:51], s30, v199
	v_cmp_gt_f32_e64 s[88:89], s30, v200
	v_cmp_gt_f32_e64 s[90:91], s30, v201
	v_cndmask_b32_e64 v198, v198, v182, s[2:3]
	v_cndmask_b32_e64 v199, v199, v183, s[50:51]
	v_cndmask_b32_e64 v200, v200, v184, s[88:89]
	v_cndmask_b32_e64 v201, v201, v185, s[90:91]
	v_rsq_f32_e32 v198, v198
	v_rsq_f32_e32 v199, v199
	v_rsq_f32_e32 v200, v200
	v_rsq_f32_e32 v201, v201
	v_mul_f32_e32 v182, 0x45800000, v198
	v_mul_f32_e32 v183, 0x45800000, v199
	v_mul_f32_e32 v184, 0x45800000, v200
	v_mul_f32_e32 v185, 0x45800000, v201
	v_cndmask_b32_e64 v186, v198, v182, s[2:3]
	v_cndmask_b32_e64 v192, v199, v183, s[50:51]
	v_cndmask_b32_e64 v194, v200, v184, s[88:89]
	v_cndmask_b32_e64 v196, v201, v185, s[90:91]
	v_pk_mul_f32 v[0:1], v[186:187], v[0:1] op_sel_hi:[0,1]
	v_pk_mul_f32 v[2:3], v[186:187], v[2:3] op_sel_hi:[0,1]
	v_pk_mul_f32 v[4:5], v[186:187], v[4:5] op_sel_hi:[0,1]
	v_pk_mul_f32 v[6:7], v[186:187], v[6:7] op_sel_hi:[0,1]
	v_pk_mul_f32 v[8:9], v[186:187], v[8:9] op_sel_hi:[0,1]
	v_pk_mul_f32 v[10:11], v[186:187], v[10:11] op_sel_hi:[0,1]
	v_pk_mul_f32 v[12:13], v[186:187], v[12:13] op_sel_hi:[0,1]
	v_pk_mul_f32 v[14:15], v[186:187], v[14:15] op_sel_hi:[0,1]
	v_pk_mul_f32 v[0:1], v[64:65], v[0:1]
	v_pk_mul_f32 v[2:3], v[66:67], v[2:3]
	v_pk_mul_f32 v[4:5], v[68:69], v[4:5]
	v_pk_mul_f32 v[6:7], v[70:71], v[6:7]
	v_pk_mul_f32 v[8:9], v[72:73], v[8:9]
	v_pk_mul_f32 v[10:11], v[74:75], v[10:11]
	v_pk_mul_f32 v[12:13], v[76:77], v[12:13]
	v_pk_mul_f32 v[14:15], v[78:79], v[14:15]
	v_pk_fma_f32 v[0:1], v[80:81], v[0:1], v[162:163]
	v_pk_fma_f32 v[2:3], v[82:83], v[2:3], v[164:165]
	v_pk_fma_f32 v[4:5], v[84:85], v[4:5], v[166:167]
	v_pk_fma_f32 v[6:7], v[86:87], v[6:7], v[168:169]
	v_pk_fma_f32 v[8:9], v[88:89], v[8:9], v[170:171]
	v_pk_fma_f32 v[10:11], v[90:91], v[10:11], v[172:173]
	v_pk_fma_f32 v[12:13], v[92:93], v[12:13], v[174:175]
	v_pk_fma_f32 v[14:15], v[94:95], v[14:15], v[176:177]
	v_cvt_pk_bf16_f32 v204, v0, v1
	v_cvt_pk_bf16_f32 v205, v2, v3
	v_cvt_pk_bf16_f32 v206, v4, v5
	v_cvt_pk_bf16_f32 v207, v6, v7
	v_cvt_pk_bf16_f32 v208, v8, v9
	v_cvt_pk_bf16_f32 v209, v10, v11
	v_cvt_pk_bf16_f32 v210, v12, v13
	v_cvt_pk_bf16_f32 v211, v14, v15
	global_store_dwordx2 v203, v[204:205], s[48:49] sc1
	global_store_dwordx2 v203, v[206:207], s[48:49] offset:512 sc1
	global_store_dwordx2 v203, v[208:209], s[48:49] offset:1024 sc1
	global_store_dwordx2 v203, v[210:211], s[48:49] offset:1536 sc1
	s_add_u32 s48, s48, 0x800
	s_addc_u32 s49, s49, 0
	v_pk_mul_f32 v[16:17], v[192:193], v[16:17] op_sel_hi:[0,1]
	v_pk_mul_f32 v[18:19], v[192:193], v[18:19] op_sel_hi:[0,1]
	v_pk_mul_f32 v[20:21], v[192:193], v[20:21] op_sel_hi:[0,1]
	v_pk_mul_f32 v[22:23], v[192:193], v[22:23] op_sel_hi:[0,1]
	v_pk_mul_f32 v[24:25], v[192:193], v[24:25] op_sel_hi:[0,1]
	v_pk_mul_f32 v[26:27], v[192:193], v[26:27] op_sel_hi:[0,1]
	v_pk_mul_f32 v[28:29], v[192:193], v[28:29] op_sel_hi:[0,1]
	v_pk_mul_f32 v[30:31], v[192:193], v[30:31] op_sel_hi:[0,1]
	v_pk_mul_f32 v[16:17], v[64:65], v[16:17]
	v_pk_mul_f32 v[18:19], v[66:67], v[18:19]
	v_pk_mul_f32 v[20:21], v[68:69], v[20:21]
	v_pk_mul_f32 v[22:23], v[70:71], v[22:23]
	v_pk_mul_f32 v[24:25], v[72:73], v[24:25]
	v_pk_mul_f32 v[26:27], v[74:75], v[26:27]
	v_pk_mul_f32 v[28:29], v[76:77], v[28:29]
	v_pk_mul_f32 v[30:31], v[78:79], v[30:31]
	v_pk_fma_f32 v[16:17], v[80:81], v[16:17], v[162:163]
	v_pk_fma_f32 v[18:19], v[82:83], v[18:19], v[164:165]
	v_pk_fma_f32 v[20:21], v[84:85], v[20:21], v[166:167]
	v_pk_fma_f32 v[22:23], v[86:87], v[22:23], v[168:169]
	v_pk_fma_f32 v[24:25], v[88:89], v[24:25], v[170:171]
	v_pk_fma_f32 v[26:27], v[90:91], v[26:27], v[172:173]
	v_pk_fma_f32 v[28:29], v[92:93], v[28:29], v[174:175]
	v_pk_fma_f32 v[30:31], v[94:95], v[30:31], v[176:177]
	v_cvt_pk_bf16_f32 v212, v16, v17
	v_cvt_pk_bf16_f32 v213, v18, v19
	v_cvt_pk_bf16_f32 v214, v20, v21
	v_cvt_pk_bf16_f32 v215, v22, v23
	v_cvt_pk_bf16_f32 v216, v24, v25
	v_cvt_pk_bf16_f32 v217, v26, v27
	v_cvt_pk_bf16_f32 v218, v28, v29
	v_cvt_pk_bf16_f32 v219, v30, v31
	global_store_dwordx2 v203, v[212:213], s[48:49] sc1
	global_store_dwordx2 v203, v[214:215], s[48:49] offset:512 sc1
	global_store_dwordx2 v203, v[216:217], s[48:49] offset:1024 sc1
	global_store_dwordx2 v203, v[218:219], s[48:49] offset:1536 sc1
	s_add_u32 s48, s48, 0x800
	s_addc_u32 s49, s49, 0
	v_pk_mul_f32 v[32:33], v[194:195], v[32:33] op_sel_hi:[0,1]
	v_pk_mul_f32 v[34:35], v[194:195], v[34:35] op_sel_hi:[0,1]
	v_pk_mul_f32 v[36:37], v[194:195], v[36:37] op_sel_hi:[0,1]
	v_pk_mul_f32 v[38:39], v[194:195], v[38:39] op_sel_hi:[0,1]
	v_pk_mul_f32 v[40:41], v[194:195], v[40:41] op_sel_hi:[0,1]
	v_pk_mul_f32 v[42:43], v[194:195], v[42:43] op_sel_hi:[0,1]
	v_pk_mul_f32 v[44:45], v[194:195], v[44:45] op_sel_hi:[0,1]
	v_pk_mul_f32 v[46:47], v[194:195], v[46:47] op_sel_hi:[0,1]
	v_pk_mul_f32 v[32:33], v[64:65], v[32:33]
	v_pk_mul_f32 v[34:35], v[66:67], v[34:35]
	v_pk_mul_f32 v[36:37], v[68:69], v[36:37]
	v_pk_mul_f32 v[38:39], v[70:71], v[38:39]
	v_pk_mul_f32 v[40:41], v[72:73], v[40:41]
	v_pk_mul_f32 v[42:43], v[74:75], v[42:43]
	v_pk_mul_f32 v[44:45], v[76:77], v[44:45]
	v_pk_mul_f32 v[46:47], v[78:79], v[46:47]
	v_pk_fma_f32 v[32:33], v[80:81], v[32:33], v[162:163]
	v_pk_fma_f32 v[34:35], v[82:83], v[34:35], v[164:165]
	v_pk_fma_f32 v[36:37], v[84:85], v[36:37], v[166:167]
	v_pk_fma_f32 v[38:39], v[86:87], v[38:39], v[168:169]
	v_pk_fma_f32 v[40:41], v[88:89], v[40:41], v[170:171]
	v_pk_fma_f32 v[42:43], v[90:91], v[42:43], v[172:173]
	v_pk_fma_f32 v[44:45], v[92:93], v[44:45], v[174:175]
	v_pk_fma_f32 v[46:47], v[94:95], v[46:47], v[176:177]
	v_cvt_pk_bf16_f32 v204, v32, v33
	v_cvt_pk_bf16_f32 v205, v34, v35
	v_cvt_pk_bf16_f32 v206, v36, v37
	v_cvt_pk_bf16_f32 v207, v38, v39
	v_cvt_pk_bf16_f32 v208, v40, v41
	v_cvt_pk_bf16_f32 v209, v42, v43
	v_cvt_pk_bf16_f32 v210, v44, v45
	v_cvt_pk_bf16_f32 v211, v46, v47
	global_store_dwordx2 v203, v[204:205], s[48:49] sc1
	global_store_dwordx2 v203, v[206:207], s[48:49] offset:512 sc1
	global_store_dwordx2 v203, v[208:209], s[48:49] offset:1024 sc1
	global_store_dwordx2 v203, v[210:211], s[48:49] offset:1536 sc1
	s_add_u32 s48, s48, 0x800
	s_addc_u32 s49, s49, 0
	v_pk_mul_f32 v[48:49], v[196:197], v[48:49] op_sel_hi:[0,1]
	v_pk_mul_f32 v[50:51], v[196:197], v[50:51] op_sel_hi:[0,1]
	v_pk_mul_f32 v[52:53], v[196:197], v[52:53] op_sel_hi:[0,1]
	v_pk_mul_f32 v[54:55], v[196:197], v[54:55] op_sel_hi:[0,1]
	v_pk_mul_f32 v[56:57], v[196:197], v[56:57] op_sel_hi:[0,1]
	v_pk_mul_f32 v[58:59], v[196:197], v[58:59] op_sel_hi:[0,1]
	v_pk_mul_f32 v[60:61], v[196:197], v[60:61] op_sel_hi:[0,1]
	v_pk_mul_f32 v[62:63], v[196:197], v[62:63] op_sel_hi:[0,1]
	v_pk_mul_f32 v[48:49], v[64:65], v[48:49]
	v_pk_mul_f32 v[50:51], v[66:67], v[50:51]
	v_pk_mul_f32 v[52:53], v[68:69], v[52:53]
	v_pk_mul_f32 v[54:55], v[70:71], v[54:55]
	v_pk_mul_f32 v[56:57], v[72:73], v[56:57]
	v_pk_mul_f32 v[58:59], v[74:75], v[58:59]
	v_pk_mul_f32 v[60:61], v[76:77], v[60:61]
	v_pk_mul_f32 v[62:63], v[78:79], v[62:63]
	v_pk_fma_f32 v[48:49], v[80:81], v[48:49], v[162:163]
	v_pk_fma_f32 v[50:51], v[82:83], v[50:51], v[164:165]
	v_pk_fma_f32 v[52:53], v[84:85], v[52:53], v[166:167]
	v_pk_fma_f32 v[54:55], v[86:87], v[54:55], v[168:169]
	v_pk_fma_f32 v[56:57], v[88:89], v[56:57], v[170:171]
	v_pk_fma_f32 v[58:59], v[90:91], v[58:59], v[172:173]
	v_pk_fma_f32 v[60:61], v[92:93], v[60:61], v[174:175]
	v_pk_fma_f32 v[62:63], v[94:95], v[62:63], v[176:177]
	v_cvt_pk_bf16_f32 v212, v48, v49
	v_cvt_pk_bf16_f32 v213, v50, v51
	v_cvt_pk_bf16_f32 v214, v52, v53
	v_cvt_pk_bf16_f32 v215, v54, v55
	v_cvt_pk_bf16_f32 v216, v56, v57
	v_cvt_pk_bf16_f32 v217, v58, v59
	v_cvt_pk_bf16_f32 v218, v60, v61
	v_cvt_pk_bf16_f32 v219, v62, v63
	global_store_dwordx2 v203, v[212:213], s[48:49] sc1
	global_store_dwordx2 v203, v[214:215], s[48:49] offset:512 sc1
	global_store_dwordx2 v203, v[216:217], s[48:49] offset:1024 sc1
	global_store_dwordx2 v203, v[218:219], s[48:49] offset:1536 sc1
	s_add_u32 s48, s48, 0x800
	s_addc_u32 s49, s49, 0
	s_waitcnt vmcnt(8)
	v_mul_f32_e32 v178, v98, v98
	v_mul_f32_e32 v179, v114, v114
	v_mul_f32_e32 v180, v130, v130
	v_mul_f32_e32 v181, v146, v146
	v_fma_f32 v178, v99, v99, v178
	v_fma_f32 v179, v115, v115, v179
	v_fma_f32 v180, v131, v131, v180
	v_fma_f32 v181, v147, v147, v181
	v_fma_f32 v178, v100, v100, v178
	v_fma_f32 v179, v116, v116, v179
	v_fma_f32 v180, v132, v132, v180
	v_fma_f32 v181, v148, v148, v181
	v_fma_f32 v178, v101, v101, v178
	v_fma_f32 v179, v117, v117, v179
	v_fma_f32 v180, v133, v133, v180
	v_fma_f32 v181, v149, v149, v181
	v_fma_f32 v178, v102, v102, v178
	v_fma_f32 v179, v118, v118, v179
	v_fma_f32 v180, v134, v134, v180
	v_fma_f32 v181, v150, v150, v181
	v_fma_f32 v178, v103, v103, v178
	v_fma_f32 v179, v119, v119, v179
	v_fma_f32 v180, v135, v135, v180
	v_fma_f32 v181, v151, v151, v181
	v_fma_f32 v178, v104, v104, v178
	v_fma_f32 v179, v120, v120, v179
	v_fma_f32 v180, v136, v136, v180
	v_fma_f32 v181, v152, v152, v181
	v_fma_f32 v178, v105, v105, v178
	v_fma_f32 v179, v121, v121, v179
	v_fma_f32 v180, v137, v137, v180
	v_fma_f32 v181, v153, v153, v181
	v_fma_f32 v178, v106, v106, v178
	v_fma_f32 v179, v122, v122, v179
	v_fma_f32 v180, v138, v138, v180
	v_fma_f32 v181, v154, v154, v181
	v_fma_f32 v178, v107, v107, v178
	v_fma_f32 v179, v123, v123, v179
	v_fma_f32 v180, v139, v139, v180
	v_fma_f32 v181, v155, v155, v181
	v_fma_f32 v178, v108, v108, v178
	v_fma_f32 v179, v124, v124, v179
	v_fma_f32 v180, v140, v140, v180
	v_fma_f32 v181, v156, v156, v181
	v_fma_f32 v178, v109, v109, v178
	v_fma_f32 v179, v125, v125, v179
	v_fma_f32 v180, v141, v141, v180
	v_fma_f32 v181, v157, v157, v181
	v_fma_f32 v178, v110, v110, v178
	v_fma_f32 v179, v126, v126, v179
	v_fma_f32 v180, v142, v142, v180
	v_fma_f32 v181, v158, v158, v181
	v_fma_f32 v178, v111, v111, v178
	v_fma_f32 v179, v127, v127, v179
	v_fma_f32 v180, v143, v143, v180
	v_fma_f32 v181, v159, v159, v181
	v_fma_f32 v178, v112, v112, v178
	v_fma_f32 v179, v128, v128, v179
	v_fma_f32 v180, v144, v144, v180
	v_fma_f32 v181, v160, v160, v181
	v_fma_f32 v178, v113, v113, v178
	v_fma_f32 v179, v129, v129, v179
	v_fma_f32 v180, v145, v145, v180
	v_fma_f32 v181, v161, v161, v181
	v_add_f32_dpp v178, v178, v178 quad_perm:[1,0,3,2] row_mask:0xf bank_mask:0xf
	v_add_f32_dpp v179, v179, v179 quad_perm:[1,0,3,2] row_mask:0xf bank_mask:0xf
	v_add_f32_dpp v180, v180, v180 quad_perm:[1,0,3,2] row_mask:0xf bank_mask:0xf
	v_add_f32_dpp v181, v181, v181 quad_perm:[1,0,3,2] row_mask:0xf bank_mask:0xf
	v_add_f32_dpp v178, v178, v178 quad_perm:[2,3,0,1] row_mask:0xf bank_mask:0xf
	v_add_f32_dpp v179, v179, v179 quad_perm:[2,3,0,1] row_mask:0xf bank_mask:0xf
	v_add_f32_dpp v180, v180, v180 quad_perm:[2,3,0,1] row_mask:0xf bank_mask:0xf
	v_add_f32_dpp v181, v181, v181 quad_perm:[2,3,0,1] row_mask:0xf bank_mask:0xf
	v_add_f32_dpp v178, v178, v178 row_half_mirror row_mask:0xf bank_mask:0xf
	v_add_f32_dpp v179, v179, v179 row_half_mirror row_mask:0xf bank_mask:0xf
	v_add_f32_dpp v180, v180, v180 row_half_mirror row_mask:0xf bank_mask:0xf
	v_add_f32_dpp v181, v181, v181 row_half_mirror row_mask:0xf bank_mask:0xf
	v_add_f32_dpp v178, v178, v178 row_ror:8 row_mask:0xf bank_mask:0xf
	v_add_f32_dpp v179, v179, v179 row_ror:8 row_mask:0xf bank_mask:0xf
	v_add_f32_dpp v180, v180, v180 row_ror:8 row_mask:0xf bank_mask:0xf
	v_add_f32_dpp v181, v181, v181 row_ror:8 row_mask:0xf bank_mask:0xf
	v_mov_b32_e32 v182, v178
	v_mov_b32_e32 v183, v179
	v_mov_b32_e32 v184, v180
	v_mov_b32_e32 v185, v181
	v_permlane16_swap_b32_e32 v182, v178
	v_permlane16_swap_b32_e32 v183, v179
	v_permlane16_swap_b32_e32 v184, v180
	v_permlane16_swap_b32_e32 v185, v181
	v_add_f32_e32 v178, v178, v182
	v_add_f32_e32 v179, v179, v183
	v_add_f32_e32 v180, v180, v184
	v_add_f32_e32 v181, v181, v185
	v_mov_b32_e32 v182, v178
	v_mov_b32_e32 v183, v179
	v_mov_b32_e32 v184, v180
	v_mov_b32_e32 v185, v181
	v_permlane32_swap_b32_e32 v182, v178
	v_permlane32_swap_b32_e32 v183, v179
	v_permlane32_swap_b32_e32 v184, v180
	v_permlane32_swap_b32_e32 v185, v181
	v_add_f32_e32 v178, v178, v182
	v_add_f32_e32 v179, v179, v183
	v_add_f32_e32 v180, v180, v184
	v_add_f32_e32 v181, v181, v185
	v_fmamk_f32 v198, v178, 0x3a800000, v225
	v_fmamk_f32 v199, v179, 0x3a800000, v225
	v_fmamk_f32 v200, v180, 0x3a800000, v225
	v_fmamk_f32 v201, v181, 0x3a800000, v225
	v_mul_f32_e32 v182, 0x4b800000, v198
	v_mul_f32_e32 v183, 0x4b800000, v199
	v_mul_f32_e32 v184, 0x4b800000, v200
	v_mul_f32_e32 v185, 0x4b800000, v201
	v_cmp_gt_f32_e64 s[2:3], s30, v198
	v_cmp_gt_f32_e64 s[50:51], s30, v199
	v_cmp_gt_f32_e64 s[88:89], s30, v200
	v_cmp_gt_f32_e64 s[90:91], s30, v201
	v_cndmask_b32_e64 v198, v198, v182, s[2:3]
	v_cndmask_b32_e64 v199, v199, v183, s[50:51]
	v_cndmask_b32_e64 v200, v200, v184, s[88:89]
	v_cndmask_b32_e64 v201, v201, v185, s[90:91]
	v_rsq_f32_e32 v198, v198
	v_rsq_f32_e32 v199, v199
	v_rsq_f32_e32 v200, v200
	v_rsq_f32_e32 v201, v201
	v_mul_f32_e32 v182, 0x45800000, v198
	v_mul_f32_e32 v183, 0x45800000, v199
	v_mul_f32_e32 v184, 0x45800000, v200
	v_mul_f32_e32 v185, 0x45800000, v201
	v_cndmask_b32_e64 v186, v198, v182, s[2:3]
	v_cndmask_b32_e64 v192, v199, v183, s[50:51]
	v_cndmask_b32_e64 v194, v200, v184, s[88:89]
	v_cndmask_b32_e64 v196, v201, v185, s[90:91]
	v_pk_mul_f32 v[98:99], v[186:187], v[98:99] op_sel_hi:[0,1]
	v_pk_mul_f32 v[100:101], v[186:187], v[100:101] op_sel_hi:[0,1]
	v_pk_mul_f32 v[102:103], v[186:187], v[102:103] op_sel_hi:[0,1]
	v_pk_mul_f32 v[104:105], v[186:187], v[104:105] op_sel_hi:[0,1]
	v_pk_mul_f32 v[106:107], v[186:187], v[106:107] op_sel_hi:[0,1]
	v_pk_mul_f32 v[108:109], v[186:187], v[108:109] op_sel_hi:[0,1]
	v_pk_mul_f32 v[110:111], v[186:187], v[110:111] op_sel_hi:[0,1]
	v_pk_mul_f32 v[112:113], v[186:187], v[112:113] op_sel_hi:[0,1]
	v_pk_mul_f32 v[98:99], v[64:65], v[98:99]
	v_pk_mul_f32 v[100:101], v[66:67], v[100:101]
	v_pk_mul_f32 v[102:103], v[68:69], v[102:103]
	v_pk_mul_f32 v[104:105], v[70:71], v[104:105]
	v_pk_mul_f32 v[106:107], v[72:73], v[106:107]
	v_pk_mul_f32 v[108:109], v[74:75], v[108:109]
	v_pk_mul_f32 v[110:111], v[76:77], v[110:111]
	v_pk_mul_f32 v[112:113], v[78:79], v[112:113]
	v_pk_fma_f32 v[98:99], v[80:81], v[98:99], v[162:163]
	v_pk_fma_f32 v[100:101], v[82:83], v[100:101], v[164:165]
	v_pk_fma_f32 v[102:103], v[84:85], v[102:103], v[166:167]
	v_pk_fma_f32 v[104:105], v[86:87], v[104:105], v[168:169]
	v_pk_fma_f32 v[106:107], v[88:89], v[106:107], v[170:171]
	v_pk_fma_f32 v[108:109], v[90:91], v[108:109], v[172:173]
	v_pk_fma_f32 v[110:111], v[92:93], v[110:111], v[174:175]
	v_pk_fma_f32 v[112:113], v[94:95], v[112:113], v[176:177]
	v_cvt_pk_bf16_f32 v204, v98, v99
	v_cvt_pk_bf16_f32 v205, v100, v101
	v_cvt_pk_bf16_f32 v206, v102, v103
	v_cvt_pk_bf16_f32 v207, v104, v105
	v_cvt_pk_bf16_f32 v208, v106, v107
	v_cvt_pk_bf16_f32 v209, v108, v109
	v_cvt_pk_bf16_f32 v210, v110, v111
	v_cvt_pk_bf16_f32 v211, v112, v113
	global_store_dwordx2 v203, v[204:205], s[48:49] sc1
	global_store_dwordx2 v203, v[206:207], s[48:49] offset:512 sc1
	global_store_dwordx2 v203, v[208:209], s[48:49] offset:1024 sc1
	global_store_dwordx2 v203, v[210:211], s[48:49] offset:1536 sc1
	s_add_u32 s48, s48, 0x800
	s_addc_u32 s49, s49, 0
	v_pk_mul_f32 v[114:115], v[192:193], v[114:115] op_sel_hi:[0,1]
	v_pk_mul_f32 v[116:117], v[192:193], v[116:117] op_sel_hi:[0,1]
	v_pk_mul_f32 v[118:119], v[192:193], v[118:119] op_sel_hi:[0,1]
	v_pk_mul_f32 v[120:121], v[192:193], v[120:121] op_sel_hi:[0,1]
	v_pk_mul_f32 v[122:123], v[192:193], v[122:123] op_sel_hi:[0,1]
	v_pk_mul_f32 v[124:125], v[192:193], v[124:125] op_sel_hi:[0,1]
	v_pk_mul_f32 v[126:127], v[192:193], v[126:127] op_sel_hi:[0,1]
	v_pk_mul_f32 v[128:129], v[192:193], v[128:129] op_sel_hi:[0,1]
	v_pk_mul_f32 v[114:115], v[64:65], v[114:115]
	v_pk_mul_f32 v[116:117], v[66:67], v[116:117]
	v_pk_mul_f32 v[118:119], v[68:69], v[118:119]
	v_pk_mul_f32 v[120:121], v[70:71], v[120:121]
	v_pk_mul_f32 v[122:123], v[72:73], v[122:123]
	v_pk_mul_f32 v[124:125], v[74:75], v[124:125]
	v_pk_mul_f32 v[126:127], v[76:77], v[126:127]
	v_pk_mul_f32 v[128:129], v[78:79], v[128:129]
	v_pk_fma_f32 v[114:115], v[80:81], v[114:115], v[162:163]
	v_pk_fma_f32 v[116:117], v[82:83], v[116:117], v[164:165]
	v_pk_fma_f32 v[118:119], v[84:85], v[118:119], v[166:167]
	v_pk_fma_f32 v[120:121], v[86:87], v[120:121], v[168:169]
	v_pk_fma_f32 v[122:123], v[88:89], v[122:123], v[170:171]
	v_pk_fma_f32 v[124:125], v[90:91], v[124:125], v[172:173]
	v_pk_fma_f32 v[126:127], v[92:93], v[126:127], v[174:175]
	v_pk_fma_f32 v[128:129], v[94:95], v[128:129], v[176:177]
	v_cvt_pk_bf16_f32 v212, v114, v115
	v_cvt_pk_bf16_f32 v213, v116, v117
	v_cvt_pk_bf16_f32 v214, v118, v119
	v_cvt_pk_bf16_f32 v215, v120, v121
	v_cvt_pk_bf16_f32 v216, v122, v123
	v_cvt_pk_bf16_f32 v217, v124, v125
	v_cvt_pk_bf16_f32 v218, v126, v127
	v_cvt_pk_bf16_f32 v219, v128, v129
	global_store_dwordx2 v203, v[212:213], s[48:49] sc1
	global_store_dwordx2 v203, v[214:215], s[48:49] offset:512 sc1
	global_store_dwordx2 v203, v[216:217], s[48:49] offset:1024 sc1
	global_store_dwordx2 v203, v[218:219], s[48:49] offset:1536 sc1
	s_add_u32 s48, s48, 0x800
	s_addc_u32 s49, s49, 0
	v_pk_mul_f32 v[130:131], v[194:195], v[130:131] op_sel_hi:[0,1]
	v_pk_mul_f32 v[132:133], v[194:195], v[132:133] op_sel_hi:[0,1]
	v_pk_mul_f32 v[134:135], v[194:195], v[134:135] op_sel_hi:[0,1]
	v_pk_mul_f32 v[136:137], v[194:195], v[136:137] op_sel_hi:[0,1]
	v_pk_mul_f32 v[138:139], v[194:195], v[138:139] op_sel_hi:[0,1]
	v_pk_mul_f32 v[140:141], v[194:195], v[140:141] op_sel_hi:[0,1]
	v_pk_mul_f32 v[142:143], v[194:195], v[142:143] op_sel_hi:[0,1]
	v_pk_mul_f32 v[144:145], v[194:195], v[144:145] op_sel_hi:[0,1]
	v_pk_mul_f32 v[130:131], v[64:65], v[130:131]
	v_pk_mul_f32 v[132:133], v[66:67], v[132:133]
	v_pk_mul_f32 v[134:135], v[68:69], v[134:135]
	v_pk_mul_f32 v[136:137], v[70:71], v[136:137]
	v_pk_mul_f32 v[138:139], v[72:73], v[138:139]
	v_pk_mul_f32 v[140:141], v[74:75], v[140:141]
	v_pk_mul_f32 v[142:143], v[76:77], v[142:143]
	v_pk_mul_f32 v[144:145], v[78:79], v[144:145]
	v_pk_fma_f32 v[130:131], v[80:81], v[130:131], v[162:163]
	v_pk_fma_f32 v[132:133], v[82:83], v[132:133], v[164:165]
	v_pk_fma_f32 v[134:135], v[84:85], v[134:135], v[166:167]
	v_pk_fma_f32 v[136:137], v[86:87], v[136:137], v[168:169]
	v_pk_fma_f32 v[138:139], v[88:89], v[138:139], v[170:171]
	v_pk_fma_f32 v[140:141], v[90:91], v[140:141], v[172:173]
	v_pk_fma_f32 v[142:143], v[92:93], v[142:143], v[174:175]
	v_pk_fma_f32 v[144:145], v[94:95], v[144:145], v[176:177]
	v_cvt_pk_bf16_f32 v204, v130, v131
	v_cvt_pk_bf16_f32 v205, v132, v133
	v_cvt_pk_bf16_f32 v206, v134, v135
	v_cvt_pk_bf16_f32 v207, v136, v137
	v_cvt_pk_bf16_f32 v208, v138, v139
	v_cvt_pk_bf16_f32 v209, v140, v141
	v_cvt_pk_bf16_f32 v210, v142, v143
	v_cvt_pk_bf16_f32 v211, v144, v145
	global_store_dwordx2 v203, v[204:205], s[48:49] sc1
	global_store_dwordx2 v203, v[206:207], s[48:49] offset:512 sc1
	global_store_dwordx2 v203, v[208:209], s[48:49] offset:1024 sc1
	global_store_dwordx2 v203, v[210:211], s[48:49] offset:1536 sc1
	s_add_u32 s48, s48, 0x800
	s_addc_u32 s49, s49, 0
	v_pk_mul_f32 v[146:147], v[196:197], v[146:147] op_sel_hi:[0,1]
	v_pk_mul_f32 v[148:149], v[196:197], v[148:149] op_sel_hi:[0,1]
	v_pk_mul_f32 v[150:151], v[196:197], v[150:151] op_sel_hi:[0,1]
	v_pk_mul_f32 v[152:153], v[196:197], v[152:153] op_sel_hi:[0,1]
	v_pk_mul_f32 v[154:155], v[196:197], v[154:155] op_sel_hi:[0,1]
	v_pk_mul_f32 v[156:157], v[196:197], v[156:157] op_sel_hi:[0,1]
	v_pk_mul_f32 v[158:159], v[196:197], v[158:159] op_sel_hi:[0,1]
	v_pk_mul_f32 v[160:161], v[196:197], v[160:161] op_sel_hi:[0,1]
	v_pk_mul_f32 v[146:147], v[64:65], v[146:147]
	v_pk_mul_f32 v[148:149], v[66:67], v[148:149]
	v_pk_mul_f32 v[150:151], v[68:69], v[150:151]
	v_pk_mul_f32 v[152:153], v[70:71], v[152:153]
	v_pk_mul_f32 v[154:155], v[72:73], v[154:155]
	v_pk_mul_f32 v[156:157], v[74:75], v[156:157]
	v_pk_mul_f32 v[158:159], v[76:77], v[158:159]
	v_pk_mul_f32 v[160:161], v[78:79], v[160:161]
	v_pk_fma_f32 v[146:147], v[80:81], v[146:147], v[162:163]
	v_pk_fma_f32 v[148:149], v[82:83], v[148:149], v[164:165]
	v_pk_fma_f32 v[150:151], v[84:85], v[150:151], v[166:167]
	v_pk_fma_f32 v[152:153], v[86:87], v[152:153], v[168:169]
	v_pk_fma_f32 v[154:155], v[88:89], v[154:155], v[170:171]
	v_pk_fma_f32 v[156:157], v[90:91], v[156:157], v[172:173]
	v_pk_fma_f32 v[158:159], v[92:93], v[158:159], v[174:175]
	v_pk_fma_f32 v[160:161], v[94:95], v[160:161], v[176:177]
	v_cvt_pk_bf16_f32 v212, v146, v147
	v_cvt_pk_bf16_f32 v213, v148, v149
	v_cvt_pk_bf16_f32 v214, v150, v151
	v_cvt_pk_bf16_f32 v215, v152, v153
	v_cvt_pk_bf16_f32 v216, v154, v155
	v_cvt_pk_bf16_f32 v217, v156, v157
	v_cvt_pk_bf16_f32 v218, v158, v159
	v_cvt_pk_bf16_f32 v219, v160, v161
	global_store_dwordx2 v203, v[212:213], s[48:49] sc1
	global_store_dwordx2 v203, v[214:215], s[48:49] offset:512 sc1
	global_store_dwordx2 v203, v[216:217], s[48:49] offset:1024 sc1
	global_store_dwordx2 v203, v[218:219], s[48:49] offset:1536 sc1
	s_add_u32 s48, s48, 0x800
	s_addc_u32 s49, s49, 0
	s_nop 1
	s_branch .LBB0_286

.LBB0_455:
	s_andn2_b64 vcc, exec, s[12:13]
	s_cbranch_vccnz .LBB0_479
	s_cmp_gt_i32 s5, 11
	s_mov_b64 s[12:13], -1
	s_cbranch_scc0 .LBB0_461
	v_readlane_b32 s40, v253, 43
	v_readlane_b32 s42, v254, 34
	v_readlane_b32 s44, v254, 38
	s_mov_b64 s[86:87], s[58:59]
	s_cmpk_gt_i32 s52, 0x7fff
	v_readlane_b32 s41, v253, 44
	v_readlane_b32 s11, v254, 18
	v_readlane_b32 s43, v254, 35
	v_readlane_b32 s45, v254, 39
	s_mov_b64 s[48:49], 0x200
	s_mov_b64 s[50:51], 0x400
	s_mov_b64 s[84:85], s[56:57]
	s_mov_b64 s[56:57], 0x600
	s_cbranch_scc1 .LBB0_460
	v_readlane_b32 s2, v250, 0
	s_cmpk_lg_u32 s2, 0x100
	s_cbranch_scc1 .Lnrm_C_fallback
	v_lshrrev_b32_e32 v0, 6, v222
	v_and_b32_e32 v1, 63, v222
	v_readlane_b32 s4, v254, 48
	v_readfirstlane_b32 s3, v0
	v_readlane_b32 s82, v250, 2
	v_readlane_b32 s83, v250, 3
	s_lshl_b32 s4, s4, 3
	s_add_i32 s4, s4, s3
	s_load_dwordx2 s[18:19], s[82:83], 0x90
	s_mov_b32 s12, s72
	s_mov_b32 s13, s73
	s_lshr_b32 s2, s4, 7
	s_mul_i32 s2, s2, 0x9000
	s_add_u32 s20, s74, s2
	s_addc_u32 s21, s75, 0
	s_add_u32 s88, s20, 0x7000
	s_addc_u32 s89, s21, 0
	s_add_u32 s90, s20, 0x6000
	s_addc_u32 s91, s21, 0
	v_lshlrev_b32_e32 v202, 4, v1
	v_lshlrev_b32_e32 v203, 3, v1
	s_lshl_b32 s11, s4, 16
	s_lshl_b32 s2, s4, 15
	s_add_u32 s48, s74, s2
	s_addc_u32 s49, s75, 0
	s_add_u32 s48, s48, 0x13000000
	s_addc_u32 s49, s49, 0
	s_waitcnt lgkmcnt(0)
	s_and_b32 s13, s13, 0xffff
	s_mov_b32 s14, 0x8000000
	s_mov_b32 s15, 0x20000
	global_load_dwordx4 v[64:67], v202, s[18:19]
	global_load_dwordx4 v[68:71], v202, s[18:19] offset:1024
	global_load_dwordx4 v[72:75], v202, s[18:19] offset:2048
	global_load_dwordx4 v[76:79], v202, s[18:19] offset:3072
	global_load_dwordx4 v[80:83], v202, s[88:89]
	global_load_dwordx4 v[84:87], v202, s[88:89] offset:1024
	global_load_dwordx4 v[88:91], v202, s[88:89] offset:2048
	global_load_dwordx4 v[92:95], v202, s[88:89] offset:3072
	global_load_dwordx4 v[162:165], v202, s[90:91]
	global_load_dwordx4 v[166:169], v202, s[90:91] offset:1024
	global_load_dwordx4 v[170:173], v202, s[90:91] offset:2048
	global_load_dwordx4 v[174:177], v202, s[90:91] offset:3072
	buffer_load_dwordx4 v[0:3], v202, s[12:15], s11 offen sc1
	buffer_load_dwordx4 v[4:7], v202, s[12:15], s11 offen offset:1024 sc1
	buffer_load_dwordx4 v[8:11], v202, s[12:15], s11 offen offset:2048 sc1
	buffer_load_dwordx4 v[12:15], v202, s[12:15], s11 offen offset:3072 sc1
	s_add_u32 s11, s11, 0x1000
	buffer_load_dwordx4 v[16:19], v202, s[12:15], s11 offen sc1
	buffer_load_dwordx4 v[20:23], v202, s[12:15], s11 offen offset:1024 sc1
	buffer_load_dwordx4 v[24:27], v202, s[12:15], s11 offen offset:2048 sc1
	buffer_load_dwordx4 v[28:31], v202, s[12:15], s11 offen offset:3072 sc1
	s_add_u32 s11, s11, 0x1000
	buffer_load_dwordx4 v[32:35], v202, s[12:15], s11 offen sc1
	buffer_load_dwordx4 v[36:39], v202, s[12:15], s11 offen offset:1024 sc1
	buffer_load_dwordx4 v[40:43], v202, s[12:15], s11 offen offset:2048 sc1
	buffer_load_dwordx4 v[44:47], v202, s[12:15], s11 offen offset:3072 sc1
	s_add_u32 s11, s11, 0x1000
	buffer_load_dwordx4 v[48:51], v202, s[12:15], s11 offen sc1
	buffer_load_dwordx4 v[52:55], v202, s[12:15], s11 offen offset:1024 sc1
	buffer_load_dwordx4 v[56:59], v202, s[12:15], s11 offen offset:2048 sc1
	buffer_load_dwordx4 v[60:63], v202, s[12:15], s11 offen offset:3072 sc1
	s_add_u32 s11, s11, 0x1000
	buffer_load_dwordx4 v[98:101], v202, s[12:15], s11 offen sc1
	buffer_load_dwordx4 v[102:105], v202, s[12:15], s11 offen offset:1024 sc1
	buffer_load_dwordx4 v[106:109], v202, s[12:15], s11 offen offset:2048 sc1
	buffer_load_dwordx4 v[110:113], v202, s[12:15], s11 offen offset:3072 sc1
	s_add_u32 s11, s11, 0x1000
	buffer_load_dwordx4 v[114:117], v202, s[12:15], s11 offen sc1
	buffer_load_dwordx4 v[118:121], v202, s[12:15], s11 offen offset:1024 sc1
	buffer_load_dwordx4 v[122:125], v202, s[12:15], s11 offen offset:2048 sc1
	buffer_load_dwordx4 v[126:129], v202, s[12:15], s11 offen offset:3072 sc1
	s_add_u32 s11, s11, 0x1000
	buffer_load_dwordx4 v[130:133], v202, s[12:15], s11 offen sc1
	buffer_load_dwordx4 v[134:137], v202, s[12:15], s11 offen offset:1024 sc1
	buffer_load_dwordx4 v[138:141], v202, s[12:15], s11 offen offset:2048 sc1
	buffer_load_dwordx4 v[142:145], v202, s[12:15], s11 offen offset:3072 sc1
	s_add_u32 s11, s11, 0x1000
	buffer_load_dwordx4 v[146:149], v202, s[12:15], s11 offen sc1
	buffer_load_dwordx4 v[150:153], v202, s[12:15], s11 offen offset:1024 sc1
	buffer_load_dwordx4 v[154:157], v202, s[12:15], s11 offen offset:2048 sc1
	buffer_load_dwordx4 v[158:161], v202, s[12:15], s11 offen offset:3072 sc1
	s_add_u32 s11, s11, 0x1000
	s_waitcnt vmcnt(16)
	v_pk_add_f32 v[80:81], v[80:81], 1.0 op_sel_hi:[1,0]
	v_pk_add_f32 v[82:83], v[82:83], 1.0 op_sel_hi:[1,0]
	v_pk_add_f32 v[84:85], v[84:85], 1.0 op_sel_hi:[1,0]
	v_pk_add_f32 v[86:87], v[86:87], 1.0 op_sel_hi:[1,0]
	v_pk_add_f32 v[88:89], v[88:89], 1.0 op_sel_hi:[1,0]
	v_pk_add_f32 v[90:91], v[90:91], 1.0 op_sel_hi:[1,0]
	v_pk_add_f32 v[92:93], v[92:93], 1.0 op_sel_hi:[1,0]
	v_pk_add_f32 v[94:95], v[94:95], 1.0 op_sel_hi:[1,0]
	v_mul_f32_e32 v178, v0, v0
	v_mul_f32_e32 v179, v16, v16
	v_mul_f32_e32 v180, v32, v32
	v_mul_f32_e32 v181, v48, v48
	v_fma_f32 v178, v1, v1, v178
	v_fma_f32 v179, v17, v17, v179
	v_fma_f32 v180, v33, v33, v180
	v_fma_f32 v181, v49, v49, v181
	v_fma_f32 v178, v2, v2, v178
	v_fma_f32 v179, v18, v18, v179
	v_fma_f32 v180, v34, v34, v180
	v_fma_f32 v181, v50, v50, v181
	v_fma_f32 v178, v3, v3, v178
	v_fma_f32 v179, v19, v19, v179
	v_fma_f32 v180, v35, v35, v180
	v_fma_f32 v181, v51, v51, v181
	v_fma_f32 v178, v4, v4, v178
	v_fma_f32 v179, v20, v20, v179
	v_fma_f32 v180, v36, v36, v180
	v_fma_f32 v181, v52, v52, v181
	v_fma_f32 v178, v5, v5, v178
	v_fma_f32 v179, v21, v21, v179
	v_fma_f32 v180, v37, v37, v180
	v_fma_f32 v181, v53, v53, v181
	v_fma_f32 v178, v6, v6, v178
	v_fma_f32 v179, v22, v22, v179
	v_fma_f32 v180, v38, v38, v180
	v_fma_f32 v181, v54, v54, v181
	v_fma_f32 v178, v7, v7, v178
	v_fma_f32 v179, v23, v23, v179
	v_fma_f32 v180, v39, v39, v180
	v_fma_f32 v181, v55, v55, v181
	v_fma_f32 v178, v8, v8, v178
	v_fma_f32 v179, v24, v24, v179
	v_fma_f32 v180, v40, v40, v180
	v_fma_f32 v181, v56, v56, v181
	v_fma_f32 v178, v9, v9, v178
	v_fma_f32 v179, v25, v25, v179
	v_fma_f32 v180, v41, v41, v180
	v_fma_f32 v181, v57, v57, v181
	v_fma_f32 v178, v10, v10, v178
	v_fma_f32 v179, v26, v26, v179
	v_fma_f32 v180, v42, v42, v180
	v_fma_f32 v181, v58, v58, v181
	v_fma_f32 v178, v11, v11, v178
	v_fma_f32 v179, v27, v27, v179
	v_fma_f32 v180, v43, v43, v180
	v_fma_f32 v181, v59, v59, v181
	v_fma_f32 v178, v12, v12, v178
	v_fma_f32 v179, v28, v28, v179
	v_fma_f32 v180, v44, v44, v180
	v_fma_f32 v181, v60, v60, v181
	v_fma_f32 v178, v13, v13, v178
	v_fma_f32 v179, v29, v29, v179
	v_fma_f32 v180, v45, v45, v180
	v_fma_f32 v181, v61, v61, v181
	v_fma_f32 v178, v14, v14, v178
	v_fma_f32 v179, v30, v30, v179
	v_fma_f32 v180, v46, v46, v180
	v_fma_f32 v181, v62, v62, v181
	v_fma_f32 v178, v15, v15, v178
	v_fma_f32 v179, v31, v31, v179
	v_fma_f32 v180, v47, v47, v180
	v_fma_f32 v181, v63, v63, v181
	v_add_f32_dpp v178, v178, v178 quad_perm:[1,0,3,2] row_mask:0xf bank_mask:0xf
	v_add_f32_dpp v179, v179, v179 quad_perm:[1,0,3,2] row_mask:0xf bank_mask:0xf
	v_add_f32_dpp v180, v180, v180 quad_perm:[1,0,3,2] row_mask:0xf bank_mask:0xf
	v_add_f32_dpp v181, v181, v181 quad_perm:[1,0,3,2] row_mask:0xf bank_mask:0xf
	v_add_f32_dpp v178, v178, v178 quad_perm:[2,3,0,1] row_mask:0xf bank_mask:0xf
	v_add_f32_dpp v179, v179, v179 quad_perm:[2,3,0,1] row_mask:0xf bank_mask:0xf
	v_add_f32_dpp v180, v180, v180 quad_perm:[2,3,0,1] row_mask:0xf bank_mask:0xf
	v_add_f32_dpp v181, v181, v181 quad_perm:[2,3,0,1] row_mask:0xf bank_mask:0xf
	v_add_f32_dpp v178, v178, v178 row_half_mirror row_mask:0xf bank_mask:0xf
	v_add_f32_dpp v179, v179, v179 row_half_mirror row_mask:0xf bank_mask:0xf
	v_add_f32_dpp v180, v180, v180 row_half_mirror row_mask:0xf bank_mask:0xf
	v_add_f32_dpp v181, v181, v181 row_half_mirror row_mask:0xf bank_mask:0xf
	v_add_f32_dpp v178, v178, v178 row_ror:8 row_mask:0xf bank_mask:0xf
	v_add_f32_dpp v179, v179, v179 row_ror:8 row_mask:0xf bank_mask:0xf
	v_add_f32_dpp v180, v180, v180 row_ror:8 row_mask:0xf bank_mask:0xf
	v_add_f32_dpp v181, v181, v181 row_ror:8 row_mask:0xf bank_mask:0xf
	v_mov_b32_e32 v182, v178
	v_mov_b32_e32 v183, v179
	v_mov_b32_e32 v184, v180
	v_mov_b32_e32 v185, v181
	v_permlane16_swap_b32_e32 v182, v178
	v_permlane16_swap_b32_e32 v183, v179
	v_permlane16_swap_b32_e32 v184, v180
	v_permlane16_swap_b32_e32 v185, v181
	v_add_f32_e32 v178, v178, v182
	v_add_f32_e32 v179, v179, v183
	v_add_f32_e32 v180, v180, v184
	v_add_f32_e32 v181, v181, v185
	v_mov_b32_e32 v182, v178
	v_mov_b32_e32 v183, v179
	v_mov_b32_e32 v184, v180
	v_mov_b32_e32 v185, v181
	v_permlane32_swap_b32_e32 v182, v178
	v_permlane32_swap_b32_e32 v183, v179
	v_permlane32_swap_b32_e32 v184, v180
	v_permlane32_swap_b32_e32 v185, v181
	v_add_f32_e32 v178, v178, v182
	v_add_f32_e32 v179, v179, v183
	v_add_f32_e32 v180, v180, v184
	v_add_f32_e32 v181, v181, v185
	v_fmamk_f32 v198, v178, 0x3a800000, v225
	v_fmamk_f32 v199, v179, 0x3a800000, v225
	v_fmamk_f32 v200, v180, 0x3a800000, v225
	v_fmamk_f32 v201, v181, 0x3a800000, v225
	v_mul_f32_e32 v182, 0x4b800000, v198
	v_mul_f32_e32 v183, 0x4b800000, v199
	v_mul_f32_e32 v184, 0x4b800000, v200
	v_mul_f32_e32 v185, 0x4b800000, v201
	v_cmp_gt_f32_e64 s[2:3], s30, v198
	v_cmp_gt_f32_e64 s[50:51], s30, v199
	v_cmp_gt_f32_e64 s[88:89], s30, v200
	v_cmp_gt_f32_e64 s[90:91], s30, v201
	v_cndmask_b32_e64 v198, v198, v182, s[2:3]
	v_cndmask_b32_e64 v199, v199, v183, s[50:51]
	v_cndmask_b32_e64 v200, v200, v184, s[88:89]
	v_cndmask_b32_e64 v201, v201, v185, s[90:91]
	v_rsq_f32_e32 v198, v198
	v_rsq_f32_e32 v199, v199
	v_rsq_f32_e32 v200, v200
	v_rsq_f32_e32 v201, v201
	v_mul_f32_e32 v182, 0x45800000, v198
	v_mul_f32_e32 v183, 0x45800000, v199
	v_mul_f32_e32 v184, 0x45800000, v200
	v_mul_f32_e32 v185, 0x45800000, v201
	v_cndmask_b32_e64 v186, v198, v182, s[2:3]
	v_cndmask_b32_e64 v192, v199, v183, s[50:51]
	v_cndmask_b32_e64 v194, v200, v184, s[88:89]
	v_cndmask_b32_e64 v196, v201, v185, s[90:91]
	v_pk_mul_f32 v[0:1], v[186:187], v[0:1] op_sel_hi:[0,1]
	v_pk_mul_f32 v[2:3], v[186:187], v[2:3] op_sel_hi:[0,1]
	v_pk_mul_f32 v[4:5], v[186:187], v[4:5] op_sel_hi:[0,1]
	v_pk_mul_f32 v[6:7], v[186:187], v[6:7] op_sel_hi:[0,1]
	v_pk_mul_f32 v[8:9], v[186:187], v[8:9] op_sel_hi:[0,1]
	v_pk_mul_f32 v[10:11], v[186:187], v[10:11] op_sel_hi:[0,1]
	v_pk_mul_f32 v[12:13], v[186:187], v[12:13] op_sel_hi:[0,1]
	v_pk_mul_f32 v[14:15], v[186:187], v[14:15] op_sel_hi:[0,1]
	v_pk_mul_f32 v[0:1], v[64:65], v[0:1]
	v_pk_mul_f32 v[2:3], v[66:67], v[2:3]
	v_pk_mul_f32 v[4:5], v[68:69], v[4:5]
	v_pk_mul_f32 v[6:7], v[70:71], v[6:7]
	v_pk_mul_f32 v[8:9], v[72:73], v[8:9]
	v_pk_mul_f32 v[10:11], v[74:75], v[10:11]
	v_pk_mul_f32 v[12:13], v[76:77], v[12:13]
	v_pk_mul_f32 v[14:15], v[78:79], v[14:15]
	v_pk_fma_f32 v[0:1], v[80:81], v[0:1], v[162:163]
	v_pk_fma_f32 v[2:3], v[82:83], v[2:3], v[164:165]
	v_pk_fma_f32 v[4:5], v[84:85], v[4:5], v[166:167]
	v_pk_fma_f32 v[6:7], v[86:87], v[6:7], v[168:169]
	v_pk_fma_f32 v[8:9], v[88:89], v[8:9], v[170:171]
	v_pk_fma_f32 v[10:11], v[90:91], v[10:11], v[172:173]
	v_pk_fma_f32 v[12:13], v[92:93], v[12:13], v[174:175]
	v_pk_fma_f32 v[14:15], v[94:95], v[14:15], v[176:177]
	v_cvt_pk_bf16_f32 v204, v0, v1
	v_cvt_pk_bf16_f32 v205, v2, v3
	v_cvt_pk_bf16_f32 v206, v4, v5
	v_cvt_pk_bf16_f32 v207, v6, v7
	v_cvt_pk_bf16_f32 v208, v8, v9
	v_cvt_pk_bf16_f32 v209, v10, v11
	v_cvt_pk_bf16_f32 v210, v12, v13
	v_cvt_pk_bf16_f32 v211, v14, v15
	global_store_dwordx2 v203, v[204:205], s[48:49] sc1
	global_store_dwordx2 v203, v[206:207], s[48:49] offset:512 sc1
	global_store_dwordx2 v203, v[208:209], s[48:49] offset:1024 sc1
	global_store_dwordx2 v203, v[210:211], s[48:49] offset:1536 sc1
	s_add_u32 s48, s48, 0x800
	s_addc_u32 s49, s49, 0
	v_pk_mul_f32 v[16:17], v[192:193], v[16:17] op_sel_hi:[0,1]
	v_pk_mul_f32 v[18:19], v[192:193], v[18:19] op_sel_hi:[0,1]
	v_pk_mul_f32 v[20:21], v[192:193], v[20:21] op_sel_hi:[0,1]
	v_pk_mul_f32 v[22:23], v[192:193], v[22:23] op_sel_hi:[0,1]
	v_pk_mul_f32 v[24:25], v[192:193], v[24:25] op_sel_hi:[0,1]
	v_pk_mul_f32 v[26:27], v[192:193], v[26:27] op_sel_hi:[0,1]
	v_pk_mul_f32 v[28:29], v[192:193], v[28:29] op_sel_hi:[0,1]
	v_pk_mul_f32 v[30:31], v[192:193], v[30:31] op_sel_hi:[0,1]
	v_pk_mul_f32 v[16:17], v[64:65], v[16:17]
	v_pk_mul_f32 v[18:19], v[66:67], v[18:19]
	v_pk_mul_f32 v[20:21], v[68:69], v[20:21]
	v_pk_mul_f32 v[22:23], v[70:71], v[22:23]
	v_pk_mul_f32 v[24:25], v[72:73], v[24:25]
	v_pk_mul_f32 v[26:27], v[74:75], v[26:27]
	v_pk_mul_f32 v[28:29], v[76:77], v[28:29]
	v_pk_mul_f32 v[30:31], v[78:79], v[30:31]
	v_pk_fma_f32 v[16:17], v[80:81], v[16:17], v[162:163]
	v_pk_fma_f32 v[18:19], v[82:83], v[18:19], v[164:165]
	v_pk_fma_f32 v[20:21], v[84:85], v[20:21], v[166:167]
	v_pk_fma_f32 v[22:23], v[86:87], v[22:23], v[168:169]
	v_pk_fma_f32 v[24:25], v[88:89], v[24:25], v[170:171]
	v_pk_fma_f32 v[26:27], v[90:91], v[26:27], v[172:173]
	v_pk_fma_f32 v[28:29], v[92:93], v[28:29], v[174:175]
	v_pk_fma_f32 v[30:31], v[94:95], v[30:31], v[176:177]
	v_cvt_pk_bf16_f32 v212, v16, v17
	v_cvt_pk_bf16_f32 v213, v18, v19
	v_cvt_pk_bf16_f32 v214, v20, v21
	v_cvt_pk_bf16_f32 v215, v22, v23
	v_cvt_pk_bf16_f32 v216, v24, v25
	v_cvt_pk_bf16_f32 v217, v26, v27
	v_cvt_pk_bf16_f32 v218, v28, v29
	v_cvt_pk_bf16_f32 v219, v30, v31
	global_store_dwordx2 v203, v[212:213], s[48:49] sc1
	global_store_dwordx2 v203, v[214:215], s[48:49] offset:512 sc1
	global_store_dwordx2 v203, v[216:217], s[48:49] offset:1024 sc1
	global_store_dwordx2 v203, v[218:219], s[48:49] offset:1536 sc1
	s_add_u32 s48, s48, 0x800
	s_addc_u32 s49, s49, 0
	v_pk_mul_f32 v[32:33], v[194:195], v[32:33] op_sel_hi:[0,1]
	v_pk_mul_f32 v[34:35], v[194:195], v[34:35] op_sel_hi:[0,1]
	v_pk_mul_f32 v[36:37], v[194:195], v[36:37] op_sel_hi:[0,1]
	v_pk_mul_f32 v[38:39], v[194:195], v[38:39] op_sel_hi:[0,1]
	v_pk_mul_f32 v[40:41], v[194:195], v[40:41] op_sel_hi:[0,1]
	v_pk_mul_f32 v[42:43], v[194:195], v[42:43] op_sel_hi:[0,1]
	v_pk_mul_f32 v[44:45], v[194:195], v[44:45] op_sel_hi:[0,1]
	v_pk_mul_f32 v[46:47], v[194:195], v[46:47] op_sel_hi:[0,1]
	v_pk_mul_f32 v[32:33], v[64:65], v[32:33]
	v_pk_mul_f32 v[34:35], v[66:67], v[34:35]
	v_pk_mul_f32 v[36:37], v[68:69], v[36:37]
	v_pk_mul_f32 v[38:39], v[70:71], v[38:39]
	v_pk_mul_f32 v[40:41], v[72:73], v[40:41]
	v_pk_mul_f32 v[42:43], v[74:75], v[42:43]
	v_pk_mul_f32 v[44:45], v[76:77], v[44:45]
	v_pk_mul_f32 v[46:47], v[78:79], v[46:47]
	v_pk_fma_f32 v[32:33], v[80:81], v[32:33], v[162:163]
	v_pk_fma_f32 v[34:35], v[82:83], v[34:35], v[164:165]
	v_pk_fma_f32 v[36:37], v[84:85], v[36:37], v[166:167]
	v_pk_fma_f32 v[38:39], v[86:87], v[38:39], v[168:169]
	v_pk_fma_f32 v[40:41], v[88:89], v[40:41], v[170:171]
	v_pk_fma_f32 v[42:43], v[90:91], v[42:43], v[172:173]
	v_pk_fma_f32 v[44:45], v[92:93], v[44:45], v[174:175]
	v_pk_fma_f32 v[46:47], v[94:95], v[46:47], v[176:177]
	v_cvt_pk_bf16_f32 v204, v32, v33
	v_cvt_pk_bf16_f32 v205, v34, v35
	v_cvt_pk_bf16_f32 v206, v36, v37
	v_cvt_pk_bf16_f32 v207, v38, v39
	v_cvt_pk_bf16_f32 v208, v40, v41
	v_cvt_pk_bf16_f32 v209, v42, v43
	v_cvt_pk_bf16_f32 v210, v44, v45
	v_cvt_pk_bf16_f32 v211, v46, v47
	global_store_dwordx2 v203, v[204:205], s[48:49] sc1
	global_store_dwordx2 v203, v[206:207], s[48:49] offset:512 sc1
	global_store_dwordx2 v203, v[208:209], s[48:49] offset:1024 sc1
	global_store_dwordx2 v203, v[210:211], s[48:49] offset:1536 sc1
	s_add_u32 s48, s48, 0x800
	s_addc_u32 s49, s49, 0
	v_pk_mul_f32 v[48:49], v[196:197], v[48:49] op_sel_hi:[0,1]
	v_pk_mul_f32 v[50:51], v[196:197], v[50:51] op_sel_hi:[0,1]
	v_pk_mul_f32 v[52:53], v[196:197], v[52:53] op_sel_hi:[0,1]
	v_pk_mul_f32 v[54:55], v[196:197], v[54:55] op_sel_hi:[0,1]
	v_pk_mul_f32 v[56:57], v[196:197], v[56:57] op_sel_hi:[0,1]
	v_pk_mul_f32 v[58:59], v[196:197], v[58:59] op_sel_hi:[0,1]
	v_pk_mul_f32 v[60:61], v[196:197], v[60:61] op_sel_hi:[0,1]
	v_pk_mul_f32 v[62:63], v[196:197], v[62:63] op_sel_hi:[0,1]
	v_pk_mul_f32 v[48:49], v[64:65], v[48:49]
	v_pk_mul_f32 v[50:51], v[66:67], v[50:51]
	v_pk_mul_f32 v[52:53], v[68:69], v[52:53]
	v_pk_mul_f32 v[54:55], v[70:71], v[54:55]
	v_pk_mul_f32 v[56:57], v[72:73], v[56:57]
	v_pk_mul_f32 v[58:59], v[74:75], v[58:59]
	v_pk_mul_f32 v[60:61], v[76:77], v[60:61]
	v_pk_mul_f32 v[62:63], v[78:79], v[62:63]
	v_pk_fma_f32 v[48:49], v[80:81], v[48:49], v[162:163]
	v_pk_fma_f32 v[50:51], v[82:83], v[50:51], v[164:165]
	v_pk_fma_f32 v[52:53], v[84:85], v[52:53], v[166:167]
	v_pk_fma_f32 v[54:55], v[86:87], v[54:55], v[168:169]
	v_pk_fma_f32 v[56:57], v[88:89], v[56:57], v[170:171]
	v_pk_fma_f32 v[58:59], v[90:91], v[58:59], v[172:173]
	v_pk_fma_f32 v[60:61], v[92:93], v[60:61], v[174:175]
	v_pk_fma_f32 v[62:63], v[94:95], v[62:63], v[176:177]
	v_cvt_pk_bf16_f32 v212, v48, v49
	v_cvt_pk_bf16_f32 v213, v50, v51
	v_cvt_pk_bf16_f32 v214, v52, v53
	v_cvt_pk_bf16_f32 v215, v54, v55
	v_cvt_pk_bf16_f32 v216, v56, v57
	v_cvt_pk_bf16_f32 v217, v58, v59
	v_cvt_pk_bf16_f32 v218, v60, v61
	v_cvt_pk_bf16_f32 v219, v62, v63
	global_store_dwordx2 v203, v[212:213], s[48:49] sc1
	global_store_dwordx2 v203, v[214:215], s[48:49] offset:512 sc1
	global_store_dwordx2 v203, v[216:217], s[48:49] offset:1024 sc1
	global_store_dwordx2 v203, v[218:219], s[48:49] offset:1536 sc1
	s_add_u32 s48, s48, 0x800
	s_addc_u32 s49, s49, 0
	buffer_load_dwordx4 v[0:3], v202, s[12:15], s11 offen sc1
	buffer_load_dwordx4 v[4:7], v202, s[12:15], s11 offen offset:1024 sc1
	buffer_load_dwordx4 v[8:11], v202, s[12:15], s11 offen offset:2048 sc1
	buffer_load_dwordx4 v[12:15], v202, s[12:15], s11 offen offset:3072 sc1
	s_add_u32 s11, s11, 0x1000
	buffer_load_dwordx4 v[16:19], v202, s[12:15], s11 offen sc1
	buffer_load_dwordx4 v[20:23], v202, s[12:15], s11 offen offset:1024 sc1
	buffer_load_dwordx4 v[24:27], v202, s[12:15], s11 offen offset:2048 sc1
	buffer_load_dwordx4 v[28:31], v202, s[12:15], s11 offen offset:3072 sc1
	s_add_u32 s11, s11, 0x1000
	buffer_load_dwordx4 v[32:35], v202, s[12:15], s11 offen sc1
	buffer_load_dwordx4 v[36:39], v202, s[12:15], s11 offen offset:1024 sc1
	buffer_load_dwordx4 v[40:43], v202, s[12:15], s11 offen offset:2048 sc1
	buffer_load_dwordx4 v[44:47], v202, s[12:15], s11 offen offset:3072 sc1
	s_add_u32 s11, s11, 0x1000
	buffer_load_dwordx4 v[48:51], v202, s[12:15], s11 offen sc1
	buffer_load_dwordx4 v[52:55], v202, s[12:15], s11 offen offset:1024 sc1
	buffer_load_dwordx4 v[56:59], v202, s[12:15], s11 offen offset:2048 sc1
	buffer_load_dwordx4 v[60:63], v202, s[12:15], s11 offen offset:3072 sc1
	s_add_u32 s11, s11, 0x1000
	s_waitcnt vmcnt(24)
	v_mul_f32_e32 v178, v98, v98
	v_mul_f32_e32 v179, v114, v114
	v_mul_f32_e32 v180, v130, v130
	v_mul_f32_e32 v181, v146, v146
	v_fma_f32 v178, v99, v99, v178
	v_fma_f32 v179, v115, v115, v179
	v_fma_f32 v180, v131, v131, v180
	v_fma_f32 v181, v147, v147, v181
	v_fma_f32 v178, v100, v100, v178
	v_fma_f32 v179, v116, v116, v179
	v_fma_f32 v180, v132, v132, v180
	v_fma_f32 v181, v148, v148, v181
	v_fma_f32 v178, v101, v101, v178
	v_fma_f32 v179, v117, v117, v179
	v_fma_f32 v180, v133, v133, v180
	v_fma_f32 v181, v149, v149, v181
	v_fma_f32 v178, v102, v102, v178
	v_fma_f32 v179, v118, v118, v179
	v_fma_f32 v180, v134, v134, v180
	v_fma_f32 v181, v150, v150, v181
	v_fma_f32 v178, v103, v103, v178
	v_fma_f32 v179, v119, v119, v179
	v_fma_f32 v180, v135, v135, v180
	v_fma_f32 v181, v151, v151, v181
	v_fma_f32 v178, v104, v104, v178
	v_fma_f32 v179, v120, v120, v179
	v_fma_f32 v180, v136, v136, v180
	v_fma_f32 v181, v152, v152, v181
	v_fma_f32 v178, v105, v105, v178
	v_fma_f32 v179, v121, v121, v179
	v_fma_f32 v180, v137, v137, v180
	v_fma_f32 v181, v153, v153, v181
	v_fma_f32 v178, v106, v106, v178
	v_fma_f32 v179, v122, v122, v179
	v_fma_f32 v180, v138, v138, v180
	v_fma_f32 v181, v154, v154, v181
	v_fma_f32 v178, v107, v107, v178
	v_fma_f32 v179, v123, v123, v179
	v_fma_f32 v180, v139, v139, v180
	v_fma_f32 v181, v155, v155, v181
	v_fma_f32 v178, v108, v108, v178
	v_fma_f32 v179, v124, v124, v179
	v_fma_f32 v180, v140, v140, v180
	v_fma_f32 v181, v156, v156, v181
	v_fma_f32 v178, v109, v109, v178
	v_fma_f32 v179, v125, v125, v179
	v_fma_f32 v180, v141, v141, v180
	v_fma_f32 v181, v157, v157, v181
	v_fma_f32 v178, v110, v110, v178
	v_fma_f32 v179, v126, v126, v179
	v_fma_f32 v180, v142, v142, v180
	v_fma_f32 v181, v158, v158, v181
	v_fma_f32 v178, v111, v111, v178
	v_fma_f32 v179, v127, v127, v179
	v_fma_f32 v180, v143, v143, v180
	v_fma_f32 v181, v159, v159, v181
	v_fma_f32 v178, v112, v112, v178
	v_fma_f32 v179, v128, v128, v179
	v_fma_f32 v180, v144, v144, v180
	v_fma_f32 v181, v160, v160, v181
	v_fma_f32 v178, v113, v113, v178
	v_fma_f32 v179, v129, v129, v179
	v_fma_f32 v180, v145, v145, v180
	v_fma_f32 v181, v161, v161, v181
	v_add_f32_dpp v178, v178, v178 quad_perm:[1,0,3,2] row_mask:0xf bank_mask:0xf
	v_add_f32_dpp v179, v179, v179 quad_perm:[1,0,3,2] row_mask:0xf bank_mask:0xf
	v_add_f32_dpp v180, v180, v180 quad_perm:[1,0,3,2] row_mask:0xf bank_mask:0xf
	v_add_f32_dpp v181, v181, v181 quad_perm:[1,0,3,2] row_mask:0xf bank_mask:0xf
	v_add_f32_dpp v178, v178, v178 quad_perm:[2,3,0,1] row_mask:0xf bank_mask:0xf
	v_add_f32_dpp v179, v179, v179 quad_perm:[2,3,0,1] row_mask:0xf bank_mask:0xf
	v_add_f32_dpp v180, v180, v180 quad_perm:[2,3,0,1] row_mask:0xf bank_mask:0xf
	v_add_f32_dpp v181, v181, v181 quad_perm:[2,3,0,1] row_mask:0xf bank_mask:0xf
	v_add_f32_dpp v178, v178, v178 row_half_mirror row_mask:0xf bank_mask:0xf
	v_add_f32_dpp v179, v179, v179 row_half_mirror row_mask:0xf bank_mask:0xf
	v_add_f32_dpp v180, v180, v180 row_half_mirror row_mask:0xf bank_mask:0xf
	v_add_f32_dpp v181, v181, v181 row_half_mirror row_mask:0xf bank_mask:0xf
	v_add_f32_dpp v178, v178, v178 row_ror:8 row_mask:0xf bank_mask:0xf
	v_add_f32_dpp v179, v179, v179 row_ror:8 row_mask:0xf bank_mask:0xf
	v_add_f32_dpp v180, v180, v180 row_ror:8 row_mask:0xf bank_mask:0xf
	v_add_f32_dpp v181, v181, v181 row_ror:8 row_mask:0xf bank_mask:0xf
	v_mov_b32_e32 v182, v178
	v_mov_b32_e32 v183, v179
	v_mov_b32_e32 v184, v180
	v_mov_b32_e32 v185, v181
	v_permlane16_swap_b32_e32 v182, v178
	v_permlane16_swap_b32_e32 v183, v179
	v_permlane16_swap_b32_e32 v184, v180
	v_permlane16_swap_b32_e32 v185, v181
	v_add_f32_e32 v178, v178, v182
	v_add_f32_e32 v179, v179, v183
	v_add_f32_e32 v180, v180, v184
	v_add_f32_e32 v181, v181, v185
	v_mov_b32_e32 v182, v178
	v_mov_b32_e32 v183, v179
	v_mov_b32_e32 v184, v180
	v_mov_b32_e32 v185, v181
	v_permlane32_swap_b32_e32 v182, v178
	v_permlane32_swap_b32_e32 v183, v179
	v_permlane32_swap_b32_e32 v184, v180
	v_permlane32_swap_b32_e32 v185, v181
	v_add_f32_e32 v178, v178, v182
	v_add_f32_e32 v179, v179, v183
	v_add_f32_e32 v180, v180, v184
	v_add_f32_e32 v181, v181, v185
	v_fmamk_f32 v198, v178, 0x3a800000, v225
	v_fmamk_f32 v199, v179, 0x3a800000, v225
	v_fmamk_f32 v200, v180, 0x3a800000, v225
	v_fmamk_f32 v201, v181, 0x3a800000, v225
	v_mul_f32_e32 v182, 0x4b800000, v198
	v_mul_f32_e32 v183, 0x4b800000, v199
	v_mul_f32_e32 v184, 0x4b800000, v200
	v_mul_f32_e32 v185, 0x4b800000, v201
	v_cmp_gt_f32_e64 s[2:3], s30, v198
	v_cmp_gt_f32_e64 s[50:51], s30, v199
	v_cmp_gt_f32_e64 s[88:89], s30, v200
	v_cmp_gt_f32_e64 s[90:91], s30, v201
	v_cndmask_b32_e64 v198, v198, v182, s[2:3]
	v_cndmask_b32_e64 v199, v199, v183, s[50:51]
	v_cndmask_b32_e64 v200, v200, v184, s[88:89]
	v_cndmask_b32_e64 v201, v201, v185, s[90:91]
	v_rsq_f32_e32 v198, v198
	v_rsq_f32_e32 v199, v199
	v_rsq_f32_e32 v200, v200
	v_rsq_f32_e32 v201, v201
	v_mul_f32_e32 v182, 0x45800000, v198
	v_mul_f32_e32 v183, 0x45800000, v199
	v_mul_f32_e32 v184, 0x45800000, v200
	v_mul_f32_e32 v185, 0x45800000, v201
	v_cndmask_b32_e64 v186, v198, v182, s[2:3]
	v_cndmask_b32_e64 v192, v199, v183, s[50:51]
	v_cndmask_b32_e64 v194, v200, v184, s[88:89]
	v_cndmask_b32_e64 v196, v201, v185, s[90:91]
	v_pk_mul_f32 v[98:99], v[186:187], v[98:99] op_sel_hi:[0,1]
	v_pk_mul_f32 v[100:101], v[186:187], v[100:101] op_sel_hi:[0,1]
	v_pk_mul_f32 v[102:103], v[186:187], v[102:103] op_sel_hi:[0,1]
	v_pk_mul_f32 v[104:105], v[186:187], v[104:105] op_sel_hi:[0,1]
	v_pk_mul_f32 v[106:107], v[186:187], v[106:107] op_sel_hi:[0,1]
	v_pk_mul_f32 v[108:109], v[186:187], v[108:109] op_sel_hi:[0,1]
	v_pk_mul_f32 v[110:111], v[186:187], v[110:111] op_sel_hi:[0,1]
	v_pk_mul_f32 v[112:113], v[186:187], v[112:113] op_sel_hi:[0,1]
	v_pk_mul_f32 v[98:99], v[64:65], v[98:99]
	v_pk_mul_f32 v[100:101], v[66:67], v[100:101]
	v_pk_mul_f32 v[102:103], v[68:69], v[102:103]
	v_pk_mul_f32 v[104:105], v[70:71], v[104:105]
	v_pk_mul_f32 v[106:107], v[72:73], v[106:107]
	v_pk_mul_f32 v[108:109], v[74:75], v[108:109]
	v_pk_mul_f32 v[110:111], v[76:77], v[110:111]
	v_pk_mul_f32 v[112:113], v[78:79], v[112:113]
	v_pk_fma_f32 v[98:99], v[80:81], v[98:99], v[162:163]
	v_pk_fma_f32 v[100:101], v[82:83], v[100:101], v[164:165]
	v_pk_fma_f32 v[102:103], v[84:85], v[102:103], v[166:167]
	v_pk_fma_f32 v[104:105], v[86:87], v[104:105], v[168:169]
	v_pk_fma_f32 v[106:107], v[88:89], v[106:107], v[170:171]
	v_pk_fma_f32 v[108:109], v[90:91], v[108:109], v[172:173]
	v_pk_fma_f32 v[110:111], v[92:93], v[110:111], v[174:175]
	v_pk_fma_f32 v[112:113], v[94:95], v[112:113], v[176:177]
	v_cvt_pk_bf16_f32 v204, v98, v99
	v_cvt_pk_bf16_f32 v205, v100, v101
	v_cvt_pk_bf16_f32 v206, v102, v103
	v_cvt_pk_bf16_f32 v207, v104, v105
	v_cvt_pk_bf16_f32 v208, v106, v107
	v_cvt_pk_bf16_f32 v209, v108, v109
	v_cvt_pk_bf16_f32 v210, v110, v111
	v_cvt_pk_bf16_f32 v211, v112, v113
	global_store_dwordx2 v203, v[204:205], s[48:49] sc1
	global_store_dwordx2 v203, v[206:207], s[48:49] offset:512 sc1
	global_store_dwordx2 v203, v[208:209], s[48:49] offset:1024 sc1
	global_store_dwordx2 v203, v[210:211], s[48:49] offset:1536 sc1
	s_add_u32 s48, s48, 0x800
	s_addc_u32 s49, s49, 0
	v_pk_mul_f32 v[114:115], v[192:193], v[114:115] op_sel_hi:[0,1]
	v_pk_mul_f32 v[116:117], v[192:193], v[116:117] op_sel_hi:[0,1]
	v_pk_mul_f32 v[118:119], v[192:193], v[118:119] op_sel_hi:[0,1]
	v_pk_mul_f32 v[120:121], v[192:193], v[120:121] op_sel_hi:[0,1]
	v_pk_mul_f32 v[122:123], v[192:193], v[122:123] op_sel_hi:[0,1]
	v_pk_mul_f32 v[124:125], v[192:193], v[124:125] op_sel_hi:[0,1]
	v_pk_mul_f32 v[126:127], v[192:193], v[126:127] op_sel_hi:[0,1]
	v_pk_mul_f32 v[128:129], v[192:193], v[128:129] op_sel_hi:[0,1]
	v_pk_mul_f32 v[114:115], v[64:65], v[114:115]
	v_pk_mul_f32 v[116:117], v[66:67], v[116:117]
	v_pk_mul_f32 v[118:119], v[68:69], v[118:119]
	v_pk_mul_f32 v[120:121], v[70:71], v[120:121]
	v_pk_mul_f32 v[122:123], v[72:73], v[122:123]
	v_pk_mul_f32 v[124:125], v[74:75], v[124:125]
	v_pk_mul_f32 v[126:127], v[76:77], v[126:127]
	v_pk_mul_f32 v[128:129], v[78:79], v[128:129]
	v_pk_fma_f32 v[114:115], v[80:81], v[114:115], v[162:163]
	v_pk_fma_f32 v[116:117], v[82:83], v[116:117], v[164:165]
	v_pk_fma_f32 v[118:119], v[84:85], v[118:119], v[166:167]
	v_pk_fma_f32 v[120:121], v[86:87], v[120:121], v[168:169]
	v_pk_fma_f32 v[122:123], v[88:89], v[122:123], v[170:171]
	v_pk_fma_f32 v[124:125], v[90:91], v[124:125], v[172:173]
	v_pk_fma_f32 v[126:127], v[92:93], v[126:127], v[174:175]
	v_pk_fma_f32 v[128:129], v[94:95], v[128:129], v[176:177]
	v_cvt_pk_bf16_f32 v212, v114, v115
	v_cvt_pk_bf16_f32 v213, v116, v117
	v_cvt_pk_bf16_f32 v214, v118, v119
	v_cvt_pk_bf16_f32 v215, v120, v121
	v_cvt_pk_bf16_f32 v216, v122, v123
	v_cvt_pk_bf16_f32 v217, v124, v125
	v_cvt_pk_bf16_f32 v218, v126, v127
	v_cvt_pk_bf16_f32 v219, v128, v129
	global_store_dwordx2 v203, v[212:213], s[48:49] sc1
	global_store_dwordx2 v203, v[214:215], s[48:49] offset:512 sc1
	global_store_dwordx2 v203, v[216:217], s[48:49] offset:1024 sc1
	global_store_dwordx2 v203, v[218:219], s[48:49] offset:1536 sc1
	s_add_u32 s48, s48, 0x800
	s_addc_u32 s49, s49, 0
	v_pk_mul_f32 v[130:131], v[194:195], v[130:131] op_sel_hi:[0,1]
	v_pk_mul_f32 v[132:133], v[194:195], v[132:133] op_sel_hi:[0,1]
	v_pk_mul_f32 v[134:135], v[194:195], v[134:135] op_sel_hi:[0,1]
	v_pk_mul_f32 v[136:137], v[194:195], v[136:137] op_sel_hi:[0,1]
	v_pk_mul_f32 v[138:139], v[194:195], v[138:139] op_sel_hi:[0,1]
	v_pk_mul_f32 v[140:141], v[194:195], v[140:141] op_sel_hi:[0,1]
	v_pk_mul_f32 v[142:143], v[194:195], v[142:143] op_sel_hi:[0,1]
	v_pk_mul_f32 v[144:145], v[194:195], v[144:145] op_sel_hi:[0,1]
	v_pk_mul_f32 v[130:131], v[64:65], v[130:131]
	v_pk_mul_f32 v[132:133], v[66:67], v[132:133]
	v_pk_mul_f32 v[134:135], v[68:69], v[134:135]
	v_pk_mul_f32 v[136:137], v[70:71], v[136:137]
	v_pk_mul_f32 v[138:139], v[72:73], v[138:139]
	v_pk_mul_f32 v[140:141], v[74:75], v[140:141]
	v_pk_mul_f32 v[142:143], v[76:77], v[142:143]
	v_pk_mul_f32 v[144:145], v[78:79], v[144:145]
	v_pk_fma_f32 v[130:131], v[80:81], v[130:131], v[162:163]
	v_pk_fma_f32 v[132:133], v[82:83], v[132:133], v[164:165]
	v_pk_fma_f32 v[134:135], v[84:85], v[134:135], v[166:167]
	v_pk_fma_f32 v[136:137], v[86:87], v[136:137], v[168:169]
	v_pk_fma_f32 v[138:139], v[88:89], v[138:139], v[170:171]
	v_pk_fma_f32 v[140:141], v[90:91], v[140:141], v[172:173]
	v_pk_fma_f32 v[142:143], v[92:93], v[142:143], v[174:175]
	v_pk_fma_f32 v[144:145], v[94:95], v[144:145], v[176:177]
	v_cvt_pk_bf16_f32 v204, v130, v131
	v_cvt_pk_bf16_f32 v205, v132, v133
	v_cvt_pk_bf16_f32 v206, v134, v135
	v_cvt_pk_bf16_f32 v207, v136, v137
	v_cvt_pk_bf16_f32 v208, v138, v139
	v_cvt_pk_bf16_f32 v209, v140, v141
	v_cvt_pk_bf16_f32 v210, v142, v143
	v_cvt_pk_bf16_f32 v211, v144, v145
	global_store_dwordx2 v203, v[204:205], s[48:49] sc1
	global_store_dwordx2 v203, v[206:207], s[48:49] offset:512 sc1
	global_store_dwordx2 v203, v[208:209], s[48:49] offset:1024 sc1
	global_store_dwordx2 v203, v[210:211], s[48:49] offset:1536 sc1
	s_add_u32 s48, s48, 0x800
	s_addc_u32 s49, s49, 0
	v_pk_mul_f32 v[146:147], v[196:197], v[146:147] op_sel_hi:[0,1]
	v_pk_mul_f32 v[148:149], v[196:197], v[148:149] op_sel_hi:[0,1]
	v_pk_mul_f32 v[150:151], v[196:197], v[150:151] op_sel_hi:[0,1]
	v_pk_mul_f32 v[152:153], v[196:197], v[152:153] op_sel_hi:[0,1]
	v_pk_mul_f32 v[154:155], v[196:197], v[154:155] op_sel_hi:[0,1]
	v_pk_mul_f32 v[156:157], v[196:197], v[156:157] op_sel_hi:[0,1]
	v_pk_mul_f32 v[158:159], v[196:197], v[158:159] op_sel_hi:[0,1]
	v_pk_mul_f32 v[160:161], v[196:197], v[160:161] op_sel_hi:[0,1]
	v_pk_mul_f32 v[146:147], v[64:65], v[146:147]
	v_pk_mul_f32 v[148:149], v[66:67], v[148:149]
	v_pk_mul_f32 v[150:151], v[68:69], v[150:151]
	v_pk_mul_f32 v[152:153], v[70:71], v[152:153]
	v_pk_mul_f32 v[154:155], v[72:73], v[154:155]
	v_pk_mul_f32 v[156:157], v[74:75], v[156:157]
	v_pk_mul_f32 v[158:159], v[76:77], v[158:159]
	v_pk_mul_f32 v[160:161], v[78:79], v[160:161]
	v_pk_fma_f32 v[146:147], v[80:81], v[146:147], v[162:163]
	v_pk_fma_f32 v[148:149], v[82:83], v[148:149], v[164:165]
	v_pk_fma_f32 v[150:151], v[84:85], v[150:151], v[166:167]
	v_pk_fma_f32 v[152:153], v[86:87], v[152:153], v[168:169]
	v_pk_fma_f32 v[154:155], v[88:89], v[154:155], v[170:171]
	v_pk_fma_f32 v[156:157], v[90:91], v[156:157], v[172:173]
	v_pk_fma_f32 v[158:159], v[92:93], v[158:159], v[174:175]
	v_pk_fma_f32 v[160:161], v[94:95], v[160:161], v[176:177]
	v_cvt_pk_bf16_f32 v212, v146, v147
	v_cvt_pk_bf16_f32 v213, v148, v149
	v_cvt_pk_bf16_f32 v214, v150, v151
	v_cvt_pk_bf16_f32 v215, v152, v153
	v_cvt_pk_bf16_f32 v216, v154, v155
	v_cvt_pk_bf16_f32 v217, v156, v157
	v_cvt_pk_bf16_f32 v218, v158, v159
	v_cvt_pk_bf16_f32 v219, v160, v161
	global_store_dwordx2 v203, v[212:213], s[48:49] sc1
	global_store_dwordx2 v203, v[214:215], s[48:49] offset:512 sc1
	global_store_dwordx2 v203, v[216:217], s[48:49] offset:1024 sc1
	global_store_dwordx2 v203, v[218:219], s[48:49] offset:1536 sc1
	s_add_u32 s48, s48, 0x800
	s_addc_u32 s49, s49, 0
	buffer_load_dwordx4 v[98:101], v202, s[12:15], s11 offen sc1
	buffer_load_dwordx4 v[102:105], v202, s[12:15], s11 offen offset:1024 sc1
	buffer_load_dwordx4 v[106:109], v202, s[12:15], s11 offen offset:2048 sc1
	buffer_load_dwordx4 v[110:113], v202, s[12:15], s11 offen offset:3072 sc1
	s_add_u32 s11, s11, 0x1000
	buffer_load_dwordx4 v[114:117], v202, s[12:15], s11 offen sc1
	buffer_load_dwordx4 v[118:121], v202, s[12:15], s11 offen offset:1024 sc1
	buffer_load_dwordx4 v[122:125], v202, s[12:15], s11 offen offset:2048 sc1
	buffer_load_dwordx4 v[126:129], v202, s[12:15], s11 offen offset:3072 sc1
	s_add_u32 s11, s11, 0x1000
	buffer_load_dwordx4 v[130:133], v202, s[12:15], s11 offen sc1
	buffer_load_dwordx4 v[134:137], v202, s[12:15], s11 offen offset:1024 sc1
	buffer_load_dwordx4 v[138:141], v202, s[12:15], s11 offen offset:2048 sc1
	buffer_load_dwordx4 v[142:145], v202, s[12:15], s11 offen offset:3072 sc1
	s_add_u32 s11, s11, 0x1000
	buffer_load_dwordx4 v[146:149], v202, s[12:15], s11 offen sc1
	buffer_load_dwordx4 v[150:153], v202, s[12:15], s11 offen offset:1024 sc1
	buffer_load_dwordx4 v[154:157], v202, s[12:15], s11 offen offset:2048 sc1
	buffer_load_dwordx4 v[158:161], v202, s[12:15], s11 offen offset:3072 sc1
	s_add_u32 s11, s11, 0x1000
	s_waitcnt vmcnt(24)
	v_mul_f32_e32 v178, v0, v0
	v_mul_f32_e32 v179, v16, v16
	v_mul_f32_e32 v180, v32, v32
	v_mul_f32_e32 v181, v48, v48
	v_fma_f32 v178, v1, v1, v178
	v_fma_f32 v179, v17, v17, v179
	v_fma_f32 v180, v33, v33, v180
	v_fma_f32 v181, v49, v49, v181
	v_fma_f32 v178, v2, v2, v178
	v_fma_f32 v179, v18, v18, v179
	v_fma_f32 v180, v34, v34, v180
	v_fma_f32 v181, v50, v50, v181
	v_fma_f32 v178, v3, v3, v178
	v_fma_f32 v179, v19, v19, v179
	v_fma_f32 v180, v35, v35, v180
	v_fma_f32 v181, v51, v51, v181
	v_fma_f32 v178, v4, v4, v178
	v_fma_f32 v179, v20, v20, v179
	v_fma_f32 v180, v36, v36, v180
	v_fma_f32 v181, v52, v52, v181
	v_fma_f32 v178, v5, v5, v178
	v_fma_f32 v179, v21, v21, v179
	v_fma_f32 v180, v37, v37, v180
	v_fma_f32 v181, v53, v53, v181
	v_fma_f32 v178, v6, v6, v178
	v_fma_f32 v179, v22, v22, v179
	v_fma_f32 v180, v38, v38, v180
	v_fma_f32 v181, v54, v54, v181
	v_fma_f32 v178, v7, v7, v178
	v_fma_f32 v179, v23, v23, v179
	v_fma_f32 v180, v39, v39, v180
	v_fma_f32 v181, v55, v55, v181
	v_fma_f32 v178, v8, v8, v178
	v_fma_f32 v179, v24, v24, v179
	v_fma_f32 v180, v40, v40, v180
	v_fma_f32 v181, v56, v56, v181
	v_fma_f32 v178, v9, v9, v178
	v_fma_f32 v179, v25, v25, v179
	v_fma_f32 v180, v41, v41, v180
	v_fma_f32 v181, v57, v57, v181
	v_fma_f32 v178, v10, v10, v178
	v_fma_f32 v179, v26, v26, v179
	v_fma_f32 v180, v42, v42, v180
	v_fma_f32 v181, v58, v58, v181
	v_fma_f32 v178, v11, v11, v178
	v_fma_f32 v179, v27, v27, v179
	v_fma_f32 v180, v43, v43, v180
	v_fma_f32 v181, v59, v59, v181
	v_fma_f32 v178, v12, v12, v178
	v_fma_f32 v179, v28, v28, v179
	v_fma_f32 v180, v44, v44, v180
	v_fma_f32 v181, v60, v60, v181
	v_fma_f32 v178, v13, v13, v178
	v_fma_f32 v179, v29, v29, v179
	v_fma_f32 v180, v45, v45, v180
	v_fma_f32 v181, v61, v61, v181
	v_fma_f32 v178, v14, v14, v178
	v_fma_f32 v179, v30, v30, v179
	v_fma_f32 v180, v46, v46, v180
	v_fma_f32 v181, v62, v62, v181
	v_fma_f32 v178, v15, v15, v178
	v_fma_f32 v179, v31, v31, v179
	v_fma_f32 v180, v47, v47, v180
	v_fma_f32 v181, v63, v63, v181
	v_add_f32_dpp v178, v178, v178 quad_perm:[1,0,3,2] row_mask:0xf bank_mask:0xf
	v_add_f32_dpp v179, v179, v179 quad_perm:[1,0,3,2] row_mask:0xf bank_mask:0xf
	v_add_f32_dpp v180, v180, v180 quad_perm:[1,0,3,2] row_mask:0xf bank_mask:0xf
	v_add_f32_dpp v181, v181, v181 quad_perm:[1,0,3,2] row_mask:0xf bank_mask:0xf
	v_add_f32_dpp v178, v178, v178 quad_perm:[2,3,0,1] row_mask:0xf bank_mask:0xf
	v_add_f32_dpp v179, v179, v179 quad_perm:[2,3,0,1] row_mask:0xf bank_mask:0xf
	v_add_f32_dpp v180, v180, v180 quad_perm:[2,3,0,1] row_mask:0xf bank_mask:0xf
	v_add_f32_dpp v181, v181, v181 quad_perm:[2,3,0,1] row_mask:0xf bank_mask:0xf
	v_add_f32_dpp v178, v178, v178 row_half_mirror row_mask:0xf bank_mask:0xf
	v_add_f32_dpp v179, v179, v179 row_half_mirror row_mask:0xf bank_mask:0xf
	v_add_f32_dpp v180, v180, v180 row_half_mirror row_mask:0xf bank_mask:0xf
	v_add_f32_dpp v181, v181, v181 row_half_mirror row_mask:0xf bank_mask:0xf
	v_add_f32_dpp v178, v178, v178 row_ror:8 row_mask:0xf bank_mask:0xf
	v_add_f32_dpp v179, v179, v179 row_ror:8 row_mask:0xf bank_mask:0xf
	v_add_f32_dpp v180, v180, v180 row_ror:8 row_mask:0xf bank_mask:0xf
	v_add_f32_dpp v181, v181, v181 row_ror:8 row_mask:0xf bank_mask:0xf
	v_mov_b32_e32 v182, v178
	v_mov_b32_e32 v183, v179
	v_mov_b32_e32 v184, v180
	v_mov_b32_e32 v185, v181
	v_permlane16_swap_b32_e32 v182, v178
	v_permlane16_swap_b32_e32 v183, v179
	v_permlane16_swap_b32_e32 v184, v180
	v_permlane16_swap_b32_e32 v185, v181
	v_add_f32_e32 v178, v178, v182
	v_add_f32_e32 v179, v179, v183
	v_add_f32_e32 v180, v180, v184
	v_add_f32_e32 v181, v181, v185
	v_mov_b32_e32 v182, v178
	v_mov_b32_e32 v183, v179
	v_mov_b32_e32 v184, v180
	v_mov_b32_e32 v185, v181
	v_permlane32_swap_b32_e32 v182, v178
	v_permlane32_swap_b32_e32 v183, v179
	v_permlane32_swap_b32_e32 v184, v180
	v_permlane32_swap_b32_e32 v185, v181
	v_add_f32_e32 v178, v178, v182
	v_add_f32_e32 v179, v179, v183
	v_add_f32_e32 v180, v180, v184
	v_add_f32_e32 v181, v181, v185
	v_fmamk_f32 v198, v178, 0x3a800000, v225
	v_fmamk_f32 v199, v179, 0x3a800000, v225
	v_fmamk_f32 v200, v180, 0x3a800000, v225
	v_fmamk_f32 v201, v181, 0x3a800000, v225
	v_mul_f32_e32 v182, 0x4b800000, v198
	v_mul_f32_e32 v183, 0x4b800000, v199
	v_mul_f32_e32 v184, 0x4b800000, v200
	v_mul_f32_e32 v185, 0x4b800000, v201
	v_cmp_gt_f32_e64 s[2:3], s30, v198
	v_cmp_gt_f32_e64 s[50:51], s30, v199
	v_cmp_gt_f32_e64 s[88:89], s30, v200
	v_cmp_gt_f32_e64 s[90:91], s30, v201
	v_cndmask_b32_e64 v198, v198, v182, s[2:3]
	v_cndmask_b32_e64 v199, v199, v183, s[50:51]
	v_cndmask_b32_e64 v200, v200, v184, s[88:89]
	v_cndmask_b32_e64 v201, v201, v185, s[90:91]
	v_rsq_f32_e32 v198, v198
	v_rsq_f32_e32 v199, v199
	v_rsq_f32_e32 v200, v200
	v_rsq_f32_e32 v201, v201
	v_mul_f32_e32 v182, 0x45800000, v198
	v_mul_f32_e32 v183, 0x45800000, v199
	v_mul_f32_e32 v184, 0x45800000, v200
	v_mul_f32_e32 v185, 0x45800000, v201
	v_cndmask_b32_e64 v186, v198, v182, s[2:3]
	v_cndmask_b32_e64 v192, v199, v183, s[50:51]
	v_cndmask_b32_e64 v194, v200, v184, s[88:89]
	v_cndmask_b32_e64 v196, v201, v185, s[90:91]
	v_pk_mul_f32 v[0:1], v[186:187], v[0:1] op_sel_hi:[0,1]
	v_pk_mul_f32 v[2:3], v[186:187], v[2:3] op_sel_hi:[0,1]
	v_pk_mul_f32 v[4:5], v[186:187], v[4:5] op_sel_hi:[0,1]
	v_pk_mul_f32 v[6:7], v[186:187], v[6:7] op_sel_hi:[0,1]
	v_pk_mul_f32 v[8:9], v[186:187], v[8:9] op_sel_hi:[0,1]
	v_pk_mul_f32 v[10:11], v[186:187], v[10:11] op_sel_hi:[0,1]
	v_pk_mul_f32 v[12:13], v[186:187], v[12:13] op_sel_hi:[0,1]
	v_pk_mul_f32 v[14:15], v[186:187], v[14:15] op_sel_hi:[0,1]
	v_pk_mul_f32 v[0:1], v[64:65], v[0:1]
	v_pk_mul_f32 v[2:3], v[66:67], v[2:3]
	v_pk_mul_f32 v[4:5], v[68:69], v[4:5]
	v_pk_mul_f32 v[6:7], v[70:71], v[6:7]
	v_pk_mul_f32 v[8:9], v[72:73], v[8:9]
	v_pk_mul_f32 v[10:11], v[74:75], v[10:11]
	v_pk_mul_f32 v[12:13], v[76:77], v[12:13]
	v_pk_mul_f32 v[14:15], v[78:79], v[14:15]
	v_pk_fma_f32 v[0:1], v[80:81], v[0:1], v[162:163]
	v_pk_fma_f32 v[2:3], v[82:83], v[2:3], v[164:165]
	v_pk_fma_f32 v[4:5], v[84:85], v[4:5], v[166:167]
	v_pk_fma_f32 v[6:7], v[86:87], v[6:7], v[168:169]
	v_pk_fma_f32 v[8:9], v[88:89], v[8:9], v[170:171]
	v_pk_fma_f32 v[10:11], v[90:91], v[10:11], v[172:173]
	v_pk_fma_f32 v[12:13], v[92:93], v[12:13], v[174:175]
	v_pk_fma_f32 v[14:15], v[94:95], v[14:15], v[176:177]
	v_cvt_pk_bf16_f32 v204, v0, v1
	v_cvt_pk_bf16_f32 v205, v2, v3
	v_cvt_pk_bf16_f32 v206, v4, v5
	v_cvt_pk_bf16_f32 v207, v6, v7
	v_cvt_pk_bf16_f32 v208, v8, v9
	v_cvt_pk_bf16_f32 v209, v10, v11
	v_cvt_pk_bf16_f32 v210, v12, v13
	v_cvt_pk_bf16_f32 v211, v14, v15
	global_store_dwordx2 v203, v[204:205], s[48:49] sc1
	global_store_dwordx2 v203, v[206:207], s[48:49] offset:512 sc1
	global_store_dwordx2 v203, v[208:209], s[48:49] offset:1024 sc1
	global_store_dwordx2 v203, v[210:211], s[48:49] offset:1536 sc1
	s_add_u32 s48, s48, 0x800
	s_addc_u32 s49, s49, 0
	v_pk_mul_f32 v[16:17], v[192:193], v[16:17] op_sel_hi:[0,1]
	v_pk_mul_f32 v[18:19], v[192:193], v[18:19] op_sel_hi:[0,1]
	v_pk_mul_f32 v[20:21], v[192:193], v[20:21] op_sel_hi:[0,1]
	v_pk_mul_f32 v[22:23], v[192:193], v[22:23] op_sel_hi:[0,1]
	v_pk_mul_f32 v[24:25], v[192:193], v[24:25] op_sel_hi:[0,1]
	v_pk_mul_f32 v[26:27], v[192:193], v[26:27] op_sel_hi:[0,1]
	v_pk_mul_f32 v[28:29], v[192:193], v[28:29] op_sel_hi:[0,1]
	v_pk_mul_f32 v[30:31], v[192:193], v[30:31] op_sel_hi:[0,1]
	v_pk_mul_f32 v[16:17], v[64:65], v[16:17]
	v_pk_mul_f32 v[18:19], v[66:67], v[18:19]
	v_pk_mul_f32 v[20:21], v[68:69], v[20:21]
	v_pk_mul_f32 v[22:23], v[70:71], v[22:23]
	v_pk_mul_f32 v[24:25], v[72:73], v[24:25]
	v_pk_mul_f32 v[26:27], v[74:75], v[26:27]
	v_pk_mul_f32 v[28:29], v[76:77], v[28:29]
	v_pk_mul_f32 v[30:31], v[78:79], v[30:31]
	v_pk_fma_f32 v[16:17], v[80:81], v[16:17], v[162:163]
	v_pk_fma_f32 v[18:19], v[82:83], v[18:19], v[164:165]
	v_pk_fma_f32 v[20:21], v[84:85], v[20:21], v[166:167]
	v_pk_fma_f32 v[22:23], v[86:87], v[22:23], v[168:169]
	v_pk_fma_f32 v[24:25], v[88:89], v[24:25], v[170:171]
	v_pk_fma_f32 v[26:27], v[90:91], v[26:27], v[172:173]
	v_pk_fma_f32 v[28:29], v[92:93], v[28:29], v[174:175]
	v_pk_fma_f32 v[30:31], v[94:95], v[30:31], v[176:177]
	v_cvt_pk_bf16_f32 v212, v16, v17
	v_cvt_pk_bf16_f32 v213, v18, v19
	v_cvt_pk_bf16_f32 v214, v20, v21
	v_cvt_pk_bf16_f32 v215, v22, v23
	v_cvt_pk_bf16_f32 v216, v24, v25
	v_cvt_pk_bf16_f32 v217, v26, v27
	v_cvt_pk_bf16_f32 v218, v28, v29
	v_cvt_pk_bf16_f32 v219, v30, v31
	global_store_dwordx2 v203, v[212:213], s[48:49] sc1
	global_store_dwordx2 v203, v[214:215], s[48:49] offset:512 sc1
	global_store_dwordx2 v203, v[216:217], s[48:49] offset:1024 sc1
	global_store_dwordx2 v203, v[218:219], s[48:49] offset:1536 sc1
	s_add_u32 s48, s48, 0x800
	s_addc_u32 s49, s49, 0
	v_pk_mul_f32 v[32:33], v[194:195], v[32:33] op_sel_hi:[0,1]
	v_pk_mul_f32 v[34:35], v[194:195], v[34:35] op_sel_hi:[0,1]
	v_pk_mul_f32 v[36:37], v[194:195], v[36:37] op_sel_hi:[0,1]
	v_pk_mul_f32 v[38:39], v[194:195], v[38:39] op_sel_hi:[0,1]
	v_pk_mul_f32 v[40:41], v[194:195], v[40:41] op_sel_hi:[0,1]
	v_pk_mul_f32 v[42:43], v[194:195], v[42:43] op_sel_hi:[0,1]
	v_pk_mul_f32 v[44:45], v[194:195], v[44:45] op_sel_hi:[0,1]
	v_pk_mul_f32 v[46:47], v[194:195], v[46:47] op_sel_hi:[0,1]
	v_pk_mul_f32 v[32:33], v[64:65], v[32:33]
	v_pk_mul_f32 v[34:35], v[66:67], v[34:35]
	v_pk_mul_f32 v[36:37], v[68:69], v[36:37]
	v_pk_mul_f32 v[38:39], v[70:71], v[38:39]
	v_pk_mul_f32 v[40:41], v[72:73], v[40:41]
	v_pk_mul_f32 v[42:43], v[74:75], v[42:43]
	v_pk_mul_f32 v[44:45], v[76:77], v[44:45]
	v_pk_mul_f32 v[46:47], v[78:79], v[46:47]
	v_pk_fma_f32 v[32:33], v[80:81], v[32:33], v[162:163]
	v_pk_fma_f32 v[34:35], v[82:83], v[34:35], v[164:165]
	v_pk_fma_f32 v[36:37], v[84:85], v[36:37], v[166:167]
	v_pk_fma_f32 v[38:39], v[86:87], v[38:39], v[168:169]
	v_pk_fma_f32 v[40:41], v[88:89], v[40:41], v[170:171]
	v_pk_fma_f32 v[42:43], v[90:91], v[42:43], v[172:173]
	v_pk_fma_f32 v[44:45], v[92:93], v[44:45], v[174:175]
	v_pk_fma_f32 v[46:47], v[94:95], v[46:47], v[176:177]
	v_cvt_pk_bf16_f32 v204, v32, v33
	v_cvt_pk_bf16_f32 v205, v34, v35
	v_cvt_pk_bf16_f32 v206, v36, v37
	v_cvt_pk_bf16_f32 v207, v38, v39
	v_cvt_pk_bf16_f32 v208, v40, v41
	v_cvt_pk_bf16_f32 v209, v42, v43
	v_cvt_pk_bf16_f32 v210, v44, v45
	v_cvt_pk_bf16_f32 v211, v46, v47
	global_store_dwordx2 v203, v[204:205], s[48:49] sc1
	global_store_dwordx2 v203, v[206:207], s[48:49] offset:512 sc1
	global_store_dwordx2 v203, v[208:209], s[48:49] offset:1024 sc1
	global_store_dwordx2 v203, v[210:211], s[48:49] offset:1536 sc1
	s_add_u32 s48, s48, 0x800
	s_addc_u32 s49, s49, 0
	v_pk_mul_f32 v[48:49], v[196:197], v[48:49] op_sel_hi:[0,1]
	v_pk_mul_f32 v[50:51], v[196:197], v[50:51] op_sel_hi:[0,1]
	v_pk_mul_f32 v[52:53], v[196:197], v[52:53] op_sel_hi:[0,1]
	v_pk_mul_f32 v[54:55], v[196:197], v[54:55] op_sel_hi:[0,1]
	v_pk_mul_f32 v[56:57], v[196:197], v[56:57] op_sel_hi:[0,1]
	v_pk_mul_f32 v[58:59], v[196:197], v[58:59] op_sel_hi:[0,1]
	v_pk_mul_f32 v[60:61], v[196:197], v[60:61] op_sel_hi:[0,1]
	v_pk_mul_f32 v[62:63], v[196:197], v[62:63] op_sel_hi:[0,1]
	v_pk_mul_f32 v[48:49], v[64:65], v[48:49]
	v_pk_mul_f32 v[50:51], v[66:67], v[50:51]
	v_pk_mul_f32 v[52:53], v[68:69], v[52:53]
	v_pk_mul_f32 v[54:55], v[70:71], v[54:55]
	v_pk_mul_f32 v[56:57], v[72:73], v[56:57]
	v_pk_mul_f32 v[58:59], v[74:75], v[58:59]
	v_pk_mul_f32 v[60:61], v[76:77], v[60:61]
	v_pk_mul_f32 v[62:63], v[78:79], v[62:63]
	v_pk_fma_f32 v[48:49], v[80:81], v[48:49], v[162:163]
	v_pk_fma_f32 v[50:51], v[82:83], v[50:51], v[164:165]
	v_pk_fma_f32 v[52:53], v[84:85], v[52:53], v[166:167]
	v_pk_fma_f32 v[54:55], v[86:87], v[54:55], v[168:169]
	v_pk_fma_f32 v[56:57], v[88:89], v[56:57], v[170:171]
	v_pk_fma_f32 v[58:59], v[90:91], v[58:59], v[172:173]
	v_pk_fma_f32 v[60:61], v[92:93], v[60:61], v[174:175]
	v_pk_fma_f32 v[62:63], v[94:95], v[62:63], v[176:177]
	v_cvt_pk_bf16_f32 v212, v48, v49
	v_cvt_pk_bf16_f32 v213, v50, v51
	v_cvt_pk_bf16_f32 v214, v52, v53
	v_cvt_pk_bf16_f32 v215, v54, v55
	v_cvt_pk_bf16_f32 v216, v56, v57
	v_cvt_pk_bf16_f32 v217, v58, v59
	v_cvt_pk_bf16_f32 v218, v60, v61
	v_cvt_pk_bf16_f32 v219, v62, v63
	global_store_dwordx2 v203, v[212:213], s[48:49] sc1
	global_store_dwordx2 v203, v[214:215], s[48:49] offset:512 sc1
	global_store_dwordx2 v203, v[216:217], s[48:49] offset:1024 sc1
	global_store_dwordx2 v203, v[218:219], s[48:49] offset:1536 sc1
	s_add_u32 s48, s48, 0x800
	s_addc_u32 s49, s49, 0
	s_waitcnt vmcnt(8)
	v_mul_f32_e32 v178, v98, v98
	v_mul_f32_e32 v179, v114, v114
	v_mul_f32_e32 v180, v130, v130
	v_mul_f32_e32 v181, v146, v146
	v_fma_f32 v178, v99, v99, v178
	v_fma_f32 v179, v115, v115, v179
	v_fma_f32 v180, v131, v131, v180
	v_fma_f32 v181, v147, v147, v181
	v_fma_f32 v178, v100, v100, v178
	v_fma_f32 v179, v116, v116, v179
	v_fma_f32 v180, v132, v132, v180
	v_fma_f32 v181, v148, v148, v181
	v_fma_f32 v178, v101, v101, v178
	v_fma_f32 v179, v117, v117, v179
	v_fma_f32 v180, v133, v133, v180
	v_fma_f32 v181, v149, v149, v181
	v_fma_f32 v178, v102, v102, v178
	v_fma_f32 v179, v118, v118, v179
	v_fma_f32 v180, v134, v134, v180
	v_fma_f32 v181, v150, v150, v181
	v_fma_f32 v178, v103, v103, v178
	v_fma_f32 v179, v119, v119, v179
	v_fma_f32 v180, v135, v135, v180
	v_fma_f32 v181, v151, v151, v181
	v_fma_f32 v178, v104, v104, v178
	v_fma_f32 v179, v120, v120, v179
	v_fma_f32 v180, v136, v136, v180
	v_fma_f32 v181, v152, v152, v181
	v_fma_f32 v178, v105, v105, v178
	v_fma_f32 v179, v121, v121, v179
	v_fma_f32 v180, v137, v137, v180
	v_fma_f32 v181, v153, v153, v181
	v_fma_f32 v178, v106, v106, v178
	v_fma_f32 v179, v122, v122, v179
	v_fma_f32 v180, v138, v138, v180
	v_fma_f32 v181, v154, v154, v181
	v_fma_f32 v178, v107, v107, v178
	v_fma_f32 v179, v123, v123, v179
	v_fma_f32 v180, v139, v139, v180
	v_fma_f32 v181, v155, v155, v181
	v_fma_f32 v178, v108, v108, v178
	v_fma_f32 v179, v124, v124, v179
	v_fma_f32 v180, v140, v140, v180
	v_fma_f32 v181, v156, v156, v181
	v_fma_f32 v178, v109, v109, v178
	v_fma_f32 v179, v125, v125, v179
	v_fma_f32 v180, v141, v141, v180
	v_fma_f32 v181, v157, v157, v181
	v_fma_f32 v178, v110, v110, v178
	v_fma_f32 v179, v126, v126, v179
	v_fma_f32 v180, v142, v142, v180
	v_fma_f32 v181, v158, v158, v181
	v_fma_f32 v178, v111, v111, v178
	v_fma_f32 v179, v127, v127, v179
	v_fma_f32 v180, v143, v143, v180
	v_fma_f32 v181, v159, v159, v181
	v_fma_f32 v178, v112, v112, v178
	v_fma_f32 v179, v128, v128, v179
	v_fma_f32 v180, v144, v144, v180
	v_fma_f32 v181, v160, v160, v181
	v_fma_f32 v178, v113, v113, v178
	v_fma_f32 v179, v129, v129, v179
	v_fma_f32 v180, v145, v145, v180
	v_fma_f32 v181, v161, v161, v181
	v_add_f32_dpp v178, v178, v178 quad_perm:[1,0,3,2] row_mask:0xf bank_mask:0xf
	v_add_f32_dpp v179, v179, v179 quad_perm:[1,0,3,2] row_mask:0xf bank_mask:0xf
	v_add_f32_dpp v180, v180, v180 quad_perm:[1,0,3,2] row_mask:0xf bank_mask:0xf
	v_add_f32_dpp v181, v181, v181 quad_perm:[1,0,3,2] row_mask:0xf bank_mask:0xf
	v_add_f32_dpp v178, v178, v178 quad_perm:[2,3,0,1] row_mask:0xf bank_mask:0xf
	v_add_f32_dpp v179, v179, v179 quad_perm:[2,3,0,1] row_mask:0xf bank_mask:0xf
	v_add_f32_dpp v180, v180, v180 quad_perm:[2,3,0,1] row_mask:0xf bank_mask:0xf
	v_add_f32_dpp v181, v181, v181 quad_perm:[2,3,0,1] row_mask:0xf bank_mask:0xf
	v_add_f32_dpp v178, v178, v178 row_half_mirror row_mask:0xf bank_mask:0xf
	v_add_f32_dpp v179, v179, v179 row_half_mirror row_mask:0xf bank_mask:0xf
	v_add_f32_dpp v180, v180, v180 row_half_mirror row_mask:0xf bank_mask:0xf
	v_add_f32_dpp v181, v181, v181 row_half_mirror row_mask:0xf bank_mask:0xf
	v_add_f32_dpp v178, v178, v178 row_ror:8 row_mask:0xf bank_mask:0xf
	v_add_f32_dpp v179, v179, v179 row_ror:8 row_mask:0xf bank_mask:0xf
	v_add_f32_dpp v180, v180, v180 row_ror:8 row_mask:0xf bank_mask:0xf
	v_add_f32_dpp v181, v181, v181 row_ror:8 row_mask:0xf bank_mask:0xf
	v_mov_b32_e32 v182, v178
	v_mov_b32_e32 v183, v179
	v_mov_b32_e32 v184, v180
	v_mov_b32_e32 v185, v181
	v_permlane16_swap_b32_e32 v182, v178
	v_permlane16_swap_b32_e32 v183, v179
	v_permlane16_swap_b32_e32 v184, v180
	v_permlane16_swap_b32_e32 v185, v181
	v_add_f32_e32 v178, v178, v182
	v_add_f32_e32 v179, v179, v183
	v_add_f32_e32 v180, v180, v184
	v_add_f32_e32 v181, v181, v185
	v_mov_b32_e32 v182, v178
	v_mov_b32_e32 v183, v179
	v_mov_b32_e32 v184, v180
	v_mov_b32_e32 v185, v181
	v_permlane32_swap_b32_e32 v182, v178
	v_permlane32_swap_b32_e32 v183, v179
	v_permlane32_swap_b32_e32 v184, v180
	v_permlane32_swap_b32_e32 v185, v181
	v_add_f32_e32 v178, v178, v182
	v_add_f32_e32 v179, v179, v183
	v_add_f32_e32 v180, v180, v184
	v_add_f32_e32 v181, v181, v185
	v_fmamk_f32 v198, v178, 0x3a800000, v225
	v_fmamk_f32 v199, v179, 0x3a800000, v225
	v_fmamk_f32 v200, v180, 0x3a800000, v225
	v_fmamk_f32 v201, v181, 0x3a800000, v225
	v_mul_f32_e32 v182, 0x4b800000, v198
	v_mul_f32_e32 v183, 0x4b800000, v199
	v_mul_f32_e32 v184, 0x4b800000, v200
	v_mul_f32_e32 v185, 0x4b800000, v201
	v_cmp_gt_f32_e64 s[2:3], s30, v198
	v_cmp_gt_f32_e64 s[50:51], s30, v199
	v_cmp_gt_f32_e64 s[88:89], s30, v200
	v_cmp_gt_f32_e64 s[90:91], s30, v201
	v_cndmask_b32_e64 v198, v198, v182, s[2:3]
	v_cndmask_b32_e64 v199, v199, v183, s[50:51]
	v_cndmask_b32_e64 v200, v200, v184, s[88:89]
	v_cndmask_b32_e64 v201, v201, v185, s[90:91]
	v_rsq_f32_e32 v198, v198
	v_rsq_f32_e32 v199, v199
	v_rsq_f32_e32 v200, v200
	v_rsq_f32_e32 v201, v201
	v_mul_f32_e32 v182, 0x45800000, v198
	v_mul_f32_e32 v183, 0x45800000, v199
	v_mul_f32_e32 v184, 0x45800000, v200
	v_mul_f32_e32 v185, 0x45800000, v201
	v_cndmask_b32_e64 v186, v198, v182, s[2:3]
	v_cndmask_b32_e64 v192, v199, v183, s[50:51]
	v_cndmask_b32_e64 v194, v200, v184, s[88:89]
	v_cndmask_b32_e64 v196, v201, v185, s[90:91]
	v_pk_mul_f32 v[98:99], v[186:187], v[98:99] op_sel_hi:[0,1]
	v_pk_mul_f32 v[100:101], v[186:187], v[100:101] op_sel_hi:[0,1]
	v_pk_mul_f32 v[102:103], v[186:187], v[102:103] op_sel_hi:[0,1]
	v_pk_mul_f32 v[104:105], v[186:187], v[104:105] op_sel_hi:[0,1]
	v_pk_mul_f32 v[106:107], v[186:187], v[106:107] op_sel_hi:[0,1]
	v_pk_mul_f32 v[108:109], v[186:187], v[108:109] op_sel_hi:[0,1]
	v_pk_mul_f32 v[110:111], v[186:187], v[110:111] op_sel_hi:[0,1]
	v_pk_mul_f32 v[112:113], v[186:187], v[112:113] op_sel_hi:[0,1]
	v_pk_mul_f32 v[98:99], v[64:65], v[98:99]
	v_pk_mul_f32 v[100:101], v[66:67], v[100:101]
	v_pk_mul_f32 v[102:103], v[68:69], v[102:103]
	v_pk_mul_f32 v[104:105], v[70:71], v[104:105]
	v_pk_mul_f32 v[106:107], v[72:73], v[106:107]
	v_pk_mul_f32 v[108:109], v[74:75], v[108:109]
	v_pk_mul_f32 v[110:111], v[76:77], v[110:111]
	v_pk_mul_f32 v[112:113], v[78:79], v[112:113]
	v_pk_fma_f32 v[98:99], v[80:81], v[98:99], v[162:163]
	v_pk_fma_f32 v[100:101], v[82:83], v[100:101], v[164:165]
	v_pk_fma_f32 v[102:103], v[84:85], v[102:103], v[166:167]
	v_pk_fma_f32 v[104:105], v[86:87], v[104:105], v[168:169]
	v_pk_fma_f32 v[106:107], v[88:89], v[106:107], v[170:171]
	v_pk_fma_f32 v[108:109], v[90:91], v[108:109], v[172:173]
	v_pk_fma_f32 v[110:111], v[92:93], v[110:111], v[174:175]
	v_pk_fma_f32 v[112:113], v[94:95], v[112:113], v[176:177]
	v_cvt_pk_bf16_f32 v204, v98, v99
	v_cvt_pk_bf16_f32 v205, v100, v101
	v_cvt_pk_bf16_f32 v206, v102, v103
	v_cvt_pk_bf16_f32 v207, v104, v105
	v_cvt_pk_bf16_f32 v208, v106, v107
	v_cvt_pk_bf16_f32 v209, v108, v109
	v_cvt_pk_bf16_f32 v210, v110, v111
	v_cvt_pk_bf16_f32 v211, v112, v113
	global_store_dwordx2 v203, v[204:205], s[48:49] sc1
	global_store_dwordx2 v203, v[206:207], s[48:49] offset:512 sc1
	global_store_dwordx2 v203, v[208:209], s[48:49] offset:1024 sc1
	global_store_dwordx2 v203, v[210:211], s[48:49] offset:1536 sc1
	s_add_u32 s48, s48, 0x800
	s_addc_u32 s49, s49, 0
	v_pk_mul_f32 v[114:115], v[192:193], v[114:115] op_sel_hi:[0,1]
	v_pk_mul_f32 v[116:117], v[192:193], v[116:117] op_sel_hi:[0,1]
	v_pk_mul_f32 v[118:119], v[192:193], v[118:119] op_sel_hi:[0,1]
	v_pk_mul_f32 v[120:121], v[192:193], v[120:121] op_sel_hi:[0,1]
	v_pk_mul_f32 v[122:123], v[192:193], v[122:123] op_sel_hi:[0,1]
	v_pk_mul_f32 v[124:125], v[192:193], v[124:125] op_sel_hi:[0,1]
	v_pk_mul_f32 v[126:127], v[192:193], v[126:127] op_sel_hi:[0,1]
	v_pk_mul_f32 v[128:129], v[192:193], v[128:129] op_sel_hi:[0,1]
	v_pk_mul_f32 v[114:115], v[64:65], v[114:115]
	v_pk_mul_f32 v[116:117], v[66:67], v[116:117]
	v_pk_mul_f32 v[118:119], v[68:69], v[118:119]
	v_pk_mul_f32 v[120:121], v[70:71], v[120:121]
	v_pk_mul_f32 v[122:123], v[72:73], v[122:123]
	v_pk_mul_f32 v[124:125], v[74:75], v[124:125]
	v_pk_mul_f32 v[126:127], v[76:77], v[126:127]
	v_pk_mul_f32 v[128:129], v[78:79], v[128:129]
	v_pk_fma_f32 v[114:115], v[80:81], v[114:115], v[162:163]
	v_pk_fma_f32 v[116:117], v[82:83], v[116:117], v[164:165]
	v_pk_fma_f32 v[118:119], v[84:85], v[118:119], v[166:167]
	v_pk_fma_f32 v[120:121], v[86:87], v[120:121], v[168:169]
	v_pk_fma_f32 v[122:123], v[88:89], v[122:123], v[170:171]
	v_pk_fma_f32 v[124:125], v[90:91], v[124:125], v[172:173]
	v_pk_fma_f32 v[126:127], v[92:93], v[126:127], v[174:175]
	v_pk_fma_f32 v[128:129], v[94:95], v[128:129], v[176:177]
	v_cvt_pk_bf16_f32 v212, v114, v115
	v_cvt_pk_bf16_f32 v213, v116, v117
	v_cvt_pk_bf16_f32 v214, v118, v119
	v_cvt_pk_bf16_f32 v215, v120, v121
	v_cvt_pk_bf16_f32 v216, v122, v123
	v_cvt_pk_bf16_f32 v217, v124, v125
	v_cvt_pk_bf16_f32 v218, v126, v127
	v_cvt_pk_bf16_f32 v219, v128, v129
	global_store_dwordx2 v203, v[212:213], s[48:49] sc1
	global_store_dwordx2 v203, v[214:215], s[48:49] offset:512 sc1
	global_store_dwordx2 v203, v[216:217], s[48:49] offset:1024 sc1
	global_store_dwordx2 v203, v[218:219], s[48:49] offset:1536 sc1
	s_add_u32 s48, s48, 0x800
	s_addc_u32 s49, s49, 0
	v_pk_mul_f32 v[130:131], v[194:195], v[130:131] op_sel_hi:[0,1]
	v_pk_mul_f32 v[132:133], v[194:195], v[132:133] op_sel_hi:[0,1]
	v_pk_mul_f32 v[134:135], v[194:195], v[134:135] op_sel_hi:[0,1]
	v_pk_mul_f32 v[136:137], v[194:195], v[136:137] op_sel_hi:[0,1]
	v_pk_mul_f32 v[138:139], v[194:195], v[138:139] op_sel_hi:[0,1]
	v_pk_mul_f32 v[140:141], v[194:195], v[140:141] op_sel_hi:[0,1]
	v_pk_mul_f32 v[142:143], v[194:195], v[142:143] op_sel_hi:[0,1]
	v_pk_mul_f32 v[144:145], v[194:195], v[144:145] op_sel_hi:[0,1]
	v_pk_mul_f32 v[130:131], v[64:65], v[130:131]
	v_pk_mul_f32 v[132:133], v[66:67], v[132:133]
	v_pk_mul_f32 v[134:135], v[68:69], v[134:135]
	v_pk_mul_f32 v[136:137], v[70:71], v[136:137]
	v_pk_mul_f32 v[138:139], v[72:73], v[138:139]
	v_pk_mul_f32 v[140:141], v[74:75], v[140:141]
	v_pk_mul_f32 v[142:143], v[76:77], v[142:143]
	v_pk_mul_f32 v[144:145], v[78:79], v[144:145]
	v_pk_fma_f32 v[130:131], v[80:81], v[130:131], v[162:163]
	v_pk_fma_f32 v[132:133], v[82:83], v[132:133], v[164:165]
	v_pk_fma_f32 v[134:135], v[84:85], v[134:135], v[166:167]
	v_pk_fma_f32 v[136:137], v[86:87], v[136:137], v[168:169]
	v_pk_fma_f32 v[138:139], v[88:89], v[138:139], v[170:171]
	v_pk_fma_f32 v[140:141], v[90:91], v[140:141], v[172:173]
	v_pk_fma_f32 v[142:143], v[92:93], v[142:143], v[174:175]
	v_pk_fma_f32 v[144:145], v[94:95], v[144:145], v[176:177]
	v_cvt_pk_bf16_f32 v204, v130, v131
	v_cvt_pk_bf16_f32 v205, v132, v133
	v_cvt_pk_bf16_f32 v206, v134, v135
	v_cvt_pk_bf16_f32 v207, v136, v137
	v_cvt_pk_bf16_f32 v208, v138, v139
	v_cvt_pk_bf16_f32 v209, v140, v141
	v_cvt_pk_bf16_f32 v210, v142, v143
	v_cvt_pk_bf16_f32 v211, v144, v145
	global_store_dwordx2 v203, v[204:205], s[48:49] sc1
	global_store_dwordx2 v203, v[206:207], s[48:49] offset:512 sc1
	global_store_dwordx2 v203, v[208:209], s[48:49] offset:1024 sc1
	global_store_dwordx2 v203, v[210:211], s[48:49] offset:1536 sc1
	s_add_u32 s48, s48, 0x800
	s_addc_u32 s49, s49, 0
	v_pk_mul_f32 v[146:147], v[196:197], v[146:147] op_sel_hi:[0,1]
	v_pk_mul_f32 v[148:149], v[196:197], v[148:149] op_sel_hi:[0,1]
	v_pk_mul_f32 v[150:151], v[196:197], v[150:151] op_sel_hi:[0,1]
	v_pk_mul_f32 v[152:153], v[196:197], v[152:153] op_sel_hi:[0,1]
	v_pk_mul_f32 v[154:155], v[196:197], v[154:155] op_sel_hi:[0,1]
	v_pk_mul_f32 v[156:157], v[196:197], v[156:157] op_sel_hi:[0,1]
	v_pk_mul_f32 v[158:159], v[196:197], v[158:159] op_sel_hi:[0,1]
	v_pk_mul_f32 v[160:161], v[196:197], v[160:161] op_sel_hi:[0,1]
	v_pk_mul_f32 v[146:147], v[64:65], v[146:147]
	v_pk_mul_f32 v[148:149], v[66:67], v[148:149]
	v_pk_mul_f32 v[150:151], v[68:69], v[150:151]
	v_pk_mul_f32 v[152:153], v[70:71], v[152:153]
	v_pk_mul_f32 v[154:155], v[72:73], v[154:155]
	v_pk_mul_f32 v[156:157], v[74:75], v[156:157]
	v_pk_mul_f32 v[158:159], v[76:77], v[158:159]
	v_pk_mul_f32 v[160:161], v[78:79], v[160:161]
	v_pk_fma_f32 v[146:147], v[80:81], v[146:147], v[162:163]
	v_pk_fma_f32 v[148:149], v[82:83], v[148:149], v[164:165]
	v_pk_fma_f32 v[150:151], v[84:85], v[150:151], v[166:167]
	v_pk_fma_f32 v[152:153], v[86:87], v[152:153], v[168:169]
	v_pk_fma_f32 v[154:155], v[88:89], v[154:155], v[170:171]
	v_pk_fma_f32 v[156:157], v[90:91], v[156:157], v[172:173]
	v_pk_fma_f32 v[158:159], v[92:93], v[158:159], v[174:175]
	v_pk_fma_f32 v[160:161], v[94:95], v[160:161], v[176:177]
	v_cvt_pk_bf16_f32 v212, v146, v147
	v_cvt_pk_bf16_f32 v213, v148, v149
	v_cvt_pk_bf16_f32 v214, v150, v151
	v_cvt_pk_bf16_f32 v215, v152, v153
	v_cvt_pk_bf16_f32 v216, v154, v155
	v_cvt_pk_bf16_f32 v217, v156, v157
	v_cvt_pk_bf16_f32 v218, v158, v159
	v_cvt_pk_bf16_f32 v219, v160, v161
	global_store_dwordx2 v203, v[212:213], s[48:49] sc1
	global_store_dwordx2 v203, v[214:215], s[48:49] offset:512 sc1
	global_store_dwordx2 v203, v[216:217], s[48:49] offset:1024 sc1
	global_store_dwordx2 v203, v[218:219], s[48:49] offset:1536 sc1
	s_add_u32 s48, s48, 0x800
	s_addc_u32 s49, s49, 0
	s_nop 1
	s_branch .LBB0_460
